# all remaining xor-butterfly reductions (N1, rows, EpiRes, combine, final norm, EpiFnet) via DPP and permlane swaps
# speedup vs baseline: 1.0073x; 1.0022x over previous
.LBB0_352:
	s_waitcnt vmcnt(0)
	v_pk_mul_f32 v[80:81], v[64:65], v[64:65]
	v_pk_mul_f32 v[82:83], v[62:63], v[62:63]
	v_mul_f32_e32 v76, v54, v54
	v_pk_mov_b32 v[84:85], v[82:83], v[80:81] op_sel:[1,0]
	v_mov_b32_e32 v83, v81
	v_pk_add_f32 v[80:81], v[84:85], v[82:83]
	v_pk_mul_f32 v[82:83], v[60:61], v[60:61]
	v_pk_mul_f32 v[84:85], v[58:59], v[58:59]
	v_pk_add_f32 v[80:81], v[80:81], v[80:81] op_sel_hi:[0,1]
	v_pk_mov_b32 v[86:87], v[84:85], v[82:83] op_sel:[1,0]
	v_mov_b32_e32 v85, v83
	v_pk_add_f32 v[82:83], v[86:87], v[84:85]
	v_pk_fma_f32 v[84:85], v[54:55], v[54:55], v[76:77] op_sel_hi:[1,1,0]
	v_mul_f32_e32 v76, v56, v56
	v_pk_add_f32 v[82:83], v[82:83], v[82:83] op_sel_hi:[0,1]
	v_pk_fma_f32 v[86:87], v[56:57], v[56:57], v[76:77] op_sel_hi:[1,1,0]
	v_mul_f32_e32 v84, v50, v50
	v_mul_f32_e32 v86, v51, v51
	v_mul_f32_e32 v82, v52, v52
	v_mul_f32_e32 v80, v53, v53
	v_pk_add_f32 v[84:85], v[84:85], v[86:87]
	v_pk_add_f32 v[80:81], v[82:83], v[80:81]
	s_add_i32 s44, s9, 0xffffff80
	v_pk_add_f32 v[80:81], v[84:85], v[80:81]
	s_min_i32 s0, s44, 0x4000
	v_add_f32_e32 v76, v80, v81
	s_nop 1
	v_mov_b32_dpp v80, v76 quad_perm:[1,0,3,2] row_mask:0xf bank_mask:0xf
	s_lshr_b32 s0, s0, 11
	s_mulk_i32 s0, 0x1800
	s_ashr_i32 s1, s0, 31
	s_lshl_b64 s[0:1], s[0:1], 2
	s_waitcnt lgkmcnt(0)
	v_add_f32_e32 v76, v76, v80
	s_nop 1
	v_mov_b32_dpp v80, v76 quad_perm:[2,3,0,1] row_mask:0xf bank_mask:0xf
	v_readlane_b32 s10, v250, 14
	s_add_u32 s40, s10, s0
	s_mov_b32 s0, 0xf800000
	v_readlane_b32 s11, v250, 15
	s_waitcnt lgkmcnt(0)
	v_add_f32_e32 v76, v76, v80
	s_nop 1
	v_mov_b32_dpp v80, v76 row_half_mirror row_mask:0xf bank_mask:0xf
	s_addc_u32 s41, s11, s1
	s_add_u32 s42, s40, 0x1000
	s_addc_u32 s43, s41, 0
	s_ashr_i32 s45, s44, 31
	s_waitcnt lgkmcnt(0)
	v_add_f32_e32 v76, v76, v80
	s_nop 1
	v_mov_b32_dpp v80, v76 row_mirror row_mask:0xf bank_mask:0xf
	s_waitcnt lgkmcnt(0)
	v_add_f32_e32 v76, v76, v80
	v_mov_b32_e32 v80, v76
	s_nop 1
	v_permlane16_swap_b32_e32 v76, v80
	s_waitcnt lgkmcnt(0)
	v_add_f32_e32 v76, v76, v80
	v_mov_b32_e32 v80, v76
	s_nop 1
	v_permlane32_swap_b32_e32 v76, v80
	s_waitcnt lgkmcnt(0)
	v_add_f32_e32 v76, v76, v80
	v_fmamk_f32 v76, v76, 0x3a800000, v212
	v_cmp_gt_f32_e32 vcc, s0, v76
	v_mul_f32_e32 v80, 0x4f800000, v76
	s_nop 0
	v_cndmask_b32_e32 v76, v76, v80, vcc
	v_sqrt_f32_e32 v80, v76
	s_nop 0
	v_add_u32_e32 v81, -1, v80
	v_fma_f32 v82, -v81, v80, v76
	v_cmp_ge_f32_e64 s[0:1], 0, v82
	v_add_u32_e32 v82, 1, v80
	s_nop 0
	v_cndmask_b32_e64 v81, v80, v81, s[0:1]
	v_fma_f32 v80, -v82, v80, v76
	v_cmp_lt_f32_e64 s[0:1], 0, v80
	s_nop 1
	v_cndmask_b32_e64 v80, v81, v82, s[0:1]
	v_mul_f32_e32 v81, 0x37800000, v80
	v_cndmask_b32_e32 v80, v80, v81, vcc
	v_cmp_class_f32_e32 vcc, v76, v241
	s_nop 1
	v_cndmask_b32_e32 v76, v80, v76, vcc
	v_div_scale_f32 v80, s[0:1], v76, v76, 1.0
	v_rcp_f32_e32 v81, v80
	s_lshl_b64 s[0:1], s[44:45], 11
	v_fma_f32 v82, -v80, v81, 1.0
	v_fmac_f32_e32 v81, v82, v81
	v_div_scale_f32 v82, vcc, 1.0, v76, 1.0
	v_mul_f32_e32 v83, v82, v81
	v_fma_f32 v84, -v80, v83, v82
	v_fmac_f32_e32 v83, v84, v81
	v_fma_f32 v80, -v80, v83, v82
	v_div_fmas_f32 v80, v80, v81, v83
	v_div_fixup_f32 v76, v80, v76, 1.0
	global_load_dwordx4 v[80:83], v[66:67], off
	global_load_dwordx4 v[84:87], v98, s[42:43]
	global_load_dwordx4 v[88:91], v98, s[40:41]
	v_pk_mul_f32 v[64:65], v[64:65], v[76:77] op_sel_hi:[1,0]
	v_pk_mul_f32 v[62:63], v[62:63], v[76:77] op_sel_hi:[1,0]
	v_pk_mul_f32 v[60:61], v[60:61], v[76:77] op_sel_hi:[1,0]
	v_pk_mul_f32 v[58:59], v[58:59], v[76:77] op_sel_hi:[1,0]
	v_pk_mul_f32 v[56:57], v[56:57], v[76:77] op_sel_hi:[1,0]
	v_pk_mul_f32 v[54:55], v[54:55], v[76:77] op_sel_hi:[1,0]
	v_pk_mul_f32 v[52:53], v[52:53], v[76:77] op_sel_hi:[1,0]
	v_pk_mul_f32 v[50:51], v[50:51], v[76:77] op_sel_hi:[1,0]
	s_waitcnt vmcnt(2)
	v_pk_mul_f32 v[62:63], v[80:81], v[62:63]
	v_pk_mul_f32 v[64:65], v[82:83], v[64:65]
	s_waitcnt vmcnt(1)
	v_pk_add_f32 v[80:81], v[86:87], 1.0 op_sel_hi:[1,0]
	v_pk_add_f32 v[82:83], v[84:85], 1.0 op_sel_hi:[1,0]
	s_waitcnt vmcnt(0)
	v_pk_fma_f32 v[64:65], v[80:81], v[64:65], v[90:91]
	v_pk_fma_f32 v[62:63], v[82:83], v[62:63], v[88:89]
	s_nop 0
	v_cvt_pk_bf16_f32 v62, v62, v63
	v_cvt_pk_bf16_f32 v63, v64, v65
	v_lshl_add_u64 v[64:65], v[74:75], 0, s[0:1]
	global_store_dwordx2 v[64:65], v[62:63], off
	global_load_dwordx4 v[80:83], v[66:67], off offset:1024
	v_lshlrev_b32_e32 v62, 2, v68
	global_load_dwordx4 v[84:87], v62, s[42:43]
	global_load_dwordx4 v[88:91], v98, s[40:41] offset:1024
	v_readlane_b32 s0, v253, 58
	s_add_i32 s44, s0, s9
	s_cmpk_gt_i32 s44, 0x47ff
	s_waitcnt vmcnt(2)
	v_pk_mul_f32 v[58:59], v[80:81], v[58:59]
	v_pk_mul_f32 v[60:61], v[82:83], v[60:61]
	s_waitcnt vmcnt(1)
	v_pk_add_f32 v[80:81], v[86:87], 1.0 op_sel_hi:[1,0]
	v_pk_add_f32 v[82:83], v[84:85], 1.0 op_sel_hi:[1,0]
	s_waitcnt vmcnt(0)
	v_pk_fma_f32 v[60:61], v[80:81], v[60:61], v[90:91]
	v_pk_fma_f32 v[58:59], v[82:83], v[58:59], v[88:89]
	s_nop 0
	v_cvt_pk_bf16_f32 v58, v58, v59
	v_cvt_pk_bf16_f32 v59, v60, v61
	global_store_dwordx2 v[64:65], v[58:59], off offset:512
	global_load_dwordx4 v[80:83], v[66:67], off offset:2048
	v_lshlrev_b32_e32 v58, 2, v70
	global_load_dwordx4 v[84:87], v58, s[42:43]
	global_load_dwordx4 v[88:91], v98, s[40:41] offset:2048
	s_waitcnt vmcnt(2)
	v_pk_mul_f32 v[54:55], v[80:81], v[54:55]
	v_pk_mul_f32 v[56:57], v[82:83], v[56:57]
	s_waitcnt vmcnt(1)
	v_pk_add_f32 v[60:61], v[86:87], 1.0 op_sel_hi:[1,0]
	v_pk_add_f32 v[80:81], v[84:85], 1.0 op_sel_hi:[1,0]
	s_waitcnt vmcnt(0)
	v_pk_fma_f32 v[56:57], v[56:57], v[60:61], v[90:91]
	v_pk_fma_f32 v[54:55], v[54:55], v[80:81], v[88:89]
	s_nop 0
	v_cvt_pk_bf16_f32 v54, v54, v55
	v_cvt_pk_bf16_f32 v55, v56, v57
	global_store_dwordx2 v[64:65], v[54:55], off offset:1024
	global_load_dwordx4 v[80:83], v[66:67], off offset:3072
	v_lshlrev_b32_e32 v54, 2, v72
	global_load_dwordx4 v[84:87], v54, s[42:43]
	global_load_dwordx4 v[88:91], v98, s[40:41] offset:3072
	s_waitcnt vmcnt(2)
	v_pk_mul_f32 v[50:51], v[50:51], v[80:81]
	v_pk_mul_f32 v[52:53], v[52:53], v[82:83]
	s_waitcnt vmcnt(1)
	v_pk_add_f32 v[56:57], v[86:87], 1.0 op_sel_hi:[1,0]
	v_pk_add_f32 v[60:61], v[84:85], 1.0 op_sel_hi:[1,0]
	s_waitcnt vmcnt(0)
	v_pk_fma_f32 v[52:53], v[52:53], v[56:57], v[90:91]
	v_pk_fma_f32 v[50:51], v[50:51], v[60:61], v[88:89]
	s_nop 0
	v_cvt_pk_bf16_f32 v50, v50, v51
	v_cvt_pk_bf16_f32 v51, v52, v53
	global_store_dwordx2 v[64:65], v[50:51], off offset:1536
	s_cbranch_scc1 .LBB0_347
	s_min_i32 s0, s44, 0x4000
	s_lshr_b32 s0, s0, 11
	s_mulk_i32 s0, 0x1800
	s_ashr_i32 s1, s0, 31
	s_lshl_b64 s[0:1], s[0:1], 2
	v_readlane_b32 s10, v250, 14
	v_readlane_b32 s11, v250, 15
	s_add_u32 s40, s10, s0
	s_addc_u32 s41, s11, s1
	s_add_u32 s42, s40, 0x1000
	s_addc_u32 s43, s41, 0
	global_load_dwordx4 v[80:83], v[66:67], off
	global_load_dwordx4 v[84:87], v98, s[42:43]
	global_load_dwordx4 v[88:91], v98, s[40:41]
	v_pk_mul_f32 v[50:51], v[48:49], v[48:49]
	v_pk_mul_f32 v[52:53], v[46:47], v[46:47]
	s_mov_b32 s0, 0xf800000
	v_pk_mov_b32 v[56:57], v[52:53], v[50:51] op_sel:[1,0]
	v_mov_b32_e32 v53, v51
	v_pk_add_f32 v[50:51], v[56:57], v[52:53]
	v_pk_mul_f32 v[52:53], v[12:13], v[12:13]
	v_pk_add_f32 v[50:51], v[50:51], v[50:51] op_sel_hi:[0,1]
	v_pk_mul_f32 v[56:57], v[10:11], v[10:11]
	v_mul_f32_e32 v50, v6, v6
	v_pk_mov_b32 v[60:61], v[56:57], v[52:53] op_sel:[1,0]
	v_mov_b32_e32 v57, v53
	v_pk_add_f32 v[52:53], v[60:61], v[56:57]
	v_pk_fma_f32 v[56:57], v[6:7], v[6:7], v[50:51] op_sel_hi:[1,1,0]
	v_mul_f32_e32 v50, v8, v8
	v_pk_add_f32 v[52:53], v[52:53], v[52:53] op_sel_hi:[0,1]
	v_pk_fma_f32 v[60:61], v[8:9], v[8:9], v[50:51] op_sel_hi:[1,1,0]
	v_mul_f32_e32 v56, v2, v2
	v_mul_f32_e32 v60, v3, v3
	v_mul_f32_e32 v52, v4, v4
	v_mul_f32_e32 v50, v5, v5
	v_pk_add_f32 v[56:57], v[56:57], v[60:61]
	v_pk_add_f32 v[50:51], v[52:53], v[50:51]
	s_ashr_i32 s45, s44, 31
	v_pk_add_f32 v[50:51], v[56:57], v[50:51]
	s_nop 0
	v_add_f32_e32 v50, v50, v51
	s_nop 1
	v_mov_b32_dpp v51, v50 quad_perm:[1,0,3,2] row_mask:0xf bank_mask:0xf
	s_waitcnt lgkmcnt(0)
	v_add_f32_e32 v50, v50, v51
	s_nop 1
	v_mov_b32_dpp v51, v50 quad_perm:[2,3,0,1] row_mask:0xf bank_mask:0xf
	s_waitcnt lgkmcnt(0)
	v_add_f32_e32 v50, v50, v51
	s_nop 1
	v_mov_b32_dpp v51, v50 row_half_mirror row_mask:0xf bank_mask:0xf
	s_waitcnt lgkmcnt(0)
	v_add_f32_e32 v50, v50, v51
	s_nop 1
	v_mov_b32_dpp v51, v50 row_mirror row_mask:0xf bank_mask:0xf
	s_waitcnt lgkmcnt(0)
	v_add_f32_e32 v50, v50, v51
	v_mov_b32_e32 v51, v50
	s_nop 1
	v_permlane16_swap_b32_e32 v50, v51
	s_waitcnt lgkmcnt(0)
	v_add_f32_e32 v50, v50, v51
	v_mov_b32_e32 v51, v50
	s_nop 1
	v_permlane32_swap_b32_e32 v50, v51
	s_waitcnt lgkmcnt(0)
	v_add_f32_e32 v50, v50, v51
	v_fmamk_f32 v50, v50, 0x3a800000, v212
	v_cmp_gt_f32_e32 vcc, s0, v50
	v_mul_f32_e32 v51, 0x4f800000, v50
	s_nop 0
	v_cndmask_b32_e32 v50, v50, v51, vcc
	v_sqrt_f32_e32 v51, v50
	s_nop 0
	v_add_u32_e32 v52, -1, v51
	v_fma_f32 v53, -v52, v51, v50
	v_cmp_ge_f32_e64 s[0:1], 0, v53
	v_add_u32_e32 v53, 1, v51
	s_nop 0
	v_cndmask_b32_e64 v52, v51, v52, s[0:1]
	v_fma_f32 v51, -v53, v51, v50
	v_cmp_lt_f32_e64 s[0:1], 0, v51
	s_nop 1
	v_cndmask_b32_e64 v51, v52, v53, s[0:1]
	v_mul_f32_e32 v52, 0x37800000, v51
	v_cndmask_b32_e32 v51, v51, v52, vcc
	v_cmp_class_f32_e32 vcc, v50, v241
	s_nop 1
	v_cndmask_b32_e32 v50, v51, v50, vcc
	v_div_scale_f32 v51, s[0:1], v50, v50, 1.0
	v_rcp_f32_e32 v52, v51
	s_lshl_b64 s[0:1], s[44:45], 11
	v_fma_f32 v53, -v51, v52, 1.0
	v_fmac_f32_e32 v52, v53, v52
	v_div_scale_f32 v53, vcc, 1.0, v50, 1.0
	v_mul_f32_e32 v55, v53, v52
	v_fma_f32 v56, -v51, v55, v53
	v_fmac_f32_e32 v55, v56, v52
	v_fma_f32 v51, -v51, v55, v53
	v_div_fmas_f32 v51, v51, v52, v55
	v_div_fixup_f32 v50, v51, v50, 1.0
	v_pk_mul_f32 v[48:49], v[48:49], v[50:51] op_sel_hi:[1,0]
	v_pk_mul_f32 v[46:47], v[46:47], v[50:51] op_sel_hi:[1,0]
	s_waitcnt vmcnt(2)
	v_pk_mul_f32 v[48:49], v[82:83], v[48:49]
	v_pk_mul_f32 v[46:47], v[80:81], v[46:47]
	s_waitcnt vmcnt(1)
	v_pk_add_f32 v[52:53], v[86:87], 1.0 op_sel_hi:[1,0]
	v_pk_add_f32 v[56:57], v[84:85], 1.0 op_sel_hi:[1,0]
	s_waitcnt vmcnt(0)
	v_pk_fma_f32 v[48:49], v[52:53], v[48:49], v[90:91]
	v_pk_fma_f32 v[46:47], v[56:57], v[46:47], v[88:89]
	v_lshl_add_u64 v[52:53], v[74:75], 0, s[0:1]
	v_cvt_pk_bf16_f32 v46, v46, v47
	v_cvt_pk_bf16_f32 v47, v48, v49
	global_store_dwordx2 v[52:53], v[46:47], off
	global_load_dwordx4 v[46:49], v[66:67], off offset:1024
	s_nop 0
	global_load_dwordx4 v[60:63], v62, s[42:43]
	s_nop 0
	global_load_dwordx4 v[80:83], v98, s[40:41] offset:1024
	v_pk_mul_f32 v[12:13], v[12:13], v[50:51] op_sel_hi:[1,0]
	v_pk_mul_f32 v[10:11], v[10:11], v[50:51] op_sel_hi:[1,0]
	v_pk_mul_f32 v[8:9], v[8:9], v[50:51] op_sel_hi:[1,0]
	v_pk_mul_f32 v[6:7], v[6:7], v[50:51] op_sel_hi:[1,0]
	v_pk_mul_f32 v[4:5], v[4:5], v[50:51] op_sel_hi:[1,0]
	v_pk_mul_f32 v[2:3], v[2:3], v[50:51] op_sel_hi:[1,0]
	s_waitcnt vmcnt(2)
	v_pk_mul_f32 v[10:11], v[46:47], v[10:11]
	v_pk_mul_f32 v[12:13], v[48:49], v[12:13]
	s_waitcnt vmcnt(1)
	v_pk_add_f32 v[46:47], v[62:63], 1.0 op_sel_hi:[1,0]
	v_pk_add_f32 v[48:49], v[60:61], 1.0 op_sel_hi:[1,0]
	s_waitcnt vmcnt(0)
	v_pk_fma_f32 v[12:13], v[46:47], v[12:13], v[82:83]
	v_pk_fma_f32 v[10:11], v[48:49], v[10:11], v[80:81]
	s_nop 0
	v_cvt_pk_bf16_f32 v10, v10, v11
	v_cvt_pk_bf16_f32 v11, v12, v13
	global_store_dwordx2 v[52:53], v[10:11], off offset:512
	global_load_dwordx4 v[10:13], v[66:67], off offset:2048
	s_nop 0
	global_load_dwordx4 v[46:49], v58, s[42:43]
	s_nop 0
	global_load_dwordx4 v[56:59], v98, s[40:41] offset:2048
	s_waitcnt vmcnt(2)
	v_pk_mul_f32 v[6:7], v[10:11], v[6:7]
	v_pk_mul_f32 v[8:9], v[12:13], v[8:9]
	s_waitcnt vmcnt(1)
	v_pk_add_f32 v[10:11], v[48:49], 1.0 op_sel_hi:[1,0]
	v_pk_add_f32 v[12:13], v[46:47], 1.0 op_sel_hi:[1,0]
	s_waitcnt vmcnt(0)
	v_pk_fma_f32 v[8:9], v[8:9], v[10:11], v[58:59]
	v_pk_fma_f32 v[6:7], v[6:7], v[12:13], v[56:57]
	s_nop 0
	v_cvt_pk_bf16_f32 v6, v6, v7
	v_cvt_pk_bf16_f32 v7, v8, v9
	global_store_dwordx2 v[52:53], v[6:7], off offset:1024
	global_load_dwordx4 v[6:9], v[66:67], off offset:3072
	s_nop 0
	global_load_dwordx4 v[10:13], v54, s[42:43]
	global_load_dwordx4 v[46:49], v98, s[40:41] offset:3072
	s_waitcnt vmcnt(2)
	v_pk_mul_f32 v[2:3], v[2:3], v[6:7]
	v_pk_mul_f32 v[4:5], v[4:5], v[8:9]
	s_waitcnt vmcnt(1)
	v_pk_add_f32 v[6:7], v[12:13], 1.0 op_sel_hi:[1,0]
	v_pk_add_f32 v[8:9], v[10:11], 1.0 op_sel_hi:[1,0]
	s_waitcnt vmcnt(0)
	v_pk_fma_f32 v[4:5], v[4:5], v[6:7], v[48:49]
	v_pk_fma_f32 v[2:3], v[2:3], v[8:9], v[46:47]
	s_nop 0
	v_cvt_pk_bf16_f32 v2, v2, v3
	v_cvt_pk_bf16_f32 v3, v4, v5
	global_store_dwordx2 v[52:53], v[2:3], off offset:1536
	s_branch .LBB0_347

.LBB0_723:
	s_waitcnt lgkmcnt(0)
	v_bfe_u32 v65, v64, 16, 1
	s_movk_i32 s9, 0x7fff
	v_add3_u32 v64, v64, v65, s9
	v_lshrrev_b32_e32 v72, 16, v64
	v_lshl_add_u64 v[64:65], s[86:87], 0, v[16:17]
	v_add_co_u32_e32 v64, vcc, 0xb900000, v64
	s_nop 1
	v_addc_co_u32_e32 v65, vcc, 0, v65, vcc
	s_andn2_b64 vcc, exec, s[0:1]
	global_store_short v[64:65], v72, off offset:256
	global_store_short v[64:65], v72, off offset:640
	global_store_short v[64:65], v72, off offset:1024
	global_store_short v[64:65], v72, off offset:1408
	s_cbranch_vccnz .LBB0_725
	global_load_dwordx4 v[72:75], v[12:13], off
	global_load_dwordx4 v[76:79], v[12:13], off offset:1024
	global_load_dwordx4 v[80:83], v[12:13], off offset:2048
	global_load_dwordx4 v[84:87], v[14:15], off
	v_lshlrev_b32_e32 v88, 16, v59
	v_and_b32_e32 v89, 0xffff0000, v59
	v_lshlrev_b32_e32 v90, 16, v57
	v_and_b32_e32 v91, 0xffff0000, v57
	v_lshlrev_b32_e32 v92, 16, v39
	v_and_b32_e32 v93, 0xffff0000, v39
	v_lshlrev_b32_e32 v94, 16, v41
	v_and_b32_e32 v95, 0xffff0000, v41
	v_pk_mul_f32 v[88:89], v[90:91], v[88:89]
	v_pk_mul_f32 v[90:91], v[92:93], v[94:95]
	v_lshlrev_b32_e32 v96, 16, v61
	v_and_b32_e32 v97, 0xffff0000, v61
	v_lshlrev_b32_e32 v100, 16, v63
	v_and_b32_e32 v101, 0xffff0000, v63
	v_pk_mul_f32 v[92:93], v[100:101], v[96:97]
	v_and_b32_e32 v59, 0xffff0000, v56
	v_and_b32_e32 v57, 0xffff0000, v38
	v_and_b32_e32 v61, 0xffff0000, v62
	v_lshlrev_b32_e32 v64, 16, v33
	v_and_b32_e32 v65, 0xffff0000, v33
	s_waitcnt vmcnt(2)
	v_pk_mul_f32 v[78:79], v[90:91], v[78:79]
	s_nop 0
	v_pk_fma_f32 v[74:75], v[88:89], v[74:75], v[78:79]
	v_lshlrev_b32_e32 v78, 16, v58
	s_waitcnt vmcnt(1)
	v_pk_fma_f32 v[74:75], v[92:93], v[82:83], v[74:75]
	v_and_b32_e32 v79, 0xffff0000, v58
	v_lshlrev_b32_e32 v58, 16, v56
	v_lshlrev_b32_e32 v56, 16, v38
	v_lshlrev_b32_e32 v82, 16, v40
	v_and_b32_e32 v83, 0xffff0000, v40
	v_pk_mul_f32 v[56:57], v[56:57], v[82:83]
	s_waitcnt vmcnt(0)
	v_pk_add_f32 v[74:75], v[86:87], v[74:75]
	v_lshlrev_b32_e32 v86, 16, v60
	v_and_b32_e32 v87, 0xffff0000, v60
	v_lshlrev_b32_e32 v60, 16, v62
	v_pk_mul_f32 v[58:59], v[58:59], v[78:79]
	v_pk_mul_f32 v[56:57], v[56:57], v[76:77]
	v_pk_mul_f32 v[60:61], v[60:61], v[86:87]
	v_pk_fma_f32 v[56:57], v[58:59], v[72:73], v[56:57]
	v_pk_mul_f32 v[64:65], v[74:75], v[64:65]
	v_pk_fma_f32 v[56:57], v[60:61], v[80:81], v[56:57]
	v_lshlrev_b32_e32 v74, 16, v32
	v_and_b32_e32 v75, 0xffff0000, v32
	v_pk_add_f32 v[56:57], v[84:85], v[56:57]
	v_mov_b32_e32 v61, v65
	v_pk_mul_f32 v[56:57], v[56:57], v[74:75]
	v_mov_b32_e32 v59, v64
	v_mov_b32_e32 v60, v57
	v_mov_b32_e32 v58, v56
	v_pk_mul_f32 v[60:61], v[60:61], v[60:61]
	s_nop 0
	v_pk_fma_f32 v[58:59], v[58:59], v[58:59], v[60:61]
	s_nop 0
	v_add_f32_e32 v58, v58, v59
	s_nop 1
	v_mov_b32_dpp v59, v58 quad_perm:[1,0,3,2] row_mask:0xf bank_mask:0xf
	s_waitcnt lgkmcnt(0)
	v_add_f32_e32 v58, v58, v59
	s_nop 1
	v_mov_b32_dpp v59, v58 quad_perm:[2,3,0,1] row_mask:0xf bank_mask:0xf
	s_waitcnt lgkmcnt(0)
	v_add_f32_e32 v58, v58, v59
	s_nop 1
	v_mov_b32_dpp v59, v58 row_half_mirror row_mask:0xf bank_mask:0xf
	s_waitcnt lgkmcnt(0)
	v_add_f32_e32 v58, v58, v59
	s_nop 1
	v_mov_b32_dpp v59, v58 row_mirror row_mask:0xf bank_mask:0xf
	s_waitcnt lgkmcnt(0)
	v_add_f32_e32 v58, v58, v59
	v_mov_b32_e32 v59, v58
	s_nop 1
	v_permlane16_swap_b32_e32 v58, v59
	s_waitcnt lgkmcnt(0)
	v_add_f32_e32 v58, v58, v59
	v_mov_b32_e32 v59, v58
	s_nop 1
	v_permlane32_swap_b32_e32 v58, v59
	s_waitcnt lgkmcnt(0)
	v_add_f32_e32 v58, v58, v59
	v_fmamk_f32 v58, v58, 0x3b800000, v212
	v_cmp_gt_f32_e32 vcc, s12, v58
	v_mul_f32_e32 v59, 0x4f800000, v58
	s_nop 0
	v_cndmask_b32_e32 v58, v58, v59, vcc
	v_sqrt_f32_e32 v59, v58
	s_nop 0
	v_add_u32_e32 v60, -1, v59
	v_fma_f32 v61, -v60, v59, v58
	v_cmp_ge_f32_e64 s[0:1], 0, v61
	v_add_u32_e32 v61, 1, v59
	s_nop 0
	v_cndmask_b32_e64 v60, v59, v60, s[0:1]
	v_fma_f32 v59, -v61, v59, v58
	v_cmp_lt_f32_e64 s[0:1], 0, v59
	s_nop 1
	v_cndmask_b32_e64 v59, v60, v61, s[0:1]
	v_mul_f32_e32 v60, 0x37800000, v59
	v_cndmask_b32_e32 v59, v59, v60, vcc
	v_cmp_class_f32_e32 vcc, v58, v241
	s_nop 1
	v_cndmask_b32_e32 v58, v59, v58, vcc
	v_div_scale_f32 v59, s[0:1], v58, v58, 1.0
	v_rcp_f32_e32 v60, v59
	s_nop 0
	v_fma_f32 v61, -v59, v60, 1.0
	v_fmac_f32_e32 v60, v61, v60
	v_div_scale_f32 v61, vcc, 1.0, v58, 1.0
	v_mul_f32_e32 v62, v61, v60
	v_fma_f32 v63, -v59, v62, v61
	v_fmac_f32_e32 v62, v63, v60
	v_fma_f32 v59, -v59, v62, v61
	v_div_fmas_f32 v59, v59, v60, v62
	v_div_fixup_f32 v58, v59, v58, 1.0
	v_pk_mul_f32 v[56:57], v[56:57], v[58:59] op_sel_hi:[1,0]
	v_pk_mul_f32 v[58:59], v[64:65], v[58:59] op_sel_hi:[1,0]
	v_cvt_pk_bf16_f32 v56, v56, v57
	v_cvt_pk_bf16_f32 v57, v58, v59
	global_store_dwordx2 v[18:19], v[56:57], off

.LBB0_728:
	s_waitcnt lgkmcnt(0)
	v_bfe_u32 v56, v57, 16, 1
	s_movk_i32 s0, 0x7fff
	v_add3_u32 v56, v57, v56, s0
	v_lshrrev_b32_e32 v58, 16, v56
	v_mad_i64_i32 v[56:57], s[0:1], s44, v203, v[10:11]
	s_cmp_ge_i32 s44, s4
	global_store_short v[56:57], v58, off
	global_store_short v[56:57], v58, off offset:384
	global_store_short v[56:57], v58, off offset:768
	global_store_short v[56:57], v58, off offset:1152
	s_cbranch_scc1 .LBB0_730
	global_load_dwordx4 v[56:59], v[12:13], off
	global_load_dwordx4 v[60:63], v[12:13], off offset:1024
	global_load_dwordx4 v[72:75], v[12:13], off offset:2048
	global_load_dwordx4 v[76:79], v[14:15], off
	v_lshlrev_b32_e32 v80, 16, v9
	v_and_b32_e32 v81, 0xffff0000, v9
	v_lshlrev_b32_e32 v82, 16, v45
	v_and_b32_e32 v83, 0xffff0000, v45
	v_lshlrev_b32_e32 v84, 16, v31
	v_and_b32_e32 v85, 0xffff0000, v31
	v_lshlrev_b32_e32 v86, 16, v37
	v_and_b32_e32 v87, 0xffff0000, v37
	v_pk_mul_f32 v[80:81], v[82:83], v[80:81]
	v_pk_mul_f32 v[82:83], v[84:85], v[86:87]
	v_lshlrev_b32_e32 v88, 16, v49
	v_and_b32_e32 v89, 0xffff0000, v49
	v_lshlrev_b32_e32 v90, 16, v53
	v_and_b32_e32 v91, 0xffff0000, v53
	v_pk_mul_f32 v[84:85], v[90:91], v[88:89]
	v_lshlrev_b32_e32 v64, 16, v27
	v_and_b32_e32 v65, 0xffff0000, v27
	s_ashr_i32 s45, s44, 31
	v_lshlrev_b32_e32 v98, 1, v6
	s_waitcnt vmcnt(2)
	v_pk_mul_f32 v[62:63], v[82:83], v[62:63]
	s_nop 0
	v_pk_fma_f32 v[58:59], v[80:81], v[58:59], v[62:63]
	v_lshlrev_b32_e32 v80, 16, v36
	s_waitcnt vmcnt(1)
	v_pk_fma_f32 v[58:59], v[84:85], v[74:75], v[58:59]
	v_lshlrev_b32_e32 v74, 16, v44
	s_waitcnt vmcnt(0)
	v_pk_add_f32 v[58:59], v[78:79], v[58:59]
	v_and_b32_e32 v75, 0xffff0000, v44
	v_pk_mul_f32 v[58:59], v[58:59], v[64:65]
	v_lshlrev_b32_e32 v64, 16, v8
	v_and_b32_e32 v65, 0xffff0000, v8
	v_lshlrev_b32_e32 v78, 16, v30
	v_and_b32_e32 v79, 0xffff0000, v30
	v_and_b32_e32 v81, 0xffff0000, v36
	v_pk_mul_f32 v[64:65], v[74:75], v[64:65]
	v_pk_mul_f32 v[74:75], v[78:79], v[80:81]
	v_lshlrev_b32_e32 v82, 16, v48
	v_and_b32_e32 v83, 0xffff0000, v48
	v_lshlrev_b32_e32 v84, 16, v52
	v_and_b32_e32 v85, 0xffff0000, v52
	v_pk_mul_f32 v[60:61], v[74:75], v[60:61]
	v_pk_mul_f32 v[78:79], v[84:85], v[82:83]
	v_pk_fma_f32 v[56:57], v[64:65], v[56:57], v[60:61]
	v_lshlrev_b32_e32 v62, 16, v26
	v_pk_fma_f32 v[56:57], v[78:79], v[72:73], v[56:57]
	v_and_b32_e32 v63, 0xffff0000, v26
	v_pk_add_f32 v[56:57], v[76:77], v[56:57]
	v_mov_b32_e32 v61, v58
	v_pk_mul_f32 v[56:57], v[56:57], v[62:63]
	v_mov_b32_e32 v63, v59
	v_mov_b32_e32 v62, v57
	v_mov_b32_e32 v60, v56
	v_pk_mul_f32 v[62:63], v[62:63], v[62:63]
	s_nop 0
	v_pk_fma_f32 v[60:61], v[60:61], v[60:61], v[62:63]
	s_nop 0
	v_add_f32_e32 v60, v60, v61
	s_nop 1
	v_mov_b32_dpp v61, v60 quad_perm:[1,0,3,2] row_mask:0xf bank_mask:0xf
	s_waitcnt lgkmcnt(0)
	v_add_f32_e32 v60, v60, v61
	s_nop 1
	v_mov_b32_dpp v61, v60 quad_perm:[2,3,0,1] row_mask:0xf bank_mask:0xf
	s_waitcnt lgkmcnt(0)
	v_add_f32_e32 v60, v60, v61
	s_nop 1
	v_mov_b32_dpp v61, v60 row_half_mirror row_mask:0xf bank_mask:0xf
	s_waitcnt lgkmcnt(0)
	v_add_f32_e32 v60, v60, v61
	s_nop 1
	v_mov_b32_dpp v61, v60 row_mirror row_mask:0xf bank_mask:0xf
	s_waitcnt lgkmcnt(0)
	v_add_f32_e32 v60, v60, v61
	v_mov_b32_e32 v61, v60
	s_nop 1
	v_permlane16_swap_b32_e32 v60, v61
	s_waitcnt lgkmcnt(0)
	v_add_f32_e32 v60, v60, v61
	v_mov_b32_e32 v61, v60
	s_nop 1
	v_permlane32_swap_b32_e32 v60, v61
	s_waitcnt lgkmcnt(0)
	v_add_f32_e32 v60, v60, v61
	v_fmamk_f32 v60, v60, 0x3b800000, v212
	v_cmp_gt_f32_e32 vcc, s12, v60
	v_mul_f32_e32 v61, 0x4f800000, v60
	s_nop 0
	v_cndmask_b32_e32 v60, v60, v61, vcc
	v_sqrt_f32_e32 v61, v60
	s_nop 0
	v_add_u32_e32 v62, -1, v61
	v_fma_f32 v63, -v62, v61, v60
	v_cmp_ge_f32_e64 s[0:1], 0, v63
	v_add_u32_e32 v63, 1, v61
	s_nop 0
	v_cndmask_b32_e64 v62, v61, v62, s[0:1]
	v_fma_f32 v61, -v63, v61, v60
	v_cmp_lt_f32_e64 s[0:1], 0, v61
	s_nop 1
	v_cndmask_b32_e64 v61, v62, v63, s[0:1]
	v_mul_f32_e32 v62, 0x37800000, v61
	v_cndmask_b32_e32 v61, v61, v62, vcc
	v_cmp_class_f32_e32 vcc, v60, v241
	s_nop 1
	v_cndmask_b32_e32 v60, v61, v60, vcc
	v_div_scale_f32 v61, s[0:1], v60, v60, 1.0
	v_rcp_f32_e32 v62, v61
	s_lshl_b64 s[0:1], s[44:45], 11
	s_add_u32 s0, s84, s0
	s_addc_u32 s1, s85, s1
	v_fma_f32 v63, -v61, v62, 1.0
	v_fmac_f32_e32 v62, v63, v62
	v_div_scale_f32 v63, vcc, 1.0, v60, 1.0
	v_mul_f32_e32 v64, v63, v62
	v_fma_f32 v65, -v61, v64, v63
	v_fmac_f32_e32 v64, v65, v62
	v_fma_f32 v61, -v61, v64, v63
	v_div_fmas_f32 v61, v61, v62, v64
	v_div_fixup_f32 v60, v61, v60, 1.0
	v_pk_mul_f32 v[56:57], v[56:57], v[60:61] op_sel_hi:[1,0]
	v_pk_mul_f32 v[58:59], v[58:59], v[60:61] op_sel_hi:[1,0]
	v_cvt_pk_bf16_f32 v56, v56, v57
	v_cvt_pk_bf16_f32 v57, v58, v59
	v_lshl_add_u64 v[58:59], s[0:1], 0, v[98:99]
	v_add_co_u32_e32 v58, vcc, 0x1b00000, v58
	s_nop 1
	v_addc_co_u32_e32 v59, vcc, 0, v59, vcc
	global_store_dwordx2 v[58:59], v[56:57], off offset:1536

.LBB0_733:
	s_waitcnt lgkmcnt(0)
	v_bfe_u32 v56, v57, 16, 1
	s_movk_i32 s0, 0x7fff
	v_add3_u32 v56, v57, v56, s0
	v_lshrrev_b32_e32 v58, 16, v56
	v_mad_i64_i32 v[56:57], s[0:1], s36, v203, v[10:11]
	s_cmp_ge_i32 s36, s4
	global_store_short v[56:57], v58, off
	global_store_short v[56:57], v58, off offset:384
	global_store_short v[56:57], v58, off offset:768
	global_store_short v[56:57], v58, off offset:1152
	s_cbranch_scc1 .LBB0_698
	global_load_dwordx4 v[56:59], v[12:13], off
	global_load_dwordx4 v[60:63], v[12:13], off offset:1024
	global_load_dwordx4 v[72:75], v[12:13], off offset:2048
	global_load_dwordx4 v[76:79], v[14:15], off
	v_lshlrev_b32_e32 v80, 16, v43
	v_and_b32_e32 v81, 0xffff0000, v43
	v_lshlrev_b32_e32 v82, 16, v47
	v_and_b32_e32 v83, 0xffff0000, v47
	v_lshlrev_b32_e32 v84, 16, v29
	v_and_b32_e32 v85, 0xffff0000, v29
	v_lshlrev_b32_e32 v86, 16, v35
	v_and_b32_e32 v87, 0xffff0000, v35
	v_pk_mul_f32 v[80:81], v[82:83], v[80:81]
	v_pk_mul_f32 v[82:83], v[84:85], v[86:87]
	v_lshlrev_b32_e32 v88, 16, v51
	v_and_b32_e32 v89, 0xffff0000, v51
	v_lshlrev_b32_e32 v90, 16, v55
	v_and_b32_e32 v91, 0xffff0000, v55
	v_pk_mul_f32 v[84:85], v[90:91], v[88:89]
	v_lshlrev_b32_e32 v64, 16, v25
	v_and_b32_e32 v65, 0xffff0000, v25
	s_ashr_i32 s37, s36, 31
	v_lshlrev_b32_e32 v98, 1, v6
	s_waitcnt vmcnt(2)
	v_pk_mul_f32 v[62:63], v[82:83], v[62:63]
	s_nop 0
	v_pk_fma_f32 v[58:59], v[80:81], v[58:59], v[62:63]
	v_lshlrev_b32_e32 v80, 16, v34
	s_waitcnt vmcnt(1)
	v_pk_fma_f32 v[58:59], v[84:85], v[74:75], v[58:59]
	v_lshlrev_b32_e32 v74, 16, v46
	s_waitcnt vmcnt(0)
	v_pk_add_f32 v[58:59], v[78:79], v[58:59]
	v_and_b32_e32 v75, 0xffff0000, v46
	v_pk_mul_f32 v[58:59], v[58:59], v[64:65]
	v_lshlrev_b32_e32 v64, 16, v42
	v_and_b32_e32 v65, 0xffff0000, v42
	v_lshlrev_b32_e32 v78, 16, v28
	v_and_b32_e32 v79, 0xffff0000, v28
	v_and_b32_e32 v81, 0xffff0000, v34
	v_pk_mul_f32 v[64:65], v[74:75], v[64:65]
	v_pk_mul_f32 v[74:75], v[78:79], v[80:81]
	v_lshlrev_b32_e32 v82, 16, v50
	v_and_b32_e32 v83, 0xffff0000, v50
	v_lshlrev_b32_e32 v84, 16, v54
	v_and_b32_e32 v85, 0xffff0000, v54
	v_pk_mul_f32 v[60:61], v[74:75], v[60:61]
	v_pk_mul_f32 v[78:79], v[84:85], v[82:83]
	v_pk_fma_f32 v[56:57], v[64:65], v[56:57], v[60:61]
	v_lshlrev_b32_e32 v62, 16, v24
	v_pk_fma_f32 v[56:57], v[78:79], v[72:73], v[56:57]
	v_and_b32_e32 v63, 0xffff0000, v24
	v_pk_add_f32 v[56:57], v[76:77], v[56:57]
	v_mov_b32_e32 v61, v58
	v_pk_mul_f32 v[56:57], v[56:57], v[62:63]
	v_mov_b32_e32 v63, v59
	v_mov_b32_e32 v62, v57
	v_mov_b32_e32 v60, v56
	v_pk_mul_f32 v[62:63], v[62:63], v[62:63]
	s_nop 0
	v_pk_fma_f32 v[60:61], v[60:61], v[60:61], v[62:63]
	s_nop 0
	v_add_f32_e32 v60, v60, v61
	s_nop 1
	v_mov_b32_dpp v61, v60 quad_perm:[1,0,3,2] row_mask:0xf bank_mask:0xf
	s_waitcnt lgkmcnt(0)
	v_add_f32_e32 v60, v60, v61
	s_nop 1
	v_mov_b32_dpp v61, v60 quad_perm:[2,3,0,1] row_mask:0xf bank_mask:0xf
	s_waitcnt lgkmcnt(0)
	v_add_f32_e32 v60, v60, v61
	s_nop 1
	v_mov_b32_dpp v61, v60 row_half_mirror row_mask:0xf bank_mask:0xf
	s_waitcnt lgkmcnt(0)
	v_add_f32_e32 v60, v60, v61
	s_nop 1
	v_mov_b32_dpp v61, v60 row_mirror row_mask:0xf bank_mask:0xf
	s_waitcnt lgkmcnt(0)
	v_add_f32_e32 v60, v60, v61
	v_mov_b32_e32 v61, v60
	s_nop 1
	v_permlane16_swap_b32_e32 v60, v61
	s_waitcnt lgkmcnt(0)
	v_add_f32_e32 v60, v60, v61
	v_mov_b32_e32 v61, v60
	s_nop 1
	v_permlane32_swap_b32_e32 v60, v61
	s_waitcnt lgkmcnt(0)
	v_add_f32_e32 v60, v60, v61
	v_fmamk_f32 v60, v60, 0x3b800000, v212
	v_cmp_gt_f32_e32 vcc, s12, v60
	v_mul_f32_e32 v61, 0x4f800000, v60
	s_nop 0
	v_cndmask_b32_e32 v60, v60, v61, vcc
	v_sqrt_f32_e32 v61, v60
	s_nop 0
	v_add_u32_e32 v62, -1, v61
	v_fma_f32 v63, -v62, v61, v60
	v_cmp_ge_f32_e64 s[0:1], 0, v63
	v_add_u32_e32 v63, 1, v61
	s_nop 0
	v_cndmask_b32_e64 v62, v61, v62, s[0:1]
	v_fma_f32 v61, -v63, v61, v60
	v_cmp_lt_f32_e64 s[0:1], 0, v61
	s_nop 1
	v_cndmask_b32_e64 v61, v62, v63, s[0:1]
	v_mul_f32_e32 v62, 0x37800000, v61
	v_cndmask_b32_e32 v61, v61, v62, vcc
	v_cmp_class_f32_e32 vcc, v60, v241
	s_nop 1
	v_cndmask_b32_e32 v60, v61, v60, vcc
	v_div_scale_f32 v61, s[0:1], v60, v60, 1.0
	v_rcp_f32_e32 v62, v61
	s_lshl_b64 s[0:1], s[36:37], 11
	s_add_u32 s0, s84, s0
	s_addc_u32 s1, s85, s1
	v_fma_f32 v63, -v61, v62, 1.0
	v_fmac_f32_e32 v62, v63, v62
	v_div_scale_f32 v63, vcc, 1.0, v60, 1.0
	v_mul_f32_e32 v64, v63, v62
	v_fma_f32 v65, -v61, v64, v63
	v_fmac_f32_e32 v64, v65, v62
	v_fma_f32 v61, -v61, v64, v63
	v_div_fmas_f32 v61, v61, v62, v64
	v_div_fixup_f32 v60, v61, v60, 1.0
	v_pk_mul_f32 v[56:57], v[56:57], v[60:61] op_sel_hi:[1,0]
	v_pk_mul_f32 v[58:59], v[58:59], v[60:61] op_sel_hi:[1,0]
	v_cvt_pk_bf16_f32 v56, v56, v57
	v_cvt_pk_bf16_f32 v57, v58, v59
	v_lshl_add_u64 v[58:59], s[0:1], 0, v[98:99]
	v_add_co_u32_e32 v58, vcc, 0x1b00000, v58
	s_nop 1
	v_addc_co_u32_e32 v59, vcc, 0, v59, vcc
	global_store_dwordx2 v[58:59], v[56:57], off offset:1536
	s_branch .LBB0_698

.LBB0_896:
	v_mov_b32_e32 v98, v0
	s_lshl_b32 s18, s18, 8
	s_add_i32 s18, s18, s10
	v_and_b32_e32 v147, 64, v1
	v_bfe_u32 v146, v98, 4, 2
	v_and_or_b32 v149, v98, 15, s18
	v_xor_b32_e32 v98, 16, v1
	v_add_u32_e32 v147, 64, v147
	v_cmp_lt_i32_e32 vcc, v98, v147
	s_lshl_b32 s17, s17, 8
	s_add_i32 s18, s17, 0x4000
	v_cndmask_b32_e32 v98, v1, v98, vcc
	v_lshlrev_b32_e32 v148, 2, v98
	v_xor_b32_e32 v98, 32, v1
	v_cmp_lt_i32_e32 vcc, v98, v147
	v_lshl_or_b32 v150, v146, 4, s14
	v_add_u32_e32 v151, s18, v149
	v_cndmask_b32_e32 v98, v1, v98, vcc
	v_pk_mul_f32 v[130:131], v[130:131], s[6:7] op_sel_hi:[1,0]
	v_pk_mul_f32 v[128:129], v[128:129], s[6:7] op_sel_hi:[1,0]
	v_pk_mul_f32 v[152:153], v[126:127], s[6:7] op_sel_hi:[1,0]
	v_pk_mul_f32 v[126:127], v[124:125], s[6:7] op_sel_hi:[1,0]
	v_pk_mul_f32 v[120:121], v[120:121], s[6:7] op_sel_hi:[1,0]
	v_lshlrev_b32_e32 v147, 2, v98
	v_lshl_or_b32 v98, v151, 11, v150
	v_cvt_pk_bf16_f32 v124, v128, v129
	v_cvt_pk_bf16_f32 v125, v130, v131
	v_cvt_pk_bf16_f32 v126, v126, v127
	v_cvt_pk_bf16_f32 v127, v152, v153
	v_pk_mul_f32 v[122:123], v[122:123], s[6:7] op_sel_hi:[1,0]
	v_pk_mul_f32 v[128:129], v[118:119], s[6:7] op_sel_hi:[1,0]
	v_pk_mul_f32 v[118:119], v[116:117], s[6:7] op_sel_hi:[1,0]
	v_cvt_pk_bf16_f32 v116, v120, v121
	global_store_dwordx4 v98, v[124:127], s[20:21]
	v_cvt_pk_bf16_f32 v117, v122, v123
	v_cvt_pk_bf16_f32 v118, v118, v119
	v_cvt_pk_bf16_f32 v119, v128, v129
	v_or_b32_e32 v98, 0x100, v98
	v_and_b32_e32 v123, 0xffff0000, v124
	v_and_b32_e32 v122, 0xffff0000, v116
	global_store_dwordx4 v98, v[116:119], s[20:21]
	v_lshlrev_b32_e32 v121, 16, v124
	v_lshlrev_b32_e32 v120, 16, v116
	v_lshlrev_b32_e32 v129, 16, v125
	v_lshlrev_b32_e32 v128, 16, v117
	v_and_b32_e32 v125, 0xffff0000, v125
	v_and_b32_e32 v124, 0xffff0000, v117
	v_lshlrev_b32_e32 v117, 16, v126
	v_lshlrev_b32_e32 v116, 16, v118
	v_and_b32_e32 v131, 0xffff0000, v126
	v_and_b32_e32 v130, 0xffff0000, v118
	v_lshlrev_b32_e32 v152, 16, v119
	v_and_b32_e32 v126, 0xffff0000, v119
	v_pk_mul_f32 v[118:119], v[122:123], v[122:123]
	v_lshlrev_b32_e32 v153, 16, v127
	v_pk_fma_f32 v[118:119], v[120:121], v[120:121], v[118:119]
	v_pk_mul_f32 v[120:121], v[124:125], v[124:125]
	v_and_b32_e32 v127, 0xffff0000, v127
	v_pk_fma_f32 v[120:121], v[128:129], v[128:129], v[120:121]
	v_cmp_eq_u32_e32 vcc, 0, v146
	v_pk_add_f32 v[118:119], v[118:119], v[120:121]
	v_pk_mul_f32 v[120:121], v[130:131], v[130:131]
	v_lshl_or_b32 v146, v146, 3, s11
	v_pk_fma_f32 v[116:117], v[116:117], v[116:117], v[120:121]
	v_pk_mul_f32 v[120:121], v[126:127], v[126:127]
	s_add_i32 s18, s17, 0x4010
	v_pk_fma_f32 v[120:121], v[152:153], v[152:153], v[120:121]
	v_pk_mul_f32 v[114:115], v[114:115], s[6:7] op_sel_hi:[1,0]
	v_pk_add_f32 v[116:117], v[116:117], v[120:121]
	v_pk_mul_f32 v[112:113], v[112:113], s[6:7] op_sel_hi:[1,0]
	v_pk_add_f32 v[116:117], v[116:117], v[118:119]
	v_add_u32_e32 v118, s18, v149
	v_add_f32_e32 v98, v116, v117
	v_mov_b32_e32 v116, v98
	s_nop 1
	v_permlane16_swap_b32_e32 v98, v116
	v_pk_mul_f32 v[104:105], v[104:105], s[6:7] op_sel_hi:[1,0]
	v_pk_mul_f32 v[106:107], v[106:107], s[6:7] op_sel_hi:[1,0]
	s_add_i32 s18, s17, 0x4020
	v_pk_mul_f32 v[94:95], v[94:95], s[6:7] op_sel_hi:[1,0]
	s_waitcnt lgkmcnt(0)
	v_add_f32_e32 v98, v98, v116
	v_mov_b32_e32 v116, v98
	s_nop 1
	v_permlane32_swap_b32_e32 v98, v116
	v_pk_mul_f32 v[86:87], v[86:87], s[6:7] op_sel_hi:[1,0]
	v_pk_mul_f32 v[96:97], v[96:97], s[6:7] op_sel_hi:[1,0]
	v_pk_mul_f32 v[88:89], v[88:89], s[6:7] op_sel_hi:[1,0]
	v_pk_mul_f32 v[78:79], v[78:79], s[6:7] op_sel_hi:[1,0]
	s_waitcnt lgkmcnt(0)
	v_add_f32_e32 v98, v98, v116
	v_cndmask_b32_e32 v98, 0, v98, vcc
	v_lshl_or_b32 v116, v151, 7, v146
	global_store_dwordx2 v116, v[98:99], s[24:25]
	v_pk_mul_f32 v[116:117], v[110:111], s[6:7] op_sel_hi:[1,0]
	v_pk_mul_f32 v[110:111], v[108:109], s[6:7] op_sel_hi:[1,0]
	v_lshl_or_b32 v98, v118, 11, v150
	v_cvt_pk_bf16_f32 v108, v112, v113
	v_cvt_pk_bf16_f32 v109, v114, v115
	v_cvt_pk_bf16_f32 v110, v110, v111
	v_cvt_pk_bf16_f32 v111, v116, v117
	v_pk_mul_f32 v[112:113], v[102:103], s[6:7] op_sel_hi:[1,0]
	v_pk_mul_f32 v[102:103], v[100:101], s[6:7] op_sel_hi:[1,0]
	v_cvt_pk_bf16_f32 v100, v104, v105
	global_store_dwordx4 v98, v[108:111], s[20:21]
	v_cvt_pk_bf16_f32 v101, v106, v107
	v_cvt_pk_bf16_f32 v102, v102, v103
	v_cvt_pk_bf16_f32 v103, v112, v113
	v_or_b32_e32 v98, 0x100, v98
	v_and_b32_e32 v107, 0xffff0000, v108
	v_and_b32_e32 v106, 0xffff0000, v100
	global_store_dwordx4 v98, v[100:103], s[20:21]
	v_lshlrev_b32_e32 v105, 16, v108
	v_lshlrev_b32_e32 v104, 16, v100
	v_lshlrev_b32_e32 v113, 16, v109
	v_lshlrev_b32_e32 v112, 16, v101
	v_and_b32_e32 v109, 0xffff0000, v109
	v_and_b32_e32 v108, 0xffff0000, v101
	v_lshlrev_b32_e32 v101, 16, v110
	v_lshlrev_b32_e32 v100, 16, v102
	v_and_b32_e32 v115, 0xffff0000, v110
	v_and_b32_e32 v114, 0xffff0000, v102
	v_lshlrev_b32_e32 v116, 16, v103
	v_and_b32_e32 v110, 0xffff0000, v103
	v_pk_mul_f32 v[102:103], v[106:107], v[106:107]
	v_lshlrev_b32_e32 v117, 16, v111
	v_pk_fma_f32 v[102:103], v[104:105], v[104:105], v[102:103]
	v_pk_mul_f32 v[104:105], v[108:109], v[108:109]
	v_and_b32_e32 v111, 0xffff0000, v111
	v_pk_fma_f32 v[104:105], v[112:113], v[112:113], v[104:105]
	v_pk_mul_f32 v[70:71], v[70:71], s[6:7] op_sel_hi:[1,0]
	v_pk_add_f32 v[102:103], v[102:103], v[104:105]
	v_pk_mul_f32 v[104:105], v[114:115], v[114:115]
	v_pk_mul_f32 v[80:81], v[80:81], s[6:7] op_sel_hi:[1,0]
	v_pk_fma_f32 v[100:101], v[100:101], v[100:101], v[104:105]
	v_pk_mul_f32 v[104:105], v[110:111], v[110:111]
	v_pk_mul_f32 v[72:73], v[72:73], s[6:7] op_sel_hi:[1,0]
	v_pk_fma_f32 v[104:105], v[116:117], v[116:117], v[104:105]
	v_pk_mul_f32 v[62:63], v[62:63], s[6:7] op_sel_hi:[1,0]
	v_pk_add_f32 v[100:101], v[100:101], v[104:105]
	v_pk_mul_f32 v[54:55], v[54:55], s[6:7] op_sel_hi:[1,0]
	v_pk_add_f32 v[100:101], v[100:101], v[102:103]
	v_add_u32_e32 v102, s18, v149
	v_add_f32_e32 v98, v100, v101
	v_mov_b32_e32 v100, v98
	s_nop 1
	v_permlane16_swap_b32_e32 v98, v100
	s_add_i32 s18, s17, 0x4030
	v_pk_mul_f32 v[64:65], v[64:65], s[6:7] op_sel_hi:[1,0]
	v_pk_mul_f32 v[56:57], v[56:57], s[6:7] op_sel_hi:[1,0]
	v_pk_mul_f32 v[46:47], v[46:47], s[6:7] op_sel_hi:[1,0]
	s_waitcnt lgkmcnt(0)
	v_add_f32_e32 v98, v98, v100
	v_mov_b32_e32 v100, v98
	s_nop 1
	v_permlane32_swap_b32_e32 v98, v100
	v_pk_mul_f32 v[38:39], v[38:39], s[6:7] op_sel_hi:[1,0]
	v_pk_mul_f32 v[48:49], v[48:49], s[6:7] op_sel_hi:[1,0]
	v_pk_mul_f32 v[40:41], v[40:41], s[6:7] op_sel_hi:[1,0]
	v_pk_mul_f32 v[30:31], v[30:31], s[6:7] op_sel_hi:[1,0]
	s_waitcnt lgkmcnt(0)
	v_add_f32_e32 v98, v98, v100
	v_cndmask_b32_e32 v98, 0, v98, vcc
	v_lshl_or_b32 v100, v118, 7, v146
	global_store_dwordx2 v100, v[98:99], s[24:25]
	v_lshl_or_b32 v98, v102, 11, v150
	v_pk_mul_f32 v[100:101], v[92:93], s[6:7] op_sel_hi:[1,0]
	v_pk_mul_f32 v[92:93], v[90:91], s[6:7] op_sel_hi:[1,0]
	v_cvt_pk_bf16_f32 v90, v94, v95
	v_pk_mul_f32 v[94:95], v[84:85], s[6:7] op_sel_hi:[1,0]
	v_pk_mul_f32 v[84:85], v[82:83], s[6:7] op_sel_hi:[1,0]
	v_cvt_pk_bf16_f32 v82, v86, v87
	v_cvt_pk_bf16_f32 v91, v96, v97
	v_cvt_pk_bf16_f32 v92, v92, v93
	v_cvt_pk_bf16_f32 v93, v100, v101
	v_cvt_pk_bf16_f32 v83, v88, v89
	v_cvt_pk_bf16_f32 v84, v84, v85
	v_cvt_pk_bf16_f32 v85, v94, v95
	v_or_b32_e32 v86, 0x100, v98
	v_and_b32_e32 v89, 0xffff0000, v90
	v_and_b32_e32 v88, 0xffff0000, v82
	global_store_dwordx4 v98, v[90:93], s[20:21]
	global_store_dwordx4 v86, v[82:85], s[20:21]
	v_lshlrev_b32_e32 v87, 16, v90
	v_lshlrev_b32_e32 v86, 16, v82
	v_lshlrev_b32_e32 v95, 16, v91
	v_lshlrev_b32_e32 v94, 16, v83
	v_and_b32_e32 v91, 0xffff0000, v91
	v_and_b32_e32 v90, 0xffff0000, v83
	v_lshlrev_b32_e32 v83, 16, v92
	v_lshlrev_b32_e32 v82, 16, v84
	v_and_b32_e32 v97, 0xffff0000, v92
	v_and_b32_e32 v96, 0xffff0000, v84
	v_lshlrev_b32_e32 v100, 16, v85
	v_and_b32_e32 v92, 0xffff0000, v85
	v_pk_mul_f32 v[84:85], v[88:89], v[88:89]
	v_lshlrev_b32_e32 v101, 16, v93
	v_pk_fma_f32 v[84:85], v[86:87], v[86:87], v[84:85]
	v_pk_mul_f32 v[86:87], v[90:91], v[90:91]
	v_and_b32_e32 v93, 0xffff0000, v93
	v_pk_fma_f32 v[86:87], v[94:95], v[94:95], v[86:87]
	v_pk_mul_f32 v[22:23], v[22:23], s[6:7] op_sel_hi:[1,0]
	v_pk_add_f32 v[84:85], v[84:85], v[86:87]
	v_pk_mul_f32 v[86:87], v[96:97], v[96:97]
	v_pk_mul_f32 v[32:33], v[32:33], s[6:7] op_sel_hi:[1,0]
	v_pk_fma_f32 v[82:83], v[82:83], v[82:83], v[86:87]
	v_pk_mul_f32 v[86:87], v[92:93], v[92:93]
	v_pk_mul_f32 v[24:25], v[24:25], s[6:7] op_sel_hi:[1,0]
	v_pk_fma_f32 v[86:87], v[100:101], v[100:101], v[86:87]
	v_pk_mul_f32 v[14:15], v[14:15], s[6:7] op_sel_hi:[1,0]
	v_pk_add_f32 v[82:83], v[82:83], v[86:87]
	v_pk_mul_f32 v[6:7], v[6:7], s[6:7] op_sel_hi:[1,0]
	v_pk_add_f32 v[82:83], v[82:83], v[84:85]
	v_add_u32_e32 v84, s18, v149
	v_add_f32_e32 v82, v82, v83
	v_mov_b32_e32 v83, v82
	s_nop 1
	v_permlane16_swap_b32_e32 v82, v83
	v_lshl_or_b32 v85, v84, 11, v150
	s_add_i32 s18, s17, 0x4080
	v_pk_mul_f32 v[16:17], v[16:17], s[6:7] op_sel_hi:[1,0]
	v_pk_mul_f32 v[8:9], v[8:9], s[6:7] op_sel_hi:[1,0]
	s_waitcnt lgkmcnt(0)
	v_add_f32_e32 v82, v82, v83
	v_mov_b32_e32 v83, v82
	s_nop 1
	v_permlane32_swap_b32_e32 v82, v83
	s_mov_b64 s[48:49], -1
	s_waitcnt lgkmcnt(0)
	v_add_f32_e32 v82, v82, v83
	v_cndmask_b32_e32 v98, 0, v82, vcc
	v_lshl_or_b32 v82, v102, 7, v146
	global_store_dwordx2 v82, v[98:99], s[24:25]
	v_pk_mul_f32 v[82:83], v[76:77], s[6:7] op_sel_hi:[1,0]
	v_pk_mul_f32 v[76:77], v[74:75], s[6:7] op_sel_hi:[1,0]
	v_cvt_pk_bf16_f32 v74, v78, v79
	v_pk_mul_f32 v[78:79], v[68:69], s[6:7] op_sel_hi:[1,0]
	v_pk_mul_f32 v[68:69], v[66:67], s[6:7] op_sel_hi:[1,0]
	v_cvt_pk_bf16_f32 v66, v70, v71
	v_cvt_pk_bf16_f32 v75, v80, v81
	v_cvt_pk_bf16_f32 v76, v76, v77
	v_cvt_pk_bf16_f32 v77, v82, v83
	v_cvt_pk_bf16_f32 v67, v72, v73
	v_cvt_pk_bf16_f32 v68, v68, v69
	v_cvt_pk_bf16_f32 v69, v78, v79
	v_or_b32_e32 v70, 0x100, v85
	v_and_b32_e32 v73, 0xffff0000, v74
	v_and_b32_e32 v72, 0xffff0000, v66
	global_store_dwordx4 v85, v[74:77], s[20:21]
	global_store_dwordx4 v70, v[66:69], s[20:21]
	v_lshlrev_b32_e32 v71, 16, v74
	v_lshlrev_b32_e32 v70, 16, v66
	v_lshlrev_b32_e32 v79, 16, v75
	v_lshlrev_b32_e32 v78, 16, v67
	v_and_b32_e32 v75, 0xffff0000, v75
	v_and_b32_e32 v74, 0xffff0000, v67
	v_lshlrev_b32_e32 v67, 16, v76
	v_lshlrev_b32_e32 v66, 16, v68
	v_and_b32_e32 v81, 0xffff0000, v76
	v_and_b32_e32 v80, 0xffff0000, v68
	v_lshlrev_b32_e32 v82, 16, v69
	v_and_b32_e32 v76, 0xffff0000, v69
	v_pk_mul_f32 v[68:69], v[72:73], v[72:73]
	v_lshlrev_b32_e32 v83, 16, v77
	v_pk_fma_f32 v[68:69], v[70:71], v[70:71], v[68:69]
	v_pk_mul_f32 v[70:71], v[74:75], v[74:75]
	v_and_b32_e32 v77, 0xffff0000, v77
	v_pk_fma_f32 v[70:71], v[78:79], v[78:79], v[70:71]
	s_nop 0
	v_pk_add_f32 v[68:69], v[68:69], v[70:71]
	v_pk_mul_f32 v[70:71], v[80:81], v[80:81]
	s_nop 0
	v_pk_fma_f32 v[66:67], v[66:67], v[66:67], v[70:71]
	v_pk_mul_f32 v[70:71], v[76:77], v[76:77]
	s_nop 0
	v_pk_fma_f32 v[70:71], v[82:83], v[82:83], v[70:71]
	s_nop 0
	v_pk_add_f32 v[66:67], v[66:67], v[70:71]
	s_nop 0
	v_pk_add_f32 v[66:67], v[66:67], v[68:69]
	v_add_u32_e32 v68, s18, v149
	v_add_f32_e32 v66, v66, v67
	v_mov_b32_e32 v67, v66
	s_nop 1
	v_permlane16_swap_b32_e32 v66, v67
	v_lshl_or_b32 v69, v68, 11, v150
	s_add_i32 s18, s17, 0x4090
	s_waitcnt lgkmcnt(0)
	v_add_f32_e32 v66, v66, v67
	v_mov_b32_e32 v67, v66
	s_nop 1
	v_permlane32_swap_b32_e32 v66, v67
	s_waitcnt lgkmcnt(0)
	v_add_f32_e32 v66, v66, v67
	v_cndmask_b32_e32 v98, 0, v66, vcc
	v_lshl_or_b32 v66, v84, 7, v146
	global_store_dwordx2 v66, v[98:99], s[24:25]
	v_pk_mul_f32 v[66:67], v[60:61], s[6:7] op_sel_hi:[1,0]
	v_pk_mul_f32 v[60:61], v[58:59], s[6:7] op_sel_hi:[1,0]
	v_cvt_pk_bf16_f32 v58, v62, v63
	v_pk_mul_f32 v[62:63], v[52:53], s[6:7] op_sel_hi:[1,0]
	v_pk_mul_f32 v[52:53], v[50:51], s[6:7] op_sel_hi:[1,0]
	v_cvt_pk_bf16_f32 v50, v54, v55
	v_cvt_pk_bf16_f32 v59, v64, v65
	v_cvt_pk_bf16_f32 v60, v60, v61
	v_cvt_pk_bf16_f32 v61, v66, v67
	v_cvt_pk_bf16_f32 v51, v56, v57
	v_cvt_pk_bf16_f32 v52, v52, v53
	v_cvt_pk_bf16_f32 v53, v62, v63
	v_or_b32_e32 v54, 0x100, v69
	v_and_b32_e32 v57, 0xffff0000, v58
	v_and_b32_e32 v56, 0xffff0000, v50
	global_store_dwordx4 v69, v[58:61], s[20:21]
	global_store_dwordx4 v54, v[50:53], s[20:21]
	v_lshlrev_b32_e32 v55, 16, v58
	v_lshlrev_b32_e32 v54, 16, v50
	v_lshlrev_b32_e32 v63, 16, v59
	v_lshlrev_b32_e32 v62, 16, v51
	v_and_b32_e32 v59, 0xffff0000, v59
	v_and_b32_e32 v58, 0xffff0000, v51
	v_lshlrev_b32_e32 v51, 16, v60
	v_lshlrev_b32_e32 v50, 16, v52
	v_and_b32_e32 v65, 0xffff0000, v60
	v_and_b32_e32 v64, 0xffff0000, v52
	v_lshlrev_b32_e32 v66, 16, v53
	v_and_b32_e32 v60, 0xffff0000, v53
	v_pk_mul_f32 v[52:53], v[56:57], v[56:57]
	v_lshlrev_b32_e32 v67, 16, v61
	v_pk_fma_f32 v[52:53], v[54:55], v[54:55], v[52:53]
	v_pk_mul_f32 v[54:55], v[58:59], v[58:59]
	v_and_b32_e32 v61, 0xffff0000, v61
	v_pk_fma_f32 v[54:55], v[62:63], v[62:63], v[54:55]
	s_nop 0
	v_pk_add_f32 v[52:53], v[52:53], v[54:55]
	v_pk_mul_f32 v[54:55], v[64:65], v[64:65]
	s_nop 0
	v_pk_fma_f32 v[50:51], v[50:51], v[50:51], v[54:55]
	v_pk_mul_f32 v[54:55], v[60:61], v[60:61]
	s_nop 0
	v_pk_fma_f32 v[54:55], v[66:67], v[66:67], v[54:55]
	s_nop 0
	v_pk_add_f32 v[50:51], v[50:51], v[54:55]
	s_nop 0
	v_pk_add_f32 v[50:51], v[50:51], v[52:53]
	v_add_u32_e32 v52, s18, v149
	v_add_f32_e32 v50, v50, v51
	v_mov_b32_e32 v51, v50
	s_nop 1
	v_permlane16_swap_b32_e32 v50, v51
	v_lshl_or_b32 v53, v52, 11, v150
	s_add_i32 s18, s17, 0x40a0
	s_addk_i32 s17, 0x40b0
	s_waitcnt lgkmcnt(0)
	v_add_f32_e32 v50, v50, v51
	v_mov_b32_e32 v51, v50
	s_nop 1
	v_permlane32_swap_b32_e32 v50, v51
	s_waitcnt lgkmcnt(0)
	v_add_f32_e32 v50, v50, v51
	v_cndmask_b32_e32 v98, 0, v50, vcc
	v_lshl_or_b32 v50, v68, 7, v146
	global_store_dwordx2 v50, v[98:99], s[24:25]
	v_pk_mul_f32 v[50:51], v[44:45], s[6:7] op_sel_hi:[1,0]
	v_pk_mul_f32 v[44:45], v[42:43], s[6:7] op_sel_hi:[1,0]
	v_cvt_pk_bf16_f32 v42, v46, v47
	v_pk_mul_f32 v[46:47], v[36:37], s[6:7] op_sel_hi:[1,0]
	v_pk_mul_f32 v[36:37], v[34:35], s[6:7] op_sel_hi:[1,0]
	v_cvt_pk_bf16_f32 v34, v38, v39
	v_cvt_pk_bf16_f32 v43, v48, v49
	v_cvt_pk_bf16_f32 v44, v44, v45
	v_cvt_pk_bf16_f32 v45, v50, v51
	v_cvt_pk_bf16_f32 v35, v40, v41
	v_cvt_pk_bf16_f32 v36, v36, v37
	v_cvt_pk_bf16_f32 v37, v46, v47
	v_or_b32_e32 v38, 0x100, v53
	v_and_b32_e32 v41, 0xffff0000, v42
	v_and_b32_e32 v40, 0xffff0000, v34
	global_store_dwordx4 v53, v[42:45], s[20:21]
	global_store_dwordx4 v38, v[34:37], s[20:21]
	v_lshlrev_b32_e32 v39, 16, v42
	v_lshlrev_b32_e32 v38, 16, v34
	v_lshlrev_b32_e32 v47, 16, v43
	v_lshlrev_b32_e32 v46, 16, v35
	v_and_b32_e32 v43, 0xffff0000, v43
	v_and_b32_e32 v42, 0xffff0000, v35
	v_lshlrev_b32_e32 v35, 16, v44
	v_lshlrev_b32_e32 v34, 16, v36
	v_and_b32_e32 v49, 0xffff0000, v44
	v_and_b32_e32 v48, 0xffff0000, v36
	v_lshlrev_b32_e32 v50, 16, v37
	v_and_b32_e32 v44, 0xffff0000, v37
	v_pk_mul_f32 v[36:37], v[40:41], v[40:41]
	v_lshlrev_b32_e32 v51, 16, v45
	v_pk_fma_f32 v[36:37], v[38:39], v[38:39], v[36:37]
	v_pk_mul_f32 v[38:39], v[42:43], v[42:43]
	v_and_b32_e32 v45, 0xffff0000, v45
	v_pk_fma_f32 v[38:39], v[46:47], v[46:47], v[38:39]
	s_nop 0
	v_pk_add_f32 v[36:37], v[36:37], v[38:39]
	v_pk_mul_f32 v[38:39], v[48:49], v[48:49]
	s_nop 0
	v_pk_fma_f32 v[34:35], v[34:35], v[34:35], v[38:39]
	v_pk_mul_f32 v[38:39], v[44:45], v[44:45]
	s_nop 0
	v_pk_fma_f32 v[38:39], v[50:51], v[50:51], v[38:39]
	s_nop 0
	v_pk_add_f32 v[34:35], v[34:35], v[38:39]
	s_nop 0
	v_pk_add_f32 v[34:35], v[34:35], v[36:37]
	v_add_u32_e32 v36, s18, v149
	v_add_f32_e32 v34, v34, v35
	v_mov_b32_e32 v35, v34
	s_nop 1
	v_permlane16_swap_b32_e32 v34, v35
	v_lshl_or_b32 v37, v36, 11, v150
	s_waitcnt lgkmcnt(0)
	v_add_f32_e32 v34, v34, v35
	v_mov_b32_e32 v35, v34
	s_nop 1
	v_permlane32_swap_b32_e32 v34, v35
	s_waitcnt lgkmcnt(0)
	v_add_f32_e32 v34, v34, v35
	v_cndmask_b32_e32 v98, 0, v34, vcc
	v_lshl_or_b32 v34, v52, 7, v146
	global_store_dwordx2 v34, v[98:99], s[24:25]
	v_pk_mul_f32 v[34:35], v[28:29], s[6:7] op_sel_hi:[1,0]
	v_pk_mul_f32 v[28:29], v[26:27], s[6:7] op_sel_hi:[1,0]
	v_cvt_pk_bf16_f32 v26, v30, v31
	v_pk_mul_f32 v[30:31], v[20:21], s[6:7] op_sel_hi:[1,0]
	v_pk_mul_f32 v[20:21], v[18:19], s[6:7] op_sel_hi:[1,0]
	v_cvt_pk_bf16_f32 v18, v22, v23
	v_cvt_pk_bf16_f32 v27, v32, v33
	v_cvt_pk_bf16_f32 v28, v28, v29
	v_cvt_pk_bf16_f32 v29, v34, v35
	v_cvt_pk_bf16_f32 v19, v24, v25
	v_cvt_pk_bf16_f32 v20, v20, v21
	v_cvt_pk_bf16_f32 v21, v30, v31
	v_or_b32_e32 v22, 0x100, v37
	v_and_b32_e32 v25, 0xffff0000, v26
	v_and_b32_e32 v24, 0xffff0000, v18
	global_store_dwordx4 v37, v[26:29], s[20:21]
	global_store_dwordx4 v22, v[18:21], s[20:21]
	v_lshlrev_b32_e32 v23, 16, v26
	v_lshlrev_b32_e32 v22, 16, v18
	v_lshlrev_b32_e32 v31, 16, v27
	v_lshlrev_b32_e32 v30, 16, v19
	v_and_b32_e32 v27, 0xffff0000, v27
	v_and_b32_e32 v26, 0xffff0000, v19
	v_lshlrev_b32_e32 v19, 16, v28
	v_lshlrev_b32_e32 v18, 16, v20
	v_and_b32_e32 v33, 0xffff0000, v28
	v_and_b32_e32 v32, 0xffff0000, v20
	v_lshlrev_b32_e32 v34, 16, v21
	v_and_b32_e32 v28, 0xffff0000, v21
	v_pk_mul_f32 v[20:21], v[24:25], v[24:25]
	v_lshlrev_b32_e32 v35, 16, v29
	v_pk_fma_f32 v[20:21], v[22:23], v[22:23], v[20:21]
	v_pk_mul_f32 v[22:23], v[26:27], v[26:27]
	v_and_b32_e32 v29, 0xffff0000, v29
	v_pk_fma_f32 v[22:23], v[30:31], v[30:31], v[22:23]
	s_nop 0
	v_pk_add_f32 v[20:21], v[20:21], v[22:23]
	v_pk_mul_f32 v[22:23], v[32:33], v[32:33]
	s_nop 0
	v_pk_fma_f32 v[18:19], v[18:19], v[18:19], v[22:23]
	v_pk_mul_f32 v[22:23], v[28:29], v[28:29]
	s_nop 0
	v_pk_fma_f32 v[22:23], v[34:35], v[34:35], v[22:23]
	s_nop 0
	v_pk_add_f32 v[18:19], v[18:19], v[22:23]
	s_nop 0
	v_pk_add_f32 v[18:19], v[18:19], v[20:21]
	v_add_u32_e32 v20, s17, v149
	v_add_f32_e32 v18, v18, v19
	v_mov_b32_e32 v19, v18
	s_nop 1
	v_permlane16_swap_b32_e32 v18, v19
	v_lshl_or_b32 v21, v20, 11, v150
	s_waitcnt lgkmcnt(0)
	v_add_f32_e32 v18, v18, v19
	v_mov_b32_e32 v19, v18
	s_nop 1
	v_permlane32_swap_b32_e32 v18, v19
	s_waitcnt lgkmcnt(0)
	v_add_f32_e32 v18, v18, v19
	v_cndmask_b32_e32 v98, 0, v18, vcc
	v_lshl_or_b32 v18, v36, 7, v146
	global_store_dwordx2 v18, v[98:99], s[24:25]
	v_pk_mul_f32 v[18:19], v[12:13], s[6:7] op_sel_hi:[1,0]
	v_pk_mul_f32 v[12:13], v[10:11], s[6:7] op_sel_hi:[1,0]
	v_cvt_pk_bf16_f32 v10, v14, v15
	v_pk_mul_f32 v[14:15], v[4:5], s[6:7] op_sel_hi:[1,0]
	v_pk_mul_f32 v[4:5], v[2:3], s[6:7] op_sel_hi:[1,0]
	v_cvt_pk_bf16_f32 v2, v6, v7
	v_cvt_pk_bf16_f32 v11, v16, v17
	v_cvt_pk_bf16_f32 v12, v12, v13
	v_cvt_pk_bf16_f32 v13, v18, v19
	v_cvt_pk_bf16_f32 v3, v8, v9
	v_cvt_pk_bf16_f32 v4, v4, v5
	v_cvt_pk_bf16_f32 v5, v14, v15
	v_or_b32_e32 v6, 0x100, v21
	v_and_b32_e32 v9, 0xffff0000, v10
	v_and_b32_e32 v8, 0xffff0000, v2
	global_store_dwordx4 v21, v[10:13], s[20:21]
	global_store_dwordx4 v6, v[2:5], s[20:21]
	v_lshlrev_b32_e32 v7, 16, v10
	v_lshlrev_b32_e32 v6, 16, v2
	v_lshlrev_b32_e32 v15, 16, v11
	v_lshlrev_b32_e32 v14, 16, v3
	v_and_b32_e32 v11, 0xffff0000, v11
	v_and_b32_e32 v10, 0xffff0000, v3
	v_lshlrev_b32_e32 v3, 16, v12
	v_lshlrev_b32_e32 v2, 16, v4
	v_and_b32_e32 v17, 0xffff0000, v12
	v_and_b32_e32 v16, 0xffff0000, v4
	v_lshlrev_b32_e32 v18, 16, v5
	v_and_b32_e32 v12, 0xffff0000, v5
	v_pk_mul_f32 v[4:5], v[8:9], v[8:9]
	v_lshlrev_b32_e32 v19, 16, v13
	v_pk_fma_f32 v[4:5], v[6:7], v[6:7], v[4:5]
	v_pk_mul_f32 v[6:7], v[10:11], v[10:11]
	v_and_b32_e32 v13, 0xffff0000, v13
	v_pk_fma_f32 v[6:7], v[14:15], v[14:15], v[6:7]
	s_nop 0
	v_pk_add_f32 v[4:5], v[4:5], v[6:7]
	v_pk_mul_f32 v[6:7], v[16:17], v[16:17]
	s_nop 0
	v_pk_fma_f32 v[2:3], v[2:3], v[2:3], v[6:7]
	v_pk_mul_f32 v[6:7], v[12:13], v[12:13]
	s_nop 0
	v_pk_fma_f32 v[6:7], v[18:19], v[18:19], v[6:7]
	s_nop 0
	v_pk_add_f32 v[2:3], v[2:3], v[6:7]
	s_nop 0
	v_pk_add_f32 v[2:3], v[2:3], v[4:5]
	s_nop 0
	v_add_f32_e32 v2, v2, v3
	v_mov_b32_e32 v3, v2
	s_nop 1
	v_permlane16_swap_b32_e32 v2, v3
	s_waitcnt lgkmcnt(0)
	v_add_f32_e32 v2, v2, v3
	v_mov_b32_e32 v3, v2
	s_nop 1
	v_permlane32_swap_b32_e32 v2, v3
	s_waitcnt lgkmcnt(0)
	v_add_f32_e32 v2, v2, v3
	v_cndmask_b32_e32 v98, 0, v2, vcc
	v_lshl_or_b32 v2, v20, 7, v146
	s_andn2_b64 vcc, exec, s[40:41]
	global_store_dwordx2 v2, v[98:99], s[24:25]
	s_cbranch_vccnz .LBB0_889
	s_andn2_b64 vcc, exec, s[0:1]
	s_cbranch_vccnz .LBB0_888
	s_barrier
	s_branch .LBB0_888

.LBB0_1061:
	s_andn2_b64 vcc, exec, s[22:23]
	s_cbranch_vccnz .LBB0_1099
	v_ashrrev_i32_e32 v3, 31, v14
	v_lshrrev_b32_e32 v3, 26, v3
	v_add_u32_e32 v3, v14, v3
	v_ashrrev_i32_e32 v10, 6, v3
	v_bfe_i32 v3, v14, 27, 1
	v_lshlrev_b32_e32 v2, 4, v14
	v_lshrrev_b32_e32 v3, 22, v3
	v_add_u32_e32 v3, v2, v3
	v_and_b32_e32 v3, 0xfffffc00, v3
	v_sub_u32_e32 v3, v2, v3
	v_lshrrev_b32_e32 v4, 4, v3
	v_bitop3_b32 v3, v4, v3, 32 bitop3:0x6c
	v_ashrrev_i32_e32 v5, 31, v3
	v_lshrrev_b32_e32 v5, 26, v5
	v_add_u32_e32 v5, v3, v5
	v_lshlrev_b32_e32 v4, 3, v10
	v_ashrrev_i32_e32 v11, 6, v5
	v_and_b32_e32 v5, 0xc0, v5
	v_and_b32_e32 v4, -16, v4
	v_sub_u32_e32 v3, v3, v5
	v_mov_b32_e32 v8, 1
	v_add_u32_e32 v4, v11, v4
	v_ashrrev_i16_sdwa v3, v8, sext(v3) dst_sel:DWORD dst_unused:UNUSED_PAD src0_sel:DWORD src1_sel:BYTE_0
	v_lshlrev_b32_e32 v6, 5, v10
	v_bfe_i32 v12, v3, 0, 16
	v_lshlrev_b32_e32 v3, 1, v4
	v_lshrrev_b32_e32 v5, 2, v4
	v_and_b32_e32 v7, 3, v11
	s_mov_b32 s4, 0x1fffe0
	v_and_b32_e32 v6, 32, v6
	v_and_b32_e32 v3, 24, v3
	v_and_b32_e32 v5, 4, v5
	v_and_or_b32 v7, v4, s4, v7
	v_or3_b32 v3, v7, v5, v3
	v_add_lshl_u32 v5, v6, v12, 1
	v_add_u32_e32 v2, 0x2000, v2
	v_lshl_add_u32 v176, v3, 11, v5
	v_ashrrev_i32_e32 v3, 31, v2
	v_lshrrev_b32_e32 v3, 22, v3
	v_add_u32_e32 v3, v2, v3
	v_ashrrev_i32_e32 v13, 10, v3
	v_mul_i32_i24_e32 v3, 0x400, v13
	v_sub_u32_e32 v2, v2, v3
	v_lshrrev_b32_e32 v3, 4, v2
	v_bitop3_b32 v2, v3, v2, 32 bitop3:0x6c
	v_lshl_add_u32 v174, v4, 11, v5
	v_ashrrev_i32_e32 v4, 31, v2
	v_lshrrev_b32_e32 v4, 26, v4
	v_lshlrev_b32_e32 v3, 3, v13
	v_add_u32_e32 v4, v2, v4
	v_and_b32_e32 v3, -16, v3
	v_ashrrev_i32_e32 v15, 6, v4
	s_ashr_i32 s18, s17, 6
	v_add_u32_e32 v3, v15, v3
	v_and_b32_e32 v6, 3, v15
	v_and_or_b32 v6, v3, s4, v6
	s_lshl_b32 s4, s18, 10
	s_lshl_b32 s7, s90, 21
	v_readlane_b32 s8, v252, 59
	s_add_u32 s7, s8, s7
	v_readlane_b32 s8, v252, 60
	v_and_b32_e32 v4, 0xc0, v4
	s_addc_u32 s8, s8, 0
	s_ashr_i32 s45, s44, 31
	v_sub_u32_e32 v2, v2, v4
	s_lshl_b64 s[10:11], s[44:45], 19
	v_ashrrev_i16_sdwa v2, v8, sext(v2) dst_sel:DWORD dst_unused:UNUSED_PAD src0_sel:DWORD src1_sel:BYTE_0
	s_add_u32 s58, s7, s10
	v_lshlrev_b32_e32 v5, 5, v13
	v_bfe_i32 v16, v2, 0, 16
	v_lshlrev_b32_e32 v2, 1, v3
	v_lshrrev_b32_e32 v4, 2, v3
	s_addc_u32 s59, s8, s11
	s_add_i32 s9, s4, 0
	v_and_b32_e32 v5, 32, v5
	v_and_b32_e32 v2, 24, v2
	v_and_b32_e32 v4, 4, v4
	s_add_i32 m0, s9, 0x10000
	v_or3_b32 v2, v6, v4, v2
	v_add_lshl_u32 v4, v5, v16, 1
	global_load_lds_dwordx4 v176, s[58:59]
	s_add_i32 m0, s9, 0x12000
	v_lshl_add_u32 v180, v2, 11, v4
	s_add_u32 s10, s58, 0x40000
	global_load_lds_dwordx4 v180, s[58:59]
	s_addc_u32 s11, s59, 0
	s_add_i32 m0, s9, 0x14000
	v_lshl_add_u32 v178, v3, 11, v4
	global_load_lds_dwordx4 v176, s[10:11]
	s_add_i32 m0, s9, 0x16000
	s_add_u32 s56, s20, s0
	global_load_lds_dwordx4 v180, s[10:11]
	s_addc_u32 s57, s21, s1
	s_add_i32 s10, s9, 0x2000
	s_mov_b32 m0, s9
	s_add_u32 s0, s56, 0x40000
	global_load_lds_dwordx4 v174, s[56:57]
	s_mov_b32 m0, s10
	s_addc_u32 s1, s57, 0
	s_add_i32 s11, s9, 0x4000
	global_load_lds_dwordx4 v178, s[56:57]
	s_mov_b32 m0, s11
	s_add_i32 s12, s9, 0x6000
	global_load_lds_dwordx4 v174, s[0:1]
	s_mov_b32 m0, s12
	v_mov_b32_e32 v3, v0
	global_load_lds_dwordx4 v178, s[0:1]
	v_readlane_b32 s0, v251, 58
	v_ashrrev_i32_e32 v2, 1, v3
	v_and_b32_e32 v8, 1, v3
	v_lshl_add_u32 v3, s33, 8, v2
	v_lshlrev_b32_e32 v4, 6, v8
	v_lshl_or_b32 v9, v3, 7, v4
	global_load_dwordx4 v[4:7], v9, s[24:25]
	global_load_dwordx4 v[18:21], v9, s[24:25] offset:16
	global_load_dwordx4 v[22:25], v9, s[24:25] offset:32
	global_load_dwordx4 v[26:29], v9, s[24:25] offset:48
	v_lshlrev_b32_e32 v3, 4, v3
	v_readlane_b32 s1, v251, 59
	s_nop 4
	global_load_dwordx4 v[30:33], v3, s[0:1]
	s_waitcnt vmcnt(0)
	v_add_f32_e32 v3, v4, v5
	v_add_f32_e32 v4, v6, v7
	v_add_f32_e32 v3, v3, v4
	v_add_f32_e32 v4, v18, v19
	v_add_f32_e32 v5, v20, v21
	v_add_f32_e32 v3, 0, v3
	v_add_f32_e32 v4, v4, v5
	v_add_f32_e32 v3, v3, v4
	v_add_f32_e32 v4, v22, v23
	v_add_f32_e32 v5, v24, v25
	v_add_f32_e32 v4, v4, v5
	v_add_f32_e32 v3, v3, v4
	v_add_f32_e32 v4, v26, v27
	v_add_f32_e32 v5, v28, v29
	v_add_f32_e32 v4, v4, v5
	v_add_f32_e32 v3, v3, v4
	v_add_f32_e32 v4, v30, v31
	v_add_f32_e32 v5, v32, v33
	v_and_b32_e32 v6, 64, v1
	v_add_f32_e32 v4, v4, v5
	v_xor_b32_e32 v5, 1, v1
	v_add_u32_e32 v17, 64, v6
	v_cmp_lt_i32_e32 vcc, v5, v17
	s_nop 1
	v_cndmask_b32_e32 v5, v1, v5, vcc
	v_cmp_eq_u32_e32 vcc, 0, v8
	v_lshlrev_b32_e32 v213, 2, v5
	v_mov_b32_dpp v5, v3 quad_perm:[1,0,3,2] row_mask:0xf bank_mask:0xf
	v_cndmask_b32_e32 v6, 0, v4, vcc
	s_nop 1
	v_mov_b32_dpp v6, v6 quad_perm:[1,0,3,2] row_mask:0xf bank_mask:0xf
	s_and_saveexec_b64 s[0:1], vcc
	s_cbranch_execz .LBB0_1064
	s_waitcnt lgkmcnt(0)
	v_add_f32_e32 v3, v3, v5
	v_fmamk_f32 v3, v3, 0x3b800000, v212
	v_rsq_f32_e32 v3, v3
	v_add_f32_e32 v4, v4, v6
	v_fmamk_f32 v4, v4, 0x3b000000, v212
	v_rsq_f32_e32 v4, v4
	v_rcp_f32_e32 v5, v3
	v_lshl_add_u32 v2, v2, 2, 0
	v_add_u32_e32 v2, 0x20400, v2
	v_mul_f32_e32 v5, v4, v5
	ds_write2st64_b32 v2, v5, v3 offset1:4
	ds_write_b32 v2, v4 offset:2048

.LBB0_1077:
	s_lshr_b32 s45, s33, 3
	s_cmp_lt_i32 s33, 64
	s_mulk_i32 s45, 0x1800
	s_cselect_b32 s58, s45, 0xc000
	s_ashr_i32 s59, s58, 31
	s_lshl_b32 s33, s33, 8
	s_add_i32 s33, s33, s13
	s_lshl_b64 s[56:57], s[58:59], 2
	s_add_u32 s45, s26, s56
	s_addc_u32 s49, s27, s57
	s_add_u32 s56, s45, 0x2000
	v_mov_b32_e32 v98, v0
	s_addc_u32 s57, s49, 0
	s_lshl_b32 s45, s44, 8
	s_or_b32 s45, s45, s14
	v_bfe_u32 v219, v98, 4, 2
	v_lshl_or_b32 v234, v219, 3, s45
	s_add_i32 s45, s58, 0x1000
	v_lshlrev_b32_e32 v158, 2, v234
	global_load_dwordx4 v[134:137], v158, s[56:57] offset:16
	global_load_dwordx4 v[138:141], v158, s[56:57]
	v_add_lshl_u32 v100, v234, s45, 2
	global_load_dwordx4 v[142:145], v158, s[36:37] offset:16
	global_load_dwordx4 v[146:149], v158, s[36:37]
	global_load_dwordx4 v[150:153], v100, s[26:27] offset:16
	global_load_dwordx4 v[154:157], v100, s[26:27]
	v_and_or_b32 v98, v98, 15, s33
	s_or_b32 s33, s58, 0x400
	v_add_lshl_u32 v162, v234, s33, 2
	v_lshlrev_b32_e32 v228, 1, v234
	v_lshlrev_b32_e32 v235, 11, v98
	v_add_u32_e32 v227, v228, v235
	v_or_b32_e32 v220, 16, v98
	v_lshlrev_b32_e32 v236, 11, v220
	v_add_u32_e32 v226, 0xb0, v98
	v_or_b32_e32 v221, 32, v98
	v_lshlrev_b32_e32 v237, 11, v226
	v_lshlrev_b32_e32 v229, 11, v221
	v_or_b32_e32 v222, 48, v98
	v_lshlrev_b32_e32 v230, 11, v222
	v_add_u32_e32 v223, 0x80, v98
	v_lshlrev_b32_e32 v231, 11, v223
	v_add_u32_e32 v224, 0x90, v98
	v_lshlrev_b32_e32 v232, 11, v224
	v_add_u32_e32 v225, 0xa0, v98
	v_lshlrev_b32_e32 v233, 11, v225
	v_cmp_eq_u32_e32 vcc, 0, v219
	s_waitcnt vmcnt(0)
	v_pk_add_f32 v[152:153], v[152:153], 1.0 op_sel_hi:[1,0]
	v_pk_add_f32 v[100:101], v[156:157], 1.0 op_sel_hi:[1,0]
	v_pk_add_f32 v[154:155], v[154:155], 1.0 op_sel_hi:[1,0]
	v_pk_mul_f32 v[100:101], v[148:149], v[100:101]
	v_pk_mul_f32 v[186:187], v[146:147], v[154:155]
	global_load_dwordx4 v[146:149], v158, s[22:23] offset:16
	global_load_dwordx4 v[154:157], v158, s[22:23]
	s_nop 0
	global_load_dwordx4 v[158:161], v162, s[26:27] offset:16
	s_nop 0
	global_load_dwordx4 v[162:165], v162, s[26:27]
	v_pk_add_f32 v[150:151], v[150:151], 1.0 op_sel_hi:[1,0]
	global_load_dwordx4 v[170:173], v227, s[96:97] nt
	v_pk_mul_f32 v[188:189], v[144:145], v[152:153]
	v_pk_mul_f32 v[190:191], v[142:143], v[150:151]
	s_waitcnt vmcnt(2)
	v_pk_add_f32 v[142:143], v[160:161], 1.0 op_sel_hi:[1,0]
	v_pk_add_f32 v[144:145], v[158:159], 1.0 op_sel_hi:[1,0]
	v_pk_mul_f32 v[196:197], v[148:149], v[142:143]
	v_pk_mul_f32 v[142:143], v[146:147], v[144:145]
	v_add_u32_e32 v146, v228, v237
	v_rcp_f32_e32 v198, v142
	v_add_u32_e32 v142, v228, v236
	global_load_dwordx4 v[166:169], v142, s[96:97] nt
	s_waitcnt vmcnt(2)
	v_pk_add_f32 v[164:165], v[164:165], 1.0 op_sel_hi:[1,0]
	v_pk_add_f32 v[162:163], v[162:163], 1.0 op_sel_hi:[1,0]
	global_load_dwordx4 v[146:149], v146, s[96:97] nt
	v_add_u32_e32 v142, v228, v229
	v_pk_mul_f32 v[156:157], v[156:157], v[164:165]
	v_pk_mul_f32 v[154:155], v[154:155], v[162:163]
	global_load_dwordx4 v[162:165], v142, s[96:97] nt
	v_add_u32_e32 v142, v228, v230
	global_load_dwordx4 v[158:161], v142, s[96:97] nt
	v_add_u32_e32 v142, v228, v231
	v_rcp_f32_e32 v194, v154
	v_rcp_f32_e32 v195, v155
	v_rcp_f32_e32 v192, v156
	v_rcp_f32_e32 v193, v157
	global_load_dwordx4 v[154:157], v142, s[96:97] nt
	v_add_u32_e32 v142, v228, v232
	global_load_dwordx4 v[150:153], v142, s[96:97] nt
	v_add_u32_e32 v142, v228, v233
	v_rcp_f32_e32 v199, v143
	global_load_dwordx4 v[142:145], v142, s[96:97] nt
	v_rcp_f32_e32 v196, v196
	v_rcp_f32_e32 v197, v197
	s_waitcnt vmcnt(7)
	v_lshlrev_b32_e32 v204, 16, v170
	v_and_b32_e32 v205, 0xffff0000, v170
	v_lshlrev_b32_e32 v170, 16, v171
	v_and_b32_e32 v171, 0xffff0000, v171
	v_lshlrev_b32_e32 v206, 16, v172
	v_and_b32_e32 v207, 0xffff0000, v172
	v_pk_mul_f32 v[204:205], v[194:195], v[204:205]
	v_pk_mul_f32 v[170:171], v[192:193], v[170:171]
	v_lshlrev_b32_e32 v172, 16, v173
	v_and_b32_e32 v173, 0xffff0000, v173
	v_pk_mul_f32 v[206:207], v[198:199], v[206:207]
	v_pk_fma_f32 v[132:133], v[132:133], v[140:141], v[170:171]
	v_pk_fma_f32 v[130:131], v[130:131], v[138:139], v[204:205]
	v_pk_mul_f32 v[172:173], v[196:197], v[172:173]
	v_pk_fma_f32 v[170:171], v[126:127], v[134:135], v[206:207]
	v_mul_f32_e32 v126, v131, v131
	v_mul_f32_e32 v127, v133, v133
	v_pk_fma_f32 v[128:129], v[128:129], v[136:137], v[172:173]
	v_fmac_f32_e32 v126, v130, v130
	v_fmac_f32_e32 v127, v132, v132
	v_add_f32_e32 v126, v126, v127
	v_mul_f32_e32 v127, v171, v171
	v_mul_f32_e32 v172, v129, v129
	v_fmac_f32_e32 v127, v170, v170
	v_fmac_f32_e32 v172, v128, v128
	v_add_f32_e32 v127, v127, v172
	v_pk_mul_f32 v[132:133], v[100:101], v[132:133]
	v_pk_mul_f32 v[130:131], v[186:187], v[130:131]
	v_pk_mul_f32 v[172:173], v[188:189], v[128:129]
	v_pk_mul_f32 v[170:171], v[190:191], v[170:171]
	v_add_f32_e32 v126, v126, v127
	v_cvt_pk_bf16_f32 v128, v130, v131
	v_cvt_pk_bf16_f32 v129, v132, v133
	v_cvt_pk_bf16_f32 v130, v170, v171
	v_cvt_pk_bf16_f32 v131, v172, v173
	global_store_dwordx4 v227, v[128:131], s[96:97]
	v_add_u32_e32 v127, 0x8000, v227
	s_waitcnt vmcnt(7)
	v_lshlrev_b32_e32 v132, 16, v168
	v_lshlrev_b32_e32 v128, 16, v166
	v_and_b32_e32 v129, 0xffff0000, v166
	v_lshlrev_b32_e32 v130, 16, v167
	v_and_b32_e32 v131, 0xffff0000, v167
	v_and_b32_e32 v133, 0xffff0000, v168
	v_pk_mul_f32 v[128:129], v[194:195], v[128:129]
	v_pk_mul_f32 v[130:131], v[192:193], v[130:131]
	v_lshlrev_b32_e32 v166, 16, v169
	v_and_b32_e32 v167, 0xffff0000, v169
	v_pk_mul_f32 v[132:133], v[198:199], v[132:133]
	v_pk_fma_f32 v[124:125], v[124:125], v[140:141], v[130:131]
	v_pk_fma_f32 v[122:123], v[122:123], v[138:139], v[128:129]
	v_pk_mul_f32 v[166:167], v[196:197], v[166:167]
	v_pk_fma_f32 v[128:129], v[118:119], v[134:135], v[132:133]
	v_mul_f32_e32 v118, v123, v123
	v_mul_f32_e32 v119, v125, v125
	v_pk_fma_f32 v[120:121], v[120:121], v[136:137], v[166:167]
	v_fmac_f32_e32 v118, v122, v122
	v_fmac_f32_e32 v119, v124, v124
	v_add_f32_e32 v118, v118, v119
	v_mul_f32_e32 v119, v129, v129
	v_mul_f32_e32 v130, v121, v121
	v_fmac_f32_e32 v119, v128, v128
	v_fmac_f32_e32 v130, v120, v120
	v_add_f32_e32 v119, v119, v130
	v_pk_mul_f32 v[124:125], v[100:101], v[124:125]
	v_pk_mul_f32 v[122:123], v[186:187], v[122:123]
	v_pk_mul_f32 v[130:131], v[188:189], v[120:121]
	v_pk_mul_f32 v[128:129], v[190:191], v[128:129]
	v_add_f32_e32 v118, v118, v119
	v_cvt_pk_bf16_f32 v120, v122, v123
	v_cvt_pk_bf16_f32 v121, v124, v125
	v_cvt_pk_bf16_f32 v122, v128, v129
	v_cvt_pk_bf16_f32 v123, v130, v131
	global_store_dwordx4 v127, v[120:123], s[96:97]
	s_waitcnt vmcnt(6)
	v_lshlrev_b32_e32 v128, 16, v165
	v_and_b32_e32 v129, 0xffff0000, v165
	v_lshlrev_b32_e32 v120, 16, v162
	v_and_b32_e32 v121, 0xffff0000, v162
	v_lshlrev_b32_e32 v122, 16, v163
	v_and_b32_e32 v123, 0xffff0000, v163
	v_pk_mul_f32 v[120:121], v[194:195], v[120:121]
	v_pk_mul_f32 v[122:123], v[192:193], v[122:123]
	v_lshlrev_b32_e32 v124, 16, v164
	v_and_b32_e32 v125, 0xffff0000, v164
	v_pk_mul_f32 v[128:129], v[196:197], v[128:129]
	v_pk_fma_f32 v[116:117], v[116:117], v[140:141], v[122:123]
	v_pk_fma_f32 v[114:115], v[114:115], v[138:139], v[120:121]
	v_pk_mul_f32 v[124:125], v[198:199], v[124:125]
	v_pk_fma_f32 v[120:121], v[112:113], v[136:137], v[128:129]
	v_mul_f32_e32 v112, v115, v115
	v_mul_f32_e32 v113, v117, v117
	v_pk_fma_f32 v[110:111], v[110:111], v[134:135], v[124:125]
	v_fmac_f32_e32 v112, v114, v114
	v_fmac_f32_e32 v113, v116, v116
	v_add_f32_e32 v112, v112, v113
	v_mul_f32_e32 v113, v111, v111
	v_mul_f32_e32 v122, v121, v121
	v_fmac_f32_e32 v113, v110, v110
	v_fmac_f32_e32 v122, v120, v120
	v_add_f32_e32 v113, v113, v122
	v_pk_mul_f32 v[116:117], v[100:101], v[116:117]
	v_pk_mul_f32 v[114:115], v[186:187], v[114:115]
	v_pk_mul_f32 v[120:121], v[188:189], v[120:121]
	v_pk_mul_f32 v[110:111], v[190:191], v[110:111]
	v_add_u32_e32 v119, 0x10000, v227
	v_add_f32_e32 v113, v112, v113
	v_cvt_pk_bf16_f32 v114, v114, v115
	v_cvt_pk_bf16_f32 v115, v116, v117
	v_cvt_pk_bf16_f32 v116, v110, v111
	v_cvt_pk_bf16_f32 v117, v120, v121
	global_store_dwordx4 v119, v[114:117], s[96:97]
	s_waitcnt vmcnt(6)
	v_lshlrev_b32_e32 v110, 16, v158
	v_and_b32_e32 v111, 0xffff0000, v158
	v_lshlrev_b32_e32 v114, 16, v159
	v_and_b32_e32 v115, 0xffff0000, v159
	v_pk_mul_f32 v[110:111], v[194:195], v[110:111]
	v_pk_mul_f32 v[114:115], v[192:193], v[114:115]
	v_lshlrev_b32_e32 v116, 16, v160
	v_and_b32_e32 v117, 0xffff0000, v160
	v_lshlrev_b32_e32 v120, 16, v161
	v_and_b32_e32 v121, 0xffff0000, v161
	v_pk_fma_f32 v[108:109], v[108:109], v[140:141], v[114:115]
	v_pk_fma_f32 v[106:107], v[106:107], v[138:139], v[110:111]
	v_pk_mul_f32 v[116:117], v[198:199], v[116:117]
	v_pk_mul_f32 v[120:121], v[196:197], v[120:121]
	v_mul_f32_e32 v110, v107, v107
	v_mul_f32_e32 v111, v109, v109
	v_pk_fma_f32 v[104:105], v[104:105], v[136:137], v[120:121]
	v_pk_fma_f32 v[102:103], v[102:103], v[134:135], v[116:117]
	v_fmac_f32_e32 v110, v106, v106
	v_fmac_f32_e32 v111, v108, v108
	v_add_f32_e32 v110, v110, v111
	v_mul_f32_e32 v111, v103, v103
	v_mul_f32_e32 v112, v105, v105
	v_fmac_f32_e32 v111, v102, v102
	v_fmac_f32_e32 v112, v104, v104
	v_add_f32_e32 v111, v111, v112
	v_add_f32_e32 v112, v110, v111
	v_pk_mul_f32 v[108:109], v[100:101], v[108:109]
	v_pk_mul_f32 v[106:107], v[186:187], v[106:107]
	v_pk_mul_f32 v[110:111], v[188:189], v[104:105]
	v_pk_mul_f32 v[104:105], v[190:191], v[102:103]
	v_add_u32_e32 v119, 0x18000, v227
	v_cvt_pk_bf16_f32 v102, v106, v107
	v_cvt_pk_bf16_f32 v103, v108, v109
	v_cvt_pk_bf16_f32 v104, v104, v105
	v_cvt_pk_bf16_f32 v105, v110, v111
	global_store_dwordx4 v119, v[102:105], s[96:97]
	s_waitcnt vmcnt(6)
	v_lshlrev_b32_e32 v106, 16, v156
	v_and_b32_e32 v107, 0xffff0000, v156
	v_lshlrev_b32_e32 v102, 16, v154
	v_and_b32_e32 v103, 0xffff0000, v154
	v_lshlrev_b32_e32 v104, 16, v155
	v_and_b32_e32 v105, 0xffff0000, v155
	v_pk_mul_f32 v[102:103], v[194:195], v[102:103]
	v_pk_mul_f32 v[104:105], v[192:193], v[104:105]
	v_lshlrev_b32_e32 v108, 16, v157
	v_and_b32_e32 v109, 0xffff0000, v157
	v_pk_fma_f32 v[96:97], v[96:97], v[140:141], v[104:105]
	v_pk_fma_f32 v[94:95], v[94:95], v[138:139], v[102:103]
	v_pk_mul_f32 v[106:107], v[198:199], v[106:107]
	v_pk_mul_f32 v[108:109], v[196:197], v[108:109]
	v_mul_f32_e32 v102, v95, v95
	v_mul_f32_e32 v103, v97, v97
	v_pk_fma_f32 v[92:93], v[92:93], v[136:137], v[108:109]
	v_pk_fma_f32 v[90:91], v[90:91], v[134:135], v[106:107]
	v_fmac_f32_e32 v102, v94, v94
	v_fmac_f32_e32 v103, v96, v96
	v_add_f32_e32 v102, v102, v103
	v_mul_f32_e32 v103, v91, v91
	v_mul_f32_e32 v104, v93, v93
	v_fmac_f32_e32 v103, v90, v90
	v_fmac_f32_e32 v104, v92, v92
	v_add_f32_e32 v103, v103, v104
	v_add_f32_e32 v111, v102, v103
	v_pk_mul_f32 v[96:97], v[100:101], v[96:97]
	v_pk_mul_f32 v[94:95], v[186:187], v[94:95]
	v_pk_mul_f32 v[102:103], v[188:189], v[92:93]
	v_pk_mul_f32 v[92:93], v[190:191], v[90:91]
	v_add_u32_e32 v110, 0x40000, v227
	v_cvt_pk_bf16_f32 v90, v94, v95
	v_cvt_pk_bf16_f32 v91, v96, v97
	v_cvt_pk_bf16_f32 v92, v92, v93
	v_cvt_pk_bf16_f32 v93, v102, v103
	global_store_dwordx4 v110, v[90:93], s[96:97]
	s_waitcnt vmcnt(6)
	v_lshlrev_b32_e32 v94, 16, v152
	v_and_b32_e32 v95, 0xffff0000, v152
	v_lshlrev_b32_e32 v90, 16, v150
	v_and_b32_e32 v91, 0xffff0000, v150
	v_lshlrev_b32_e32 v92, 16, v151
	v_and_b32_e32 v93, 0xffff0000, v151
	v_pk_mul_f32 v[90:91], v[194:195], v[90:91]
	v_pk_mul_f32 v[92:93], v[192:193], v[92:93]
	v_lshlrev_b32_e32 v96, 16, v153
	v_and_b32_e32 v97, 0xffff0000, v153
	v_pk_fma_f32 v[88:89], v[88:89], v[140:141], v[92:93]
	v_pk_fma_f32 v[86:87], v[86:87], v[138:139], v[90:91]
	v_pk_mul_f32 v[94:95], v[198:199], v[94:95]
	v_pk_mul_f32 v[96:97], v[196:197], v[96:97]
	v_mul_f32_e32 v90, v87, v87
	v_mul_f32_e32 v91, v89, v89
	v_pk_fma_f32 v[84:85], v[84:85], v[136:137], v[96:97]
	v_pk_fma_f32 v[82:83], v[82:83], v[134:135], v[94:95]
	v_fmac_f32_e32 v90, v86, v86
	v_fmac_f32_e32 v91, v88, v88
	v_add_f32_e32 v90, v90, v91
	v_mul_f32_e32 v91, v83, v83
	v_mul_f32_e32 v92, v85, v85
	v_fmac_f32_e32 v91, v82, v82
	v_fmac_f32_e32 v92, v84, v84
	v_add_f32_e32 v91, v91, v92
	v_add_f32_e32 v110, v90, v91
	v_pk_mul_f32 v[88:89], v[100:101], v[88:89]
	v_pk_mul_f32 v[86:87], v[186:187], v[86:87]
	v_pk_mul_f32 v[90:91], v[188:189], v[84:85]
	v_pk_mul_f32 v[84:85], v[190:191], v[82:83]
	v_add_u32_e32 v102, 0x48000, v227
	v_cvt_pk_bf16_f32 v82, v86, v87
	v_cvt_pk_bf16_f32 v83, v88, v89
	v_cvt_pk_bf16_f32 v84, v84, v85
	v_cvt_pk_bf16_f32 v85, v90, v91
	global_store_dwordx4 v102, v[82:85], s[96:97]
	s_waitcnt vmcnt(6)
	v_lshlrev_b32_e32 v86, 16, v144
	v_and_b32_e32 v87, 0xffff0000, v144
	v_lshlrev_b32_e32 v82, 16, v142
	v_and_b32_e32 v83, 0xffff0000, v142
	v_lshlrev_b32_e32 v84, 16, v143
	v_and_b32_e32 v85, 0xffff0000, v143
	v_pk_mul_f32 v[82:83], v[194:195], v[82:83]
	v_pk_mul_f32 v[84:85], v[192:193], v[84:85]
	v_lshlrev_b32_e32 v88, 16, v145
	v_and_b32_e32 v89, 0xffff0000, v145
	v_pk_fma_f32 v[80:81], v[80:81], v[140:141], v[84:85]
	v_pk_fma_f32 v[78:79], v[78:79], v[138:139], v[82:83]
	v_pk_mul_f32 v[86:87], v[198:199], v[86:87]
	v_pk_mul_f32 v[88:89], v[196:197], v[88:89]
	v_mul_f32_e32 v82, v79, v79
	v_mul_f32_e32 v83, v81, v81
	v_pk_fma_f32 v[76:77], v[76:77], v[136:137], v[88:89]
	v_pk_fma_f32 v[74:75], v[74:75], v[134:135], v[86:87]
	v_fmac_f32_e32 v82, v78, v78
	v_fmac_f32_e32 v83, v80, v80
	v_add_f32_e32 v82, v82, v83
	v_mul_f32_e32 v83, v75, v75
	v_mul_f32_e32 v84, v77, v77
	v_fmac_f32_e32 v83, v74, v74
	v_fmac_f32_e32 v84, v76, v76
	v_add_f32_e32 v83, v83, v84
	v_add_f32_e32 v109, v82, v83
	v_pk_mul_f32 v[80:81], v[100:101], v[80:81]
	v_pk_mul_f32 v[78:79], v[186:187], v[78:79]
	v_pk_mul_f32 v[82:83], v[188:189], v[76:77]
	v_pk_mul_f32 v[76:77], v[190:191], v[74:75]
	v_add_u32_e32 v90, 0x50000, v227
	v_cvt_pk_bf16_f32 v74, v78, v79
	v_cvt_pk_bf16_f32 v75, v80, v81
	v_cvt_pk_bf16_f32 v76, v76, v77
	v_cvt_pk_bf16_f32 v77, v82, v83
	global_store_dwordx4 v90, v[74:77], s[96:97]
	v_lshlrev_b32_e32 v78, 16, v148
	v_and_b32_e32 v79, 0xffff0000, v148
	v_lshlrev_b32_e32 v74, 16, v146
	v_and_b32_e32 v75, 0xffff0000, v146
	v_lshlrev_b32_e32 v76, 16, v147
	v_and_b32_e32 v77, 0xffff0000, v147
	v_pk_mul_f32 v[74:75], v[194:195], v[74:75]
	v_pk_mul_f32 v[76:77], v[192:193], v[76:77]
	v_lshlrev_b32_e32 v80, 16, v149
	v_and_b32_e32 v81, 0xffff0000, v149
	v_pk_fma_f32 v[72:73], v[72:73], v[140:141], v[76:77]
	v_pk_fma_f32 v[70:71], v[70:71], v[138:139], v[74:75]
	v_pk_mul_f32 v[78:79], v[198:199], v[78:79]
	v_pk_mul_f32 v[80:81], v[196:197], v[80:81]
	v_mul_f32_e32 v74, v71, v71
	v_mul_f32_e32 v75, v73, v73
	v_pk_fma_f32 v[68:69], v[68:69], v[136:137], v[80:81]
	v_pk_fma_f32 v[66:67], v[66:67], v[134:135], v[78:79]
	v_fmac_f32_e32 v74, v70, v70
	v_fmac_f32_e32 v75, v72, v72
	v_add_f32_e32 v74, v74, v75
	v_mul_f32_e32 v75, v67, v67
	v_mul_f32_e32 v76, v69, v69
	v_fmac_f32_e32 v75, v66, v66
	v_fmac_f32_e32 v76, v68, v68
	v_add_f32_e32 v75, v75, v76
	v_add_f32_e32 v108, v74, v75
	v_pk_mul_f32 v[72:73], v[100:101], v[72:73]
	v_pk_mul_f32 v[70:71], v[186:187], v[70:71]
	v_pk_mul_f32 v[74:75], v[188:189], v[68:69]
	v_pk_mul_f32 v[68:69], v[190:191], v[66:67]
	v_add_u32_e32 v82, 0x58000, v227
	v_cvt_pk_bf16_f32 v66, v70, v71
	v_cvt_pk_bf16_f32 v67, v72, v73
	v_cvt_pk_bf16_f32 v68, v68, v69
	v_cvt_pk_bf16_f32 v69, v74, v75
	global_store_dwordx4 v82, v[66:69], s[96:97]
	v_or_b32_e32 v94, 0x80, v234
	v_lshlrev_b32_e32 v95, 2, v94
	v_add_lshl_u32 v86, v94, s45, 2
	global_load_dwordx4 v[66:69], v95, s[56:57] offset:16
	global_load_dwordx4 v[70:73], v95, s[56:57]
	global_load_dwordx4 v[74:77], v95, s[36:37] offset:16
	global_load_dwordx4 v[78:81], v95, s[36:37]
	global_load_dwordx4 v[82:85], v86, s[26:27] offset:16
	s_nop 0
	global_load_dwordx4 v[86:89], v86, s[26:27]
	v_add_lshl_u32 v94, v94, s33, 2
	v_or_b32_e32 v119, 0x100, v227
	s_lshl_b32 s33, s44, 4
	s_or_b32 s33, s33, s17
	s_waitcnt vmcnt(1)
	v_pk_add_f32 v[84:85], v[84:85], 1.0 op_sel_hi:[1,0]
	s_waitcnt vmcnt(0)
	v_pk_add_f32 v[88:89], v[88:89], 1.0 op_sel_hi:[1,0]
	v_pk_add_f32 v[86:87], v[86:87], 1.0 op_sel_hi:[1,0]
	v_pk_mul_f32 v[90:91], v[80:81], v[88:89]
	v_pk_mul_f32 v[92:93], v[78:79], v[86:87]
	global_load_dwordx4 v[78:81], v95, s[22:23] offset:16
	global_load_dwordx4 v[86:89], v95, s[22:23]
	global_load_dwordx4 v[104:107], v94, s[26:27] offset:16
	s_nop 0
	global_load_dwordx4 v[94:97], v94, s[26:27]
	v_pk_add_f32 v[82:83], v[82:83], 1.0 op_sel_hi:[1,0]
	s_waitcnt vmcnt(0)
	v_pk_add_f32 v[96:97], v[96:97], 1.0 op_sel_hi:[1,0]
	v_pk_add_f32 v[94:95], v[94:95], 1.0 op_sel_hi:[1,0]
	v_pk_mul_f32 v[88:89], v[88:89], v[96:97]
	v_pk_mul_f32 v[86:87], v[86:87], v[94:95]
	v_pk_mul_f32 v[94:95], v[76:77], v[84:85]
	v_pk_mul_f32 v[96:97], v[74:75], v[82:83]
	v_pk_add_f32 v[74:75], v[106:107], 1.0 op_sel_hi:[1,0]
	v_pk_add_f32 v[76:77], v[104:105], 1.0 op_sel_hi:[1,0]
	v_pk_mul_f32 v[104:105], v[80:81], v[74:75]
	v_pk_mul_f32 v[74:75], v[78:79], v[76:77]
	v_rcp_f32_e32 v102, v86
	v_rcp_f32_e32 v106, v74
	v_or_b32_e32 v74, 0x100, v228
	v_rcp_f32_e32 v107, v75
	v_add_u32_e32 v75, v74, v235
	global_load_dwordx4 v[114:117], v75, s[96:97] nt
	v_add_u32_e32 v75, v74, v236
	global_load_dwordx4 v[120:123], v75, s[96:97] nt
	v_add_u32_e32 v75, v74, v229
	global_load_dwordx4 v[128:131], v75, s[96:97] nt
	v_add_u32_e32 v75, v74, v230
	global_load_dwordx4 v[132:135], v75, s[96:97] nt
	v_add_u32_e32 v75, v74, v231
	v_rcp_f32_e32 v103, v87
	v_rcp_f32_e32 v100, v88
	v_rcp_f32_e32 v101, v89
	global_load_dwordx4 v[86:89], v75, s[96:97] nt
	v_add_u32_e32 v75, v74, v232
	global_load_dwordx4 v[82:85], v75, s[96:97] nt
	v_add_u32_e32 v75, v74, v233
	global_load_dwordx4 v[78:81], v75, s[96:97] nt
	v_add_u32_e32 v74, v74, v237
	global_load_dwordx4 v[74:77], v74, s[96:97] nt
	v_rcp_f32_e32 v104, v104
	v_rcp_f32_e32 v105, v105
	s_waitcnt vmcnt(7)
	v_lshlrev_b32_e32 v124, 16, v114
	v_and_b32_e32 v125, 0xffff0000, v114
	v_lshlrev_b32_e32 v114, 16, v115
	v_and_b32_e32 v115, 0xffff0000, v115
	v_pk_mul_f32 v[124:125], v[102:103], v[124:125]
	v_pk_mul_f32 v[114:115], v[100:101], v[114:115]
	v_lshlrev_b32_e32 v136, 16, v116
	v_and_b32_e32 v137, 0xffff0000, v116
	v_lshlrev_b32_e32 v116, 16, v117
	v_and_b32_e32 v117, 0xffff0000, v117
	v_pk_fma_f32 v[64:65], v[64:65], v[72:73], v[114:115]
	v_pk_fma_f32 v[62:63], v[62:63], v[70:71], v[124:125]
	v_pk_mul_f32 v[136:137], v[106:107], v[136:137]
	v_pk_mul_f32 v[116:117], v[104:105], v[116:117]
	v_mul_f32_e32 v114, v63, v63
	v_mul_f32_e32 v115, v65, v65
	v_pk_fma_f32 v[60:61], v[60:61], v[68:69], v[116:117]
	v_pk_fma_f32 v[58:59], v[58:59], v[66:67], v[136:137]
	v_fmac_f32_e32 v114, v62, v62
	v_fmac_f32_e32 v115, v64, v64
	v_add_f32_e32 v114, v114, v115
	v_mul_f32_e32 v115, v59, v59
	v_mul_f32_e32 v116, v61, v61
	v_fmac_f32_e32 v115, v58, v58
	v_fmac_f32_e32 v116, v60, v60
	v_add_f32_e32 v115, v115, v116
	v_add_f32_e32 v114, v114, v115
	v_add_f32_e32 v116, v126, v114
	v_pk_mul_f32 v[64:65], v[90:91], v[64:65]
	v_pk_mul_f32 v[62:63], v[92:93], v[62:63]
	v_pk_mul_f32 v[114:115], v[94:95], v[60:61]
	v_pk_mul_f32 v[60:61], v[96:97], v[58:59]
	v_cvt_pk_bf16_f32 v58, v62, v63
	v_cvt_pk_bf16_f32 v59, v64, v65
	v_cvt_pk_bf16_f32 v60, v60, v61
	v_cvt_pk_bf16_f32 v61, v114, v115
	global_store_dwordx4 v119, v[58:61], s[96:97]
	s_waitcnt vmcnt(7)
	v_lshlrev_b32_e32 v62, 16, v122
	v_and_b32_e32 v63, 0xffff0000, v122
	v_lshlrev_b32_e32 v58, 16, v120
	v_and_b32_e32 v59, 0xffff0000, v120
	v_lshlrev_b32_e32 v60, 16, v121
	v_and_b32_e32 v61, 0xffff0000, v121
	v_pk_mul_f32 v[58:59], v[102:103], v[58:59]
	v_pk_mul_f32 v[60:61], v[100:101], v[60:61]
	v_lshlrev_b32_e32 v64, 16, v123
	v_and_b32_e32 v65, 0xffff0000, v123
	v_pk_mul_f32 v[62:63], v[106:107], v[62:63]
	v_pk_fma_f32 v[56:57], v[56:57], v[72:73], v[60:61]
	v_pk_fma_f32 v[54:55], v[54:55], v[70:71], v[58:59]
	v_pk_mul_f32 v[64:65], v[104:105], v[64:65]
	v_pk_fma_f32 v[58:59], v[50:51], v[66:67], v[62:63]
	v_mul_f32_e32 v50, v55, v55
	v_mul_f32_e32 v51, v57, v57
	v_pk_fma_f32 v[52:53], v[52:53], v[68:69], v[64:65]
	v_fmac_f32_e32 v50, v54, v54
	v_fmac_f32_e32 v51, v56, v56
	v_add_f32_e32 v50, v50, v51
	v_mul_f32_e32 v51, v59, v59
	v_mul_f32_e32 v60, v53, v53
	v_fmac_f32_e32 v51, v58, v58
	v_fmac_f32_e32 v60, v52, v52
	v_add_f32_e32 v51, v51, v60
	v_add_f32_e32 v50, v50, v51
	v_pk_mul_f32 v[56:57], v[90:91], v[56:57]
	v_pk_mul_f32 v[54:55], v[92:93], v[54:55]
	v_pk_mul_f32 v[60:61], v[94:95], v[52:53]
	v_pk_mul_f32 v[58:59], v[96:97], v[58:59]
	v_add_u32_e32 v114, 0x8100, v227
	v_add_f32_e32 v50, v118, v50
	v_cvt_pk_bf16_f32 v52, v54, v55
	v_cvt_pk_bf16_f32 v53, v56, v57
	v_cvt_pk_bf16_f32 v54, v58, v59
	v_cvt_pk_bf16_f32 v55, v60, v61
	global_store_dwordx4 v114, v[52:55], s[96:97]
	s_waitcnt vmcnt(7)
	v_lshlrev_b32_e32 v56, 16, v130
	v_and_b32_e32 v57, 0xffff0000, v130
	v_lshlrev_b32_e32 v52, 16, v128
	v_and_b32_e32 v53, 0xffff0000, v128
	v_lshlrev_b32_e32 v54, 16, v129
	v_and_b32_e32 v55, 0xffff0000, v129
	v_pk_mul_f32 v[52:53], v[102:103], v[52:53]
	v_pk_mul_f32 v[54:55], v[100:101], v[54:55]
	v_lshlrev_b32_e32 v58, 16, v131
	v_and_b32_e32 v59, 0xffff0000, v131
	v_pk_mul_f32 v[56:57], v[106:107], v[56:57]
	v_pk_fma_f32 v[48:49], v[48:49], v[72:73], v[54:55]
	v_pk_fma_f32 v[46:47], v[46:47], v[70:71], v[52:53]
	v_pk_mul_f32 v[58:59], v[104:105], v[58:59]
	v_pk_fma_f32 v[52:53], v[42:43], v[66:67], v[56:57]
	v_mul_f32_e32 v42, v47, v47
	v_mul_f32_e32 v43, v49, v49
	v_pk_fma_f32 v[44:45], v[44:45], v[68:69], v[58:59]
	v_fmac_f32_e32 v42, v46, v46
	v_fmac_f32_e32 v43, v48, v48
	v_add_f32_e32 v42, v42, v43
	v_mul_f32_e32 v43, v53, v53
	v_mul_f32_e32 v54, v45, v45
	v_fmac_f32_e32 v43, v52, v52
	v_fmac_f32_e32 v54, v44, v44
	v_add_f32_e32 v43, v43, v54
	v_add_f32_e32 v42, v42, v43
	v_pk_mul_f32 v[48:49], v[90:91], v[48:49]
	v_pk_mul_f32 v[46:47], v[92:93], v[46:47]
	v_pk_mul_f32 v[54:55], v[94:95], v[44:45]
	v_pk_mul_f32 v[52:53], v[96:97], v[52:53]
	v_add_u32_e32 v51, 0x10100, v227
	v_add_f32_e32 v42, v113, v42
	v_cvt_pk_bf16_f32 v44, v46, v47
	v_cvt_pk_bf16_f32 v45, v48, v49
	v_cvt_pk_bf16_f32 v46, v52, v53
	v_cvt_pk_bf16_f32 v47, v54, v55
	global_store_dwordx4 v51, v[44:47], s[96:97]
	s_waitcnt vmcnt(7)
	v_lshlrev_b32_e32 v48, 16, v134
	v_and_b32_e32 v49, 0xffff0000, v134
	v_lshlrev_b32_e32 v44, 16, v132
	v_and_b32_e32 v45, 0xffff0000, v132
	v_lshlrev_b32_e32 v46, 16, v133
	v_and_b32_e32 v47, 0xffff0000, v133
	v_pk_mul_f32 v[44:45], v[102:103], v[44:45]
	v_pk_mul_f32 v[46:47], v[100:101], v[46:47]
	v_lshlrev_b32_e32 v52, 16, v135
	v_and_b32_e32 v53, 0xffff0000, v135
	v_pk_mul_f32 v[48:49], v[106:107], v[48:49]
	v_pk_fma_f32 v[40:41], v[40:41], v[72:73], v[46:47]
	v_pk_fma_f32 v[38:39], v[38:39], v[70:71], v[44:45]
	v_pk_mul_f32 v[52:53], v[104:105], v[52:53]
	v_pk_fma_f32 v[44:45], v[34:35], v[66:67], v[48:49]
	v_mul_f32_e32 v34, v39, v39
	v_mul_f32_e32 v35, v41, v41
	v_pk_fma_f32 v[36:37], v[36:37], v[68:69], v[52:53]
	v_fmac_f32_e32 v34, v38, v38
	v_fmac_f32_e32 v35, v40, v40
	v_add_f32_e32 v34, v34, v35
	v_mul_f32_e32 v35, v45, v45
	v_mul_f32_e32 v46, v37, v37
	v_fmac_f32_e32 v35, v44, v44
	v_fmac_f32_e32 v46, v36, v36
	v_add_f32_e32 v35, v35, v46
	v_add_f32_e32 v34, v34, v35
	v_pk_mul_f32 v[40:41], v[90:91], v[40:41]
	v_pk_mul_f32 v[38:39], v[92:93], v[38:39]
	v_pk_mul_f32 v[46:47], v[94:95], v[36:37]
	v_pk_mul_f32 v[44:45], v[96:97], v[44:45]
	v_add_u32_e32 v43, 0x18100, v227
	v_add_f32_e32 v34, v112, v34
	v_cvt_pk_bf16_f32 v36, v38, v39
	v_cvt_pk_bf16_f32 v37, v40, v41
	v_cvt_pk_bf16_f32 v38, v44, v45
	v_cvt_pk_bf16_f32 v39, v46, v47
	global_store_dwordx4 v43, v[36:39], s[96:97]
	s_waitcnt vmcnt(7)
	v_lshlrev_b32_e32 v40, 16, v88
	v_and_b32_e32 v41, 0xffff0000, v88
	v_lshlrev_b32_e32 v36, 16, v86
	v_and_b32_e32 v37, 0xffff0000, v86
	v_lshlrev_b32_e32 v38, 16, v87
	v_and_b32_e32 v39, 0xffff0000, v87
	v_pk_mul_f32 v[36:37], v[102:103], v[36:37]
	v_pk_mul_f32 v[38:39], v[100:101], v[38:39]
	v_lshlrev_b32_e32 v44, 16, v89
	v_and_b32_e32 v45, 0xffff0000, v89
	v_pk_mul_f32 v[40:41], v[106:107], v[40:41]
	v_pk_fma_f32 v[32:33], v[32:33], v[72:73], v[38:39]
	v_pk_fma_f32 v[30:31], v[30:31], v[70:71], v[36:37]
	v_pk_mul_f32 v[44:45], v[104:105], v[44:45]
	v_pk_fma_f32 v[36:37], v[26:27], v[66:67], v[40:41]
	v_mul_f32_e32 v26, v31, v31
	v_mul_f32_e32 v27, v33, v33
	v_pk_fma_f32 v[28:29], v[28:29], v[68:69], v[44:45]
	v_fmac_f32_e32 v26, v30, v30
	v_fmac_f32_e32 v27, v32, v32
	v_add_f32_e32 v26, v26, v27
	v_mul_f32_e32 v27, v37, v37
	v_mul_f32_e32 v38, v29, v29
	v_fmac_f32_e32 v27, v36, v36
	v_fmac_f32_e32 v38, v28, v28
	v_add_f32_e32 v27, v27, v38
	v_add_f32_e32 v26, v26, v27
	v_pk_mul_f32 v[32:33], v[90:91], v[32:33]
	v_pk_mul_f32 v[30:31], v[92:93], v[30:31]
	v_pk_mul_f32 v[38:39], v[94:95], v[28:29]
	v_pk_mul_f32 v[36:37], v[96:97], v[36:37]
	v_add_u32_e32 v35, 0x40100, v227
	v_add_f32_e32 v26, v111, v26
	v_cvt_pk_bf16_f32 v28, v30, v31
	v_cvt_pk_bf16_f32 v29, v32, v33
	v_cvt_pk_bf16_f32 v30, v36, v37
	v_cvt_pk_bf16_f32 v31, v38, v39
	global_store_dwordx4 v35, v[28:31], s[96:97]
	s_waitcnt vmcnt(7)
	v_lshlrev_b32_e32 v32, 16, v84
	v_and_b32_e32 v33, 0xffff0000, v84
	v_lshlrev_b32_e32 v28, 16, v82
	v_and_b32_e32 v29, 0xffff0000, v82
	v_lshlrev_b32_e32 v30, 16, v83
	v_and_b32_e32 v31, 0xffff0000, v83
	v_pk_mul_f32 v[28:29], v[102:103], v[28:29]
	v_pk_mul_f32 v[30:31], v[100:101], v[30:31]
	v_lshlrev_b32_e32 v36, 16, v85
	v_and_b32_e32 v37, 0xffff0000, v85
	v_pk_mul_f32 v[32:33], v[106:107], v[32:33]
	v_pk_fma_f32 v[24:25], v[24:25], v[72:73], v[30:31]
	v_pk_fma_f32 v[22:23], v[22:23], v[70:71], v[28:29]
	v_pk_mul_f32 v[36:37], v[104:105], v[36:37]
	v_pk_fma_f32 v[28:29], v[18:19], v[66:67], v[32:33]
	v_mul_f32_e32 v18, v23, v23
	v_mul_f32_e32 v19, v25, v25
	v_pk_fma_f32 v[20:21], v[20:21], v[68:69], v[36:37]
	v_fmac_f32_e32 v18, v22, v22
	v_fmac_f32_e32 v19, v24, v24
	v_add_f32_e32 v18, v18, v19
	v_mul_f32_e32 v19, v29, v29
	v_mul_f32_e32 v30, v21, v21
	v_fmac_f32_e32 v19, v28, v28
	v_fmac_f32_e32 v30, v20, v20
	v_add_f32_e32 v19, v19, v30
	v_add_f32_e32 v18, v18, v19
	v_pk_mul_f32 v[24:25], v[90:91], v[24:25]
	v_pk_mul_f32 v[22:23], v[92:93], v[22:23]
	v_pk_mul_f32 v[30:31], v[94:95], v[20:21]
	v_pk_mul_f32 v[28:29], v[96:97], v[28:29]
	v_add_u32_e32 v27, 0x48100, v227
	v_add_f32_e32 v18, v110, v18
	v_cvt_pk_bf16_f32 v20, v22, v23
	v_cvt_pk_bf16_f32 v21, v24, v25
	v_cvt_pk_bf16_f32 v22, v28, v29
	v_cvt_pk_bf16_f32 v23, v30, v31
	global_store_dwordx4 v27, v[20:23], s[96:97]
	s_waitcnt vmcnt(7)
	v_lshlrev_b32_e32 v24, 16, v80
	v_and_b32_e32 v25, 0xffff0000, v80
	v_lshlrev_b32_e32 v20, 16, v78
	v_and_b32_e32 v21, 0xffff0000, v78
	v_lshlrev_b32_e32 v22, 16, v79
	v_and_b32_e32 v23, 0xffff0000, v79
	v_pk_mul_f32 v[20:21], v[102:103], v[20:21]
	v_pk_mul_f32 v[22:23], v[100:101], v[22:23]
	v_lshlrev_b32_e32 v28, 16, v81
	v_and_b32_e32 v29, 0xffff0000, v81
	v_pk_mul_f32 v[24:25], v[106:107], v[24:25]
	v_pk_fma_f32 v[16:17], v[16:17], v[72:73], v[22:23]
	v_pk_fma_f32 v[14:15], v[14:15], v[70:71], v[20:21]
	v_pk_mul_f32 v[28:29], v[104:105], v[28:29]
	v_pk_fma_f32 v[20:21], v[10:11], v[66:67], v[24:25]
	v_mul_f32_e32 v10, v15, v15
	v_mul_f32_e32 v11, v17, v17
	v_pk_fma_f32 v[12:13], v[12:13], v[68:69], v[28:29]
	v_fmac_f32_e32 v10, v14, v14
	v_fmac_f32_e32 v11, v16, v16
	v_add_f32_e32 v10, v10, v11
	v_mul_f32_e32 v11, v21, v21
	v_mul_f32_e32 v22, v13, v13
	v_fmac_f32_e32 v11, v20, v20
	v_fmac_f32_e32 v22, v12, v12
	v_add_f32_e32 v11, v11, v22
	v_add_f32_e32 v10, v10, v11
	v_pk_mul_f32 v[16:17], v[90:91], v[16:17]
	v_pk_mul_f32 v[14:15], v[92:93], v[14:15]
	v_pk_mul_f32 v[22:23], v[94:95], v[12:13]
	v_pk_mul_f32 v[20:21], v[96:97], v[20:21]
	v_add_u32_e32 v19, 0x50100, v227
	v_add_f32_e32 v10, v109, v10
	v_cvt_pk_bf16_f32 v12, v14, v15
	v_cvt_pk_bf16_f32 v13, v16, v17
	v_cvt_pk_bf16_f32 v14, v20, v21
	v_cvt_pk_bf16_f32 v15, v22, v23
	global_store_dwordx4 v19, v[12:15], s[96:97]
	s_waitcnt vmcnt(7)
	v_lshlrev_b32_e32 v16, 16, v76
	v_and_b32_e32 v17, 0xffff0000, v76
	v_lshlrev_b32_e32 v12, 16, v74
	v_and_b32_e32 v13, 0xffff0000, v74
	v_lshlrev_b32_e32 v14, 16, v75
	v_and_b32_e32 v15, 0xffff0000, v75
	v_pk_mul_f32 v[12:13], v[102:103], v[12:13]
	v_pk_mul_f32 v[14:15], v[100:101], v[14:15]
	v_lshlrev_b32_e32 v20, 16, v77
	v_and_b32_e32 v21, 0xffff0000, v77
	v_pk_mul_f32 v[16:17], v[106:107], v[16:17]
	v_pk_fma_f32 v[8:9], v[8:9], v[72:73], v[14:15]
	v_pk_fma_f32 v[6:7], v[6:7], v[70:71], v[12:13]
	v_pk_mul_f32 v[20:21], v[104:105], v[20:21]
	v_pk_fma_f32 v[12:13], v[2:3], v[66:67], v[16:17]
	v_mul_f32_e32 v2, v7, v7
	v_mul_f32_e32 v3, v9, v9
	v_pk_fma_f32 v[4:5], v[4:5], v[68:69], v[20:21]
	v_fmac_f32_e32 v2, v6, v6
	v_fmac_f32_e32 v3, v8, v8
	v_add_f32_e32 v2, v2, v3
	v_mul_f32_e32 v3, v13, v13
	v_mul_f32_e32 v14, v5, v5
	v_fmac_f32_e32 v3, v12, v12
	v_fmac_f32_e32 v14, v4, v4
	v_add_f32_e32 v3, v3, v14
	v_add_f32_e32 v2, v2, v3
	v_mov_b32_e32 v3, v116
	s_nop 1
	v_permlane16_swap_b32_e32 v116, v3
	v_pk_mul_f32 v[8:9], v[90:91], v[8:9]
	v_pk_mul_f32 v[6:7], v[92:93], v[6:7]
	v_pk_mul_f32 v[14:15], v[94:95], v[4:5]
	v_pk_mul_f32 v[12:13], v[96:97], v[12:13]
	v_add_u32_e32 v11, 0x58100, v227
	v_add_f32_e32 v2, v108, v2
	v_cvt_pk_bf16_f32 v4, v6, v7
	v_cvt_pk_bf16_f32 v5, v8, v9
	v_cvt_pk_bf16_f32 v6, v12, v13
	v_cvt_pk_bf16_f32 v7, v14, v15
	s_waitcnt lgkmcnt(0)
	v_add_f32_e32 v3, v116, v3
	global_store_dwordx4 v11, v[4:7], s[96:97]
	s_nop 1
	v_mov_b32_e32 v4, v3
	s_nop 1
	v_permlane32_swap_b32_e32 v3, v4
	s_and_saveexec_b64 s[44:45], vcc
	v_readlane_b32 s66, v254, 46
	s_cbranch_execz .LBB0_1079
	v_readlane_b32 s56, v251, 32
	s_waitcnt lgkmcnt(0)
	v_add_f32_e32 v3, v3, v4
	v_lshl_add_u32 v4, v98, 6, s33
	v_readlane_b32 s57, v251, 33
	s_nop 4
	global_store_dword v4, v3, s[56:57]
.LBB0_1079:
	s_or_b64 exec, exec, s[44:45]
	v_mov_b32_e32 v3, v50
	s_nop 1
	v_permlane16_swap_b32_e32 v50, v3
	s_waitcnt lgkmcnt(0)
	v_add_f32_e32 v3, v50, v3
	v_mov_b32_e32 v4, v3
	s_nop 1
	v_permlane32_swap_b32_e32 v3, v4
	s_and_saveexec_b64 s[44:45], vcc
	s_cbranch_execz .LBB0_1081
	v_readlane_b32 s56, v251, 32
	s_waitcnt lgkmcnt(0)
	v_add_f32_e32 v3, v3, v4
	v_lshl_add_u32 v4, v220, 6, s33
	v_readlane_b32 s57, v251, 33
	s_nop 4
	global_store_dword v4, v3, s[56:57]
.LBB0_1081:
	s_or_b64 exec, exec, s[44:45]
	v_mov_b32_e32 v3, v42
	s_nop 1
	v_permlane16_swap_b32_e32 v42, v3
	s_waitcnt lgkmcnt(0)
	v_add_f32_e32 v3, v42, v3
	v_mov_b32_e32 v4, v3
	s_nop 1
	v_permlane32_swap_b32_e32 v3, v4
	s_and_saveexec_b64 s[44:45], vcc
	s_cbranch_execz .LBB0_1083
	v_readlane_b32 s56, v251, 32
	s_waitcnt lgkmcnt(0)
	v_add_f32_e32 v3, v3, v4
	v_lshl_add_u32 v4, v221, 6, s33
	v_readlane_b32 s57, v251, 33
	s_nop 4
	global_store_dword v4, v3, s[56:57]
.LBB0_1083:
	s_or_b64 exec, exec, s[44:45]
	v_mov_b32_e32 v3, v34
	s_nop 1
	v_permlane16_swap_b32_e32 v34, v3
	s_waitcnt lgkmcnt(0)
	v_add_f32_e32 v3, v34, v3
	v_mov_b32_e32 v4, v3
	s_nop 1
	v_permlane32_swap_b32_e32 v3, v4
	s_and_saveexec_b64 s[44:45], vcc
	s_cbranch_execz .LBB0_1085
	v_readlane_b32 s56, v251, 32
	s_waitcnt lgkmcnt(0)
	v_add_f32_e32 v3, v3, v4
	v_lshl_add_u32 v4, v222, 6, s33
	v_readlane_b32 s57, v251, 33
	s_nop 4
	global_store_dword v4, v3, s[56:57]
.LBB0_1085:
	s_or_b64 exec, exec, s[44:45]
	v_mov_b32_e32 v3, v26
	s_nop 1
	v_permlane16_swap_b32_e32 v26, v3
	s_waitcnt lgkmcnt(0)
	v_add_f32_e32 v3, v26, v3
	v_mov_b32_e32 v4, v3
	s_nop 1
	v_permlane32_swap_b32_e32 v3, v4
	s_and_saveexec_b64 s[44:45], vcc
	s_cbranch_execz .LBB0_1087
	v_readlane_b32 s56, v251, 32
	s_waitcnt lgkmcnt(0)
	v_add_f32_e32 v3, v3, v4
	v_lshl_add_u32 v4, v223, 6, s33
	v_readlane_b32 s57, v251, 33
	s_nop 4
	global_store_dword v4, v3, s[56:57]
.LBB0_1087:
	s_or_b64 exec, exec, s[44:45]
	v_mov_b32_e32 v3, v18
	s_nop 1
	v_permlane16_swap_b32_e32 v18, v3
	s_waitcnt lgkmcnt(0)
	v_add_f32_e32 v3, v18, v3
	v_mov_b32_e32 v4, v3
	s_nop 1
	v_permlane32_swap_b32_e32 v3, v4
	s_and_saveexec_b64 s[44:45], vcc
	s_cbranch_execz .LBB0_1089
	v_readlane_b32 s56, v251, 32
	s_waitcnt lgkmcnt(0)
	v_add_f32_e32 v3, v3, v4
	v_lshl_add_u32 v4, v224, 6, s33
	v_readlane_b32 s57, v251, 33
	s_nop 4
	global_store_dword v4, v3, s[56:57]
.LBB0_1089:
	s_or_b64 exec, exec, s[44:45]
	v_mov_b32_e32 v3, v10
	s_nop 1
	v_permlane16_swap_b32_e32 v10, v3
	s_waitcnt lgkmcnt(0)
	v_add_f32_e32 v3, v10, v3
	v_mov_b32_e32 v4, v3
	s_nop 1
	v_permlane32_swap_b32_e32 v3, v4
	s_and_saveexec_b64 s[44:45], vcc
	s_cbranch_execz .LBB0_1091
	v_readlane_b32 s56, v251, 32
	s_waitcnt lgkmcnt(0)
	v_add_f32_e32 v3, v3, v4
	v_lshl_add_u32 v4, v225, 6, s33
	v_readlane_b32 s57, v251, 33
	s_nop 4
	global_store_dword v4, v3, s[56:57]
.LBB0_1091:
	s_or_b64 exec, exec, s[44:45]
	v_mov_b32_e32 v3, v2
	s_nop 1
	v_permlane16_swap_b32_e32 v2, v3
	s_waitcnt lgkmcnt(0)
	v_add_f32_e32 v2, v2, v3
	v_mov_b32_e32 v3, v2
	s_nop 1
	v_permlane32_swap_b32_e32 v2, v3
	s_and_saveexec_b64 s[44:45], vcc
	s_cbranch_execz .LBB0_1093
	v_readlane_b32 s56, v251, 32
	s_waitcnt lgkmcnt(0)
	v_add_f32_e32 v2, v2, v3
	v_lshl_add_u32 v3, v226, 6, s33
	v_readlane_b32 s57, v251, 33
	s_nop 4
	global_store_dword v3, v2, s[56:57]
.LBB0_1093:
	s_or_b64 exec, exec, s[44:45]
	s_waitcnt lgkmcnt(0)
	s_barrier
	s_andn2_b64 vcc, exec, s[38:39]
	s_mov_b64 s[38:39], -1
	s_cbranch_vccnz .LBB0_1068
	s_waitcnt lgkmcnt(0)
	v_mov_b32_e32 v3, v0
	v_readlane_b32 s38, v251, 58
	v_ashrrev_i32_e32 v2, 1, v3
	v_and_b32_e32 v20, 1, v3
	v_lshl_add_u32 v21, s19, 8, v2
	v_lshlrev_b32_e32 v3, 6, v20
	v_lshl_or_b32 v3, v21, 7, v3
	global_load_dwordx4 v[4:7], v3, s[24:25] offset:48
	global_load_dwordx4 v[8:11], v3, s[24:25] offset:32
	global_load_dwordx4 v[12:15], v3, s[24:25] offset:16
	global_load_dwordx4 v[16:19], v3, s[24:25]
	v_readlane_b32 s39, v251, 59
	v_cmp_eq_u32_e32 vcc, 0, v20
	s_waitcnt vmcnt(3)
	v_add_f32_e32 v4, v4, v5
	s_waitcnt vmcnt(2)
	v_add_f32_e32 v8, v8, v9
	s_waitcnt vmcnt(1)
	v_add_f32_e32 v12, v12, v13
	s_waitcnt vmcnt(0)
	v_add_f32_e32 v3, v16, v17
	v_add_f32_e32 v16, v18, v19
	v_add_f32_e32 v3, v3, v16
	v_add_f32_e32 v13, v14, v15
	v_add_f32_e32 v3, 0, v3
	v_add_f32_e32 v12, v12, v13
	v_add_f32_e32 v9, v10, v11
	v_add_f32_e32 v3, v3, v12
	v_add_f32_e32 v8, v8, v9
	v_add_f32_e32 v5, v6, v7
	v_add_f32_e32 v3, v3, v8
	v_add_f32_e32 v4, v4, v5
	v_add_f32_e32 v3, v3, v4
	v_lshlrev_b32_e32 v4, 4, v21
	global_load_dwordx4 v[4:7], v4, s[38:39]
	s_waitcnt vmcnt(0)
	v_add_f32_e32 v4, v4, v5
	v_add_f32_e32 v5, v6, v7
	v_add_f32_e32 v4, v4, v5
	v_cndmask_b32_e32 v6, 0, v4, vcc
	v_mov_b32_dpp v5, v3 quad_perm:[1,0,3,2] row_mask:0xf bank_mask:0xf
	s_nop 0
	v_mov_b32_dpp v6, v6 quad_perm:[1,0,3,2] row_mask:0xf bank_mask:0xf
	s_and_saveexec_b64 s[38:39], vcc
	s_cbranch_execz .LBB0_1096
	s_waitcnt lgkmcnt(1)
	v_add_f32_e32 v3, v3, v5
	v_fmamk_f32 v3, v3, 0x3b800000, v212
	v_rsq_f32_e32 v3, v3
	s_waitcnt lgkmcnt(0)
	v_add_f32_e32 v4, v4, v6
	v_fmamk_f32 v4, v4, 0x3b000000, v212
	v_rsq_f32_e32 v4, v4
	v_rcp_f32_e32 v5, v3
	v_lshl_add_u32 v2, v2, 2, 0
	v_add_u32_e32 v2, 0x20400, v2
	v_mul_f32_e32 v5, v4, v5
	ds_write2st64_b32 v2, v5, v3 offset1:4
	ds_write_b32 v2, v4 offset:2048

.LBB0_1124:
	v_lshl_add_u64 v[142:143], s[58:59], 0, v[98:99]
	global_load_dwordx4 v[196:199], v[142:143], off offset:528 nt
	global_load_dwordx4 v[204:207], v[142:143], off offset:512 nt
	v_add_u32_e32 v142, 0x10200, v98
	global_load_dwordx4 v[208:211], v142, s[58:59] offset:16 nt
	global_load_dwordx4 v[214:217], v142, s[58:59] nt
	v_add_u32_e32 v142, 0x20200, v98
	global_load_dwordx4 v[150:153], v142, s[58:59] offset:16 nt
	global_load_dwordx4 v[154:157], v142, s[58:59] nt
	v_add_u32_e32 v146, 0x30200, v98
	global_load_dwordx4 v[142:145], v146, s[58:59] offset:16 nt
	s_nop 0
	global_load_dwordx4 v[146:149], v146, s[58:59] nt
	v_or_b32_e32 v195, 0x100, v185
	s_and_b64 vcc, exec, s[40:41]
	s_waitcnt vmcnt(7)
	v_pk_fma_f32 v[198:199], v[120:121], v[140:141], v[198:199]
	s_waitcnt vmcnt(6)
	v_pk_fma_f32 v[206:207], v[124:125], v[136:137], v[206:207]
	v_pk_fma_f32 v[204:205], v[122:123], v[134:135], v[204:205]
	v_mul_f32_e32 v213, v207, v207
	v_mul_f32_e32 v186, v205, v205
	v_pk_fma_f32 v[196:197], v[118:119], v[138:139], v[196:197]
	v_fmac_f32_e32 v186, v204, v204
	v_fmac_f32_e32 v213, v206, v206
	v_add_f32_e32 v186, v186, v213
	v_mul_f32_e32 v213, v197, v197
	v_mul_f32_e32 v218, v199, v199
	v_fmac_f32_e32 v213, v196, v196
	v_fmac_f32_e32 v218, v198, v198
	v_add_f32_e32 v213, v213, v218
	v_add_f32_e32 v186, v186, v213
	v_pk_mul_f32 v[206:207], v[172:173], v[206:207]
	v_pk_mul_f32 v[204:205], v[170:171], v[204:205]
	v_pk_mul_f32 v[218:219], v[174:175], v[198:199]
	v_pk_mul_f32 v[198:199], v[100:101], v[196:197]
	v_add_f32_e32 v186, v192, v186
	v_cvt_pk_bf16_f32 v196, v204, v205
	v_cvt_pk_bf16_f32 v197, v206, v207
	v_cvt_pk_bf16_f32 v198, v198, v199
	v_cvt_pk_bf16_f32 v199, v218, v219
	global_store_dwordx4 v195, v[196:199], s[96:97]
	s_waitcnt vmcnt(6)
	v_pk_fma_f32 v[206:207], v[102:103], v[138:139], v[208:209]
	v_pk_fma_f32 v[204:205], v[104:105], v[140:141], v[210:211]
	s_waitcnt vmcnt(5)
	v_pk_fma_f32 v[196:197], v[108:109], v[136:137], v[216:217]
	v_pk_fma_f32 v[198:199], v[106:107], v[134:135], v[214:215]
	v_mul_f32_e32 v208, v197, v197
	v_mul_f32_e32 v192, v199, v199
	v_fmac_f32_e32 v192, v198, v198
	v_fmac_f32_e32 v208, v196, v196
	v_add_f32_e32 v192, v192, v208
	v_mul_f32_e32 v208, v207, v207
	v_mul_f32_e32 v209, v205, v205
	v_fmac_f32_e32 v208, v206, v206
	v_fmac_f32_e32 v209, v204, v204
	v_add_f32_e32 v208, v208, v209
	v_add_f32_e32 v192, v192, v208
	v_pk_mul_f32 v[208:209], v[172:173], v[196:197]
	v_pk_mul_f32 v[196:197], v[170:171], v[198:199]
	v_pk_mul_f32 v[204:205], v[174:175], v[204:205]
	v_pk_mul_f32 v[198:199], v[100:101], v[206:207]
	v_add_u32_e32 v195, 0x8100, v185
	v_add_f32_e32 v192, v193, v192
	v_cvt_pk_bf16_f32 v196, v196, v197
	v_cvt_pk_bf16_f32 v197, v208, v209
	v_cvt_pk_bf16_f32 v198, v198, v199
	v_cvt_pk_bf16_f32 v199, v204, v205
	s_waitcnt vmcnt(3)
	v_pk_fma_f32 v[156:157], v[88:89], v[136:137], v[156:157]
	v_pk_fma_f32 v[154:155], v[86:87], v[134:135], v[154:155]
	global_store_dwordx4 v195, v[196:199], s[96:97]
	v_mul_f32_e32 v193, v155, v155
	v_mul_f32_e32 v195, v157, v157
	v_pk_fma_f32 v[152:153], v[84:85], v[140:141], v[152:153]
	v_pk_fma_f32 v[150:151], v[82:83], v[138:139], v[150:151]
	v_fmac_f32_e32 v193, v154, v154
	v_fmac_f32_e32 v195, v156, v156
	v_add_f32_e32 v193, v193, v195
	v_mul_f32_e32 v195, v151, v151
	v_mul_f32_e32 v197, v153, v153
	v_fmac_f32_e32 v195, v150, v150
	v_fmac_f32_e32 v197, v152, v152
	v_add_f32_e32 v195, v195, v197
	v_add_f32_e32 v193, v193, v195
	v_add_f32_e32 v193, v194, v193
	v_pk_mul_f32 v[156:157], v[172:173], v[156:157]
	v_pk_mul_f32 v[154:155], v[170:171], v[154:155]
	v_pk_mul_f32 v[194:195], v[174:175], v[152:153]
	v_pk_mul_f32 v[152:153], v[100:101], v[150:151]
	v_add_u32_e32 v196, 0x10100, v185
	v_cvt_pk_bf16_f32 v150, v154, v155
	v_cvt_pk_bf16_f32 v151, v156, v157
	v_cvt_pk_bf16_f32 v152, v152, v153
	v_cvt_pk_bf16_f32 v153, v194, v195
	s_waitcnt vmcnt(2)
	v_pk_fma_f32 v[148:149], v[72:73], v[136:137], v[148:149]
	v_pk_fma_f32 v[146:147], v[70:71], v[134:135], v[146:147]
	global_store_dwordx4 v196, v[150:153], s[96:97]
	v_pk_fma_f32 v[144:145], v[68:69], v[140:141], v[144:145]
	v_pk_fma_f32 v[142:143], v[66:67], v[138:139], v[142:143]
	v_mul_f32_e32 v150, v147, v147
	v_mul_f32_e32 v151, v149, v149
	v_fmac_f32_e32 v150, v146, v146
	v_fmac_f32_e32 v151, v148, v148
	v_add_f32_e32 v150, v150, v151
	v_mul_f32_e32 v151, v143, v143
	v_mul_f32_e32 v153, v145, v145
	v_fmac_f32_e32 v151, v142, v142
	v_fmac_f32_e32 v153, v144, v144
	v_add_f32_e32 v151, v151, v153
	v_add_f32_e32 v150, v150, v151
	v_add_f32_e32 v191, v191, v150
	v_pk_mul_f32 v[148:149], v[172:173], v[148:149]
	v_pk_mul_f32 v[146:147], v[170:171], v[146:147]
	v_pk_mul_f32 v[150:151], v[174:175], v[144:145]
	v_pk_mul_f32 v[144:145], v[100:101], v[142:143]
	v_add_u32_e32 v152, 0x18100, v185
	v_cvt_pk_bf16_f32 v142, v146, v147
	v_cvt_pk_bf16_f32 v143, v148, v149
	v_cvt_pk_bf16_f32 v144, v144, v145
	v_cvt_pk_bf16_f32 v145, v150, v151
	global_store_dwordx4 v152, v[142:145], s[96:97]
	v_add_u32_e32 v213, 0x40100, v185
	s_nop 0
	v_add_u32_e32 v142, 0x80200, v98
	global_load_dwordx4 v[194:197], v142, s[58:59] offset:16 nt
	global_load_dwordx4 v[204:207], v142, s[58:59] nt
	v_add_u32_e32 v142, 0x90200, v98
	global_load_dwordx4 v[208:211], v142, s[58:59] offset:16 nt
	global_load_dwordx4 v[214:217], v142, s[58:59] nt
	v_add_u32_e32 v142, 0xa0200, v98
	v_add_u32_e32 v98, 0xb0200, v98
	global_load_dwordx4 v[150:153], v142, s[58:59] offset:16 nt
	global_load_dwordx4 v[154:157], v142, s[58:59] nt
	s_nop 0
	global_load_dwordx4 v[142:145], v98, s[58:59] offset:16 nt
	global_load_dwordx4 v[146:149], v98, s[58:59] nt
	s_waitcnt vmcnt(7)
	v_pk_fma_f32 v[196:197], v[52:53], v[140:141], v[196:197]
	s_waitcnt vmcnt(6)
	v_pk_fma_f32 v[198:199], v[56:57], v[136:137], v[206:207]
	v_pk_fma_f32 v[204:205], v[54:55], v[134:135], v[204:205]
	v_mul_f32_e32 v206, v199, v199
	v_mul_f32_e32 v98, v205, v205
	v_pk_fma_f32 v[194:195], v[50:51], v[138:139], v[194:195]
	v_fmac_f32_e32 v98, v204, v204
	v_fmac_f32_e32 v206, v198, v198
	v_add_f32_e32 v98, v98, v206
	v_mul_f32_e32 v206, v195, v195
	v_mul_f32_e32 v207, v197, v197
	v_fmac_f32_e32 v206, v194, v194
	v_fmac_f32_e32 v207, v196, v196
	v_add_f32_e32 v206, v206, v207
	v_add_f32_e32 v98, v98, v206
	v_pk_mul_f32 v[198:199], v[172:173], v[198:199]
	v_pk_mul_f32 v[204:205], v[170:171], v[204:205]
	v_pk_mul_f32 v[206:207], v[174:175], v[196:197]
	v_pk_mul_f32 v[196:197], v[100:101], v[194:195]
	v_add_f32_e32 v98, v190, v98
	v_cvt_pk_bf16_f32 v194, v204, v205
	v_cvt_pk_bf16_f32 v195, v198, v199
	v_cvt_pk_bf16_f32 v196, v196, v197
	v_cvt_pk_bf16_f32 v197, v206, v207
	global_store_dwordx4 v213, v[194:197], s[96:97]
	s_waitcnt vmcnt(6)
	v_pk_fma_f32 v[198:199], v[36:37], v[140:141], v[210:211]
	v_pk_fma_f32 v[204:205], v[34:35], v[138:139], v[208:209]
	s_waitcnt vmcnt(5)
	v_pk_fma_f32 v[194:195], v[40:41], v[136:137], v[216:217]
	v_pk_fma_f32 v[196:197], v[38:39], v[134:135], v[214:215]
	v_mul_f32_e32 v207, v195, v195
	v_mul_f32_e32 v206, v197, v197
	v_fmac_f32_e32 v206, v196, v196
	v_fmac_f32_e32 v207, v194, v194
	v_add_f32_e32 v206, v206, v207
	v_mul_f32_e32 v207, v205, v205
	v_mul_f32_e32 v208, v199, v199
	v_fmac_f32_e32 v207, v204, v204
	v_fmac_f32_e32 v208, v198, v198
	v_add_f32_e32 v207, v207, v208
	v_add_f32_e32 v206, v206, v207
	v_add_f32_e32 v189, v189, v206
	v_pk_mul_f32 v[206:207], v[172:173], v[194:195]
	v_pk_mul_f32 v[194:195], v[170:171], v[196:197]
	v_pk_mul_f32 v[198:199], v[174:175], v[198:199]
	v_pk_mul_f32 v[196:197], v[100:101], v[204:205]
	v_add_u32_e32 v190, 0x48100, v185
	v_cvt_pk_bf16_f32 v194, v194, v195
	v_cvt_pk_bf16_f32 v195, v206, v207
	v_cvt_pk_bf16_f32 v196, v196, v197
	v_cvt_pk_bf16_f32 v197, v198, v199
	s_waitcnt vmcnt(3)
	v_pk_fma_f32 v[156:157], v[24:25], v[136:137], v[156:157]
	v_pk_fma_f32 v[154:155], v[22:23], v[134:135], v[154:155]
	s_waitcnt vmcnt(1)
	v_pk_fma_f32 v[136:137], v[8:9], v[136:137], v[148:149]
	v_pk_fma_f32 v[146:147], v[6:7], v[134:135], v[146:147]
	global_store_dwordx4 v190, v[194:197], s[96:97]
	v_mul_f32_e32 v134, v147, v147
	v_mul_f32_e32 v135, v137, v137
	v_pk_fma_f32 v[194:195], v[18:19], v[138:139], v[150:151]
	v_mul_f32_e32 v150, v155, v155
	v_mul_f32_e32 v151, v157, v157
	v_pk_fma_f32 v[152:153], v[20:21], v[140:141], v[152:153]
	v_fmac_f32_e32 v150, v154, v154
	v_fmac_f32_e32 v151, v156, v156
	v_pk_fma_f32 v[140:141], v[4:5], v[140:141], v[144:145]
	v_pk_fma_f32 v[138:139], v[2:3], v[138:139], v[142:143]
	v_fmac_f32_e32 v134, v146, v146
	v_fmac_f32_e32 v135, v136, v136
	v_add_f32_e32 v150, v150, v151
	v_mul_f32_e32 v151, v195, v195
	v_mul_f32_e32 v196, v153, v153
	v_add_f32_e32 v134, v134, v135
	v_mul_f32_e32 v135, v139, v139
	v_mul_f32_e32 v142, v141, v141
	v_fmac_f32_e32 v151, v194, v194
	v_fmac_f32_e32 v196, v152, v152
	v_fmac_f32_e32 v135, v138, v138
	v_fmac_f32_e32 v142, v140, v140
	v_add_f32_e32 v151, v151, v196
	v_add_f32_e32 v135, v135, v142
	v_add_f32_e32 v150, v150, v151
	v_pk_mul_f32 v[156:157], v[172:173], v[156:157]
	v_pk_mul_f32 v[154:155], v[170:171], v[154:155]
	v_pk_mul_f32 v[196:197], v[174:175], v[152:153]
	v_pk_mul_f32 v[194:195], v[100:101], v[194:195]
	v_add_f32_e32 v134, v134, v135
	v_pk_mul_f32 v[142:143], v[172:173], v[136:137]
	v_pk_mul_f32 v[136:137], v[170:171], v[146:147]
	v_pk_mul_f32 v[140:141], v[174:175], v[140:141]
	v_pk_mul_f32 v[100:101], v[100:101], v[138:139]
	v_add_u32_e32 v190, 0x50100, v185
	v_add_f32_e32 v150, v188, v150
	v_cvt_pk_bf16_f32 v152, v154, v155
	v_cvt_pk_bf16_f32 v153, v156, v157
	v_cvt_pk_bf16_f32 v154, v194, v195
	v_cvt_pk_bf16_f32 v155, v196, v197
	v_add_u32_e32 v151, 0x58100, v185
	v_add_f32_e32 v134, v187, v134
	v_cvt_pk_bf16_f32 v136, v136, v137
	v_cvt_pk_bf16_f32 v137, v142, v143
	v_cvt_pk_bf16_f32 v138, v100, v101
	v_cvt_pk_bf16_f32 v139, v140, v141
	global_store_dwordx4 v190, v[152:155], s[96:97]
	global_store_dwordx4 v151, v[136:139], s[96:97]
	s_cbranch_vccz .LBB0_1142
	v_mov_b32_e32 v100, v186
	s_nop 1
	v_permlane16_swap_b32_e32 v186, v100
	s_lshl_b32 s38, s67, 4
	v_cmp_eq_u32_e32 vcc, 0, v183
	s_or_b32 s45, s38, s18
	s_waitcnt lgkmcnt(0)
	v_add_f32_e32 v100, v186, v100
	v_mov_b32_e32 v101, v100
	s_nop 1
	v_permlane32_swap_b32_e32 v100, v101
	s_and_saveexec_b64 s[38:39], vcc
	s_cbranch_execz .LBB0_1127
	v_readlane_b32 s58, v251, 32
	s_waitcnt lgkmcnt(0)
	v_add_f32_e32 v100, v100, v101
	v_lshl_add_u32 v101, v184, 6, s45
	v_readlane_b32 s59, v251, 33
	s_nop 4
	global_store_dword v101, v100, s[58:59]
.LBB0_1127:
	s_or_b64 exec, exec, s[38:39]
	v_mov_b32_e32 v100, v192
	s_nop 1
	v_permlane16_swap_b32_e32 v192, v100
	s_waitcnt lgkmcnt(0)
	v_add_f32_e32 v100, v192, v100
	v_mov_b32_e32 v101, v100
	s_nop 1
	v_permlane32_swap_b32_e32 v100, v101
	s_and_saveexec_b64 s[38:39], vcc
	s_cbranch_execz .LBB0_1129
	s_add_i32 s49, s45, 0x400
	v_readlane_b32 s58, v251, 32
	s_waitcnt lgkmcnt(0)
	v_add_f32_e32 v100, v100, v101
	v_lshl_add_u32 v101, v184, 6, s49
	v_readlane_b32 s59, v251, 33
	s_nop 4
	global_store_dword v101, v100, s[58:59]
.LBB0_1129:
	s_or_b64 exec, exec, s[38:39]
	v_mov_b32_e32 v100, v193
	s_nop 1
	v_permlane16_swap_b32_e32 v193, v100
	s_waitcnt lgkmcnt(0)
	v_add_f32_e32 v100, v193, v100
	v_mov_b32_e32 v101, v100
	s_nop 1
	v_permlane32_swap_b32_e32 v100, v101
	s_and_saveexec_b64 s[38:39], vcc
	s_cbranch_execz .LBB0_1131
	s_add_i32 s49, s45, 0x800
	v_readlane_b32 s58, v251, 32
	s_waitcnt lgkmcnt(0)
	v_add_f32_e32 v100, v100, v101
	v_lshl_add_u32 v101, v184, 6, s49
	v_readlane_b32 s59, v251, 33
	s_nop 4
	global_store_dword v101, v100, s[58:59]
.LBB0_1131:
	s_or_b64 exec, exec, s[38:39]
	v_mov_b32_e32 v100, v191
	s_nop 1
	v_permlane16_swap_b32_e32 v191, v100
	s_waitcnt lgkmcnt(0)
	v_add_f32_e32 v100, v191, v100
	v_mov_b32_e32 v101, v100
	s_nop 1
	v_permlane32_swap_b32_e32 v100, v101
	s_and_saveexec_b64 s[38:39], vcc
	s_cbranch_execz .LBB0_1133
	s_add_i32 s49, s45, 0xc00
	v_readlane_b32 s58, v251, 32
	s_waitcnt lgkmcnt(0)
	v_add_f32_e32 v100, v100, v101
	v_lshl_add_u32 v101, v184, 6, s49
	v_readlane_b32 s59, v251, 33
	s_nop 4
	global_store_dword v101, v100, s[58:59]
.LBB0_1133:
	s_or_b64 exec, exec, s[38:39]
	v_mov_b32_e32 v100, v98
	s_nop 1
	v_permlane16_swap_b32_e32 v98, v100
	s_waitcnt lgkmcnt(0)
	v_add_f32_e32 v98, v98, v100
	v_mov_b32_e32 v100, v98
	s_nop 1
	v_permlane32_swap_b32_e32 v98, v100
	s_and_saveexec_b64 s[38:39], vcc
	s_cbranch_execz .LBB0_1135
	s_add_i32 s49, s45, 0x2000
	v_readlane_b32 s58, v251, 32
	s_waitcnt lgkmcnt(0)
	v_add_f32_e32 v98, v98, v100
	v_lshl_add_u32 v100, v184, 6, s49
	v_readlane_b32 s59, v251, 33
	s_nop 4
	global_store_dword v100, v98, s[58:59]
.LBB0_1135:
	s_or_b64 exec, exec, s[38:39]
	v_mov_b32_e32 v98, v189
	s_nop 1
	v_permlane16_swap_b32_e32 v189, v98
	s_waitcnt lgkmcnt(0)
	v_add_f32_e32 v98, v189, v98
	v_mov_b32_e32 v100, v98
	s_nop 1
	v_permlane32_swap_b32_e32 v98, v100
	s_and_saveexec_b64 s[38:39], vcc
	s_cbranch_execz .LBB0_1137
	s_add_i32 s49, s45, 0x2400
	v_readlane_b32 s58, v251, 32
	s_waitcnt lgkmcnt(0)
	v_add_f32_e32 v98, v98, v100
	v_lshl_add_u32 v100, v184, 6, s49
	v_readlane_b32 s59, v251, 33
	s_nop 4
	global_store_dword v100, v98, s[58:59]
.LBB0_1137:
	s_or_b64 exec, exec, s[38:39]
	v_mov_b32_e32 v98, v150
	s_nop 1
	v_permlane16_swap_b32_e32 v150, v98
	s_waitcnt lgkmcnt(0)
	v_add_f32_e32 v98, v150, v98
	v_mov_b32_e32 v100, v98
	s_nop 1
	v_permlane32_swap_b32_e32 v98, v100
	s_and_saveexec_b64 s[38:39], vcc
	s_cbranch_execz .LBB0_1139
	s_add_i32 s49, s45, 0x2800
	v_readlane_b32 s58, v251, 32
	s_waitcnt lgkmcnt(0)
	v_add_f32_e32 v98, v98, v100
	v_lshl_add_u32 v100, v184, 6, s49
	v_readlane_b32 s59, v251, 33
	s_nop 4
	global_store_dword v100, v98, s[58:59]
.LBB0_1139:
	s_or_b64 exec, exec, s[38:39]
	v_mov_b32_e32 v98, v134
	s_nop 1
	v_permlane16_swap_b32_e32 v134, v98
	s_waitcnt lgkmcnt(0)
	v_add_f32_e32 v98, v134, v98
	v_mov_b32_e32 v100, v98
	s_nop 1
	v_permlane32_swap_b32_e32 v98, v100
	s_and_saveexec_b64 s[38:39], vcc
	s_cbranch_execz .LBB0_1141
	s_addk_i32 s45, 0x2c00
	v_readlane_b32 s58, v251, 32
	s_waitcnt lgkmcnt(0)
	v_add_f32_e32 v98, v98, v100
	v_lshl_add_u32 v100, v184, 6, s45
	v_readlane_b32 s59, v251, 33
	s_nop 4
	global_store_dword v100, v98, s[58:59]

.LBB0_1144:
	v_mov_b32_e32 v3, v0
	v_readlane_b32 s38, v251, 58
	v_ashrrev_i32_e32 v2, 1, v3
	v_and_b32_e32 v20, 1, v3
	v_lshl_add_u32 v21, s66, 8, v2
	v_lshlrev_b32_e32 v3, 6, v20
	v_lshl_or_b32 v3, v21, 7, v3
	global_load_dwordx4 v[4:7], v3, s[24:25] offset:48
	global_load_dwordx4 v[8:11], v3, s[24:25] offset:32
	global_load_dwordx4 v[12:15], v3, s[24:25] offset:16
	global_load_dwordx4 v[16:19], v3, s[24:25]
	v_readlane_b32 s39, v251, 59
	v_cmp_eq_u32_e32 vcc, 0, v20
	s_waitcnt vmcnt(0)
	v_add_f32_e32 v4, v4, v5
	v_add_f32_e32 v8, v8, v9
	v_add_f32_e32 v12, v12, v13
	v_add_f32_e32 v3, v16, v17
	v_add_f32_e32 v16, v18, v19
	v_add_f32_e32 v3, v3, v16
	v_add_f32_e32 v13, v14, v15
	v_add_f32_e32 v3, 0, v3
	v_add_f32_e32 v12, v12, v13
	v_add_f32_e32 v9, v10, v11
	v_add_f32_e32 v3, v3, v12
	v_add_f32_e32 v8, v8, v9
	v_add_f32_e32 v5, v6, v7
	v_add_f32_e32 v3, v3, v8
	v_add_f32_e32 v4, v4, v5
	v_add_f32_e32 v3, v3, v4
	v_lshlrev_b32_e32 v4, 4, v21
	global_load_dwordx4 v[4:7], v4, s[38:39]
	s_waitcnt vmcnt(0)
	v_add_f32_e32 v4, v4, v5
	v_add_f32_e32 v5, v6, v7
	v_add_f32_e32 v4, v4, v5
	v_cndmask_b32_e32 v6, 0, v4, vcc
	v_mov_b32_dpp v5, v3 quad_perm:[1,0,3,2] row_mask:0xf bank_mask:0xf
	s_nop 0
	v_mov_b32_dpp v6, v6 quad_perm:[1,0,3,2] row_mask:0xf bank_mask:0xf
	s_and_saveexec_b64 s[38:39], vcc
	s_cbranch_execz .LBB0_1146
	s_waitcnt lgkmcnt(1)
	v_add_f32_e32 v3, v3, v5
	v_fmamk_f32 v3, v3, 0x3b800000, v212
	v_rsq_f32_e32 v3, v3
	s_waitcnt lgkmcnt(0)
	v_add_f32_e32 v4, v4, v6
	v_fmamk_f32 v4, v4, 0x3b000000, v212
	v_rsq_f32_e32 v4, v4
	v_rcp_f32_e32 v5, v3
	v_lshl_add_u32 v2, v2, 2, 0
	v_add_u32_e32 v2, 0x20400, v2
	v_mul_f32_e32 v5, v4, v5
	ds_write2st64_b32 v2, v5, v3 offset1:4
	ds_write_b32 v2, v4 offset:2048

.LBB0_1250:
	v_add_co_u32_e32 v40, vcc, 0x400000, v38
	global_load_dwordx2 v[50:51], v[38:39], off nt
	s_nop 0
	v_addc_co_u32_e32 v41, vcc, 0, v39, vcc
	v_add_co_u32_e32 v42, vcc, 0x800000, v38
	global_load_dwordx2 v[52:53], v[40:41], off nt
	s_nop 0
	v_addc_co_u32_e32 v43, vcc, 0, v39, vcc
	global_load_dwordx2 v[92:93], v[42:43], off nt
	v_add_co_u32_e32 v48, vcc, 0xc00000, v38
	global_load_dwordx4 v[76:79], v[18:19], off
	s_nop 0
	v_addc_co_u32_e32 v49, vcc, 0, v39, vcc
	global_load_dwordx2 v[94:95], v[48:49], off nt
	global_load_dwordx4 v[80:83], v[36:37], off nt
	global_load_dwordx4 v[84:87], v[14:15], off
	global_load_dwordx4 v[88:91], v[16:17], off
	s_add_i32 s0, s2, 0x4000
	global_load_dwordx4 v[10:13], v[36:37], off offset:1024 nt
	global_load_dwordx4 v[6:9], v[36:37], off offset:2048 nt
	s_waitcnt lgkmcnt(0)
	global_load_dwordx4 v[2:5], v[36:37], off offset:3072 nt
	global_load_dwordx2 v[66:67], v[38:39], off offset:512 nt
	global_load_dwordx2 v[58:59], v[38:39], off offset:1024 nt
	global_load_dwordx2 v[46:47], v[38:39], off offset:1536 nt
	s_ashr_i32 s1, s0, 31
	s_lshl_b64 s[22:23], s[0:1], 11
	global_load_dwordx2 v[64:65], v[40:41], off offset:512 nt
	global_load_dwordx2 v[56:57], v[40:41], off offset:1024 nt
	global_load_dwordx2 v[44:45], v[40:41], off offset:1536 nt
	global_load_dwordx2 v[62:63], v[42:43], off offset:512 nt
	global_load_dwordx2 v[54:55], v[42:43], off offset:1024 nt
	s_nop 0
	global_load_dwordx2 v[42:43], v[42:43], off offset:1536 nt
	v_lshl_add_u64 v[40:41], v[34:35], 0, s[22:23]
	global_load_dwordx2 v[68:69], v[48:49], off offset:512 nt
	global_load_dwordx2 v[60:61], v[48:49], off offset:1024 nt
	s_nop 0
	global_load_dwordx2 v[48:49], v[48:49], off offset:1536 nt
	s_waitcnt vmcnt(22)
	v_lshlrev_b32_e32 v96, 16, v50
	v_and_b32_e32 v97, 0xffff0000, v50
	v_lshlrev_b32_e32 v50, 16, v51
	v_and_b32_e32 v51, 0xffff0000, v51
	v_pk_add_f32 v[96:97], v[96:97], 0 op_sel_hi:[1,0]
	v_pk_add_f32 v[50:51], v[50:51], 0 op_sel_hi:[1,0]
	s_waitcnt vmcnt(21)
	v_lshlrev_b32_e32 v100, 16, v52
	v_and_b32_e32 v101, 0xffff0000, v52
	v_lshlrev_b32_e32 v52, 16, v53
	v_and_b32_e32 v53, 0xffff0000, v53
	v_pk_add_f32 v[96:97], v[96:97], v[100:101]
	s_waitcnt vmcnt(20)
	v_lshlrev_b32_e32 v100, 16, v92
	v_and_b32_e32 v101, 0xffff0000, v92
	v_pk_add_f32 v[50:51], v[50:51], v[52:53]
	v_lshlrev_b32_e32 v52, 16, v93
	v_and_b32_e32 v53, 0xffff0000, v93
	v_pk_add_f32 v[92:93], v[96:97], v[100:101]
	s_waitcnt vmcnt(18)
	v_lshlrev_b32_e32 v96, 16, v94
	v_and_b32_e32 v97, 0xffff0000, v94
	v_pk_add_f32 v[50:51], v[50:51], v[52:53]
	v_lshlrev_b32_e32 v52, 16, v95
	v_and_b32_e32 v53, 0xffff0000, v95
	v_pk_add_f32 v[92:93], v[92:93], v[96:97]
	v_pk_add_f32 v[50:51], v[50:51], v[52:53]
	s_waitcnt vmcnt(16)
	v_pk_fma_f32 v[52:53], v[92:93], v[84:85], v[80:81]
	v_pk_fma_f32 v[50:51], v[50:51], v[86:87], v[82:83]
	v_pk_add_f32 v[78:79], v[78:79], 1.0 op_sel_hi:[1,0]
	v_pk_add_f32 v[76:77], v[76:77], 1.0 op_sel_hi:[1,0]
	s_waitcnt vmcnt(15)
	v_pk_mul_f32 v[80:81], v[88:89], v[52:53]
	v_pk_mul_f32 v[82:83], v[90:91], v[50:51]
	v_pk_mul_f32 v[76:77], v[80:81], v[76:77]
	v_pk_mul_f32 v[78:79], v[82:83], v[78:79]
	v_cvt_pk_bf16_f32 v76, v76, v77
	v_cvt_pk_bf16_f32 v77, v78, v79
	global_store_dwordx2 v[40:41], v[76:77], off
	global_load_dwordx4 v[76:79], v[20:21], off
	s_nop 0
	global_load_dwordx4 v[80:83], v[22:23], off
	global_load_dwordx4 v[84:87], v[16:17], off offset:1024
	s_waitcnt vmcnt(15)
	v_lshlrev_b32_e32 v88, 16, v66
	v_and_b32_e32 v89, 0xffff0000, v66
	v_lshlrev_b32_e32 v66, 16, v67
	v_and_b32_e32 v67, 0xffff0000, v67
	v_pk_add_f32 v[88:89], v[88:89], 0 op_sel_hi:[1,0]
	v_pk_add_f32 v[66:67], v[66:67], 0 op_sel_hi:[1,0]
	s_waitcnt vmcnt(12)
	v_lshlrev_b32_e32 v90, 16, v64
	v_and_b32_e32 v91, 0xffff0000, v64
	v_lshlrev_b32_e32 v64, 16, v65
	v_and_b32_e32 v65, 0xffff0000, v65
	v_pk_add_f32 v[88:89], v[88:89], v[90:91]
	s_waitcnt vmcnt(9)
	v_lshlrev_b32_e32 v90, 16, v62
	v_and_b32_e32 v91, 0xffff0000, v62
	v_pk_add_f32 v[64:65], v[66:67], v[64:65]
	v_lshlrev_b32_e32 v62, 16, v63
	v_and_b32_e32 v63, 0xffff0000, v63
	v_pk_add_f32 v[66:67], v[88:89], v[90:91]
	s_waitcnt vmcnt(6)
	v_lshlrev_b32_e32 v88, 16, v68
	v_and_b32_e32 v89, 0xffff0000, v68
	v_pk_add_f32 v[62:63], v[64:65], v[62:63]
	v_lshlrev_b32_e32 v64, 16, v69
	v_and_b32_e32 v65, 0xffff0000, v69
	v_pk_add_f32 v[66:67], v[66:67], v[88:89]
	v_pk_add_f32 v[62:63], v[62:63], v[64:65]
	s_waitcnt vmcnt(2)
	v_pk_fma_f32 v[10:11], v[66:67], v[76:77], v[10:11]
	v_pk_fma_f32 v[12:13], v[62:63], v[78:79], v[12:13]
	s_waitcnt vmcnt(1)
	v_pk_add_f32 v[62:63], v[82:83], 1.0 op_sel_hi:[1,0]
	v_pk_add_f32 v[64:65], v[80:81], 1.0 op_sel_hi:[1,0]
	s_waitcnt vmcnt(0)
	v_pk_mul_f32 v[66:67], v[84:85], v[10:11]
	v_pk_mul_f32 v[68:69], v[86:87], v[12:13]
	v_pk_mul_f32 v[64:65], v[66:67], v[64:65]
	v_pk_mul_f32 v[62:63], v[68:69], v[62:63]
	v_cvt_pk_bf16_f32 v64, v64, v65
	v_cvt_pk_bf16_f32 v65, v62, v63
	global_store_dwordx2 v[40:41], v[64:65], off offset:512
	global_load_dwordx4 v[62:65], v[24:25], off
	s_nop 0
	global_load_dwordx4 v[66:69], v[26:27], off
	global_load_dwordx4 v[76:79], v[16:17], off offset:2048
	v_lshlrev_b32_e32 v80, 16, v58
	v_and_b32_e32 v81, 0xffff0000, v58
	v_lshlrev_b32_e32 v58, 16, v59
	v_and_b32_e32 v59, 0xffff0000, v59
	v_pk_add_f32 v[80:81], v[80:81], 0 op_sel_hi:[1,0]
	v_pk_add_f32 v[58:59], v[58:59], 0 op_sel_hi:[1,0]
	v_lshlrev_b32_e32 v82, 16, v56
	v_and_b32_e32 v83, 0xffff0000, v56
	v_lshlrev_b32_e32 v56, 16, v57
	v_and_b32_e32 v57, 0xffff0000, v57
	v_pk_add_f32 v[80:81], v[80:81], v[82:83]
	v_lshlrev_b32_e32 v82, 16, v54
	v_and_b32_e32 v83, 0xffff0000, v54
	v_pk_add_f32 v[56:57], v[58:59], v[56:57]
	v_lshlrev_b32_e32 v54, 16, v55
	v_and_b32_e32 v55, 0xffff0000, v55
	v_pk_add_f32 v[58:59], v[80:81], v[82:83]
	v_lshlrev_b32_e32 v80, 16, v60
	v_and_b32_e32 v81, 0xffff0000, v60
	v_pk_add_f32 v[54:55], v[56:57], v[54:55]
	v_lshlrev_b32_e32 v56, 16, v61
	v_and_b32_e32 v57, 0xffff0000, v61
	v_pk_add_f32 v[58:59], v[58:59], v[80:81]
	v_pk_add_f32 v[54:55], v[54:55], v[56:57]
	v_mul_f32_e32 v11, v11, v11
	v_mul_f32_e32 v13, v13, v13
	v_fmac_f32_e32 v11, v10, v10
	v_fmac_f32_e32 v13, v12, v12
	v_add_f32_e32 v10, v11, v13
	s_waitcnt vmcnt(2)
	v_pk_fma_f32 v[54:55], v[54:55], v[64:65], v[8:9]
	v_pk_fma_f32 v[56:57], v[58:59], v[62:63], v[6:7]
	s_waitcnt vmcnt(1)
	v_pk_add_f32 v[6:7], v[68:69], 1.0 op_sel_hi:[1,0]
	v_pk_add_f32 v[8:9], v[66:67], 1.0 op_sel_hi:[1,0]
	s_waitcnt vmcnt(0)
	v_pk_mul_f32 v[58:59], v[76:77], v[56:57]
	v_pk_mul_f32 v[60:61], v[78:79], v[54:55]
	v_pk_mul_f32 v[8:9], v[58:59], v[8:9]
	v_pk_mul_f32 v[6:7], v[60:61], v[6:7]
	v_cvt_pk_bf16_f32 v8, v8, v9
	v_cvt_pk_bf16_f32 v9, v6, v7
	global_store_dwordx2 v[40:41], v[8:9], off offset:1024
	global_load_dwordx4 v[58:61], v[28:29], off
	s_nop 0
	global_load_dwordx4 v[6:9], v[16:17], off offset:3072
	global_load_dwordx4 v[62:65], v[30:31], off
	v_lshlrev_b32_e32 v66, 16, v46
	v_and_b32_e32 v67, 0xffff0000, v46
	v_lshlrev_b32_e32 v46, 16, v47
	v_and_b32_e32 v47, 0xffff0000, v47
	v_pk_add_f32 v[66:67], v[66:67], 0 op_sel_hi:[1,0]
	v_pk_add_f32 v[46:47], v[46:47], 0 op_sel_hi:[1,0]
	v_lshlrev_b32_e32 v68, 16, v44
	v_and_b32_e32 v69, 0xffff0000, v44
	v_lshlrev_b32_e32 v44, 16, v45
	v_and_b32_e32 v45, 0xffff0000, v45
	v_pk_add_f32 v[66:67], v[66:67], v[68:69]
	v_lshlrev_b32_e32 v68, 16, v42
	v_and_b32_e32 v69, 0xffff0000, v42
	v_pk_add_f32 v[44:45], v[46:47], v[44:45]
	v_lshlrev_b32_e32 v42, 16, v43
	v_and_b32_e32 v43, 0xffff0000, v43
	v_pk_add_f32 v[42:43], v[44:45], v[42:43]
	v_lshlrev_b32_e32 v44, 16, v49
	v_and_b32_e32 v45, 0xffff0000, v49
	v_pk_add_f32 v[42:43], v[42:43], v[44:45]
	v_mul_f32_e32 v44, v53, v53
	v_mul_f32_e32 v45, v51, v51
	v_pk_add_f32 v[46:47], v[66:67], v[68:69]
	v_lshlrev_b32_e32 v66, 16, v48
	v_and_b32_e32 v67, 0xffff0000, v48
	v_fmac_f32_e32 v44, v52, v52
	v_fmac_f32_e32 v45, v50, v50
	v_mul_f32_e32 v11, v57, v57
	v_mul_f32_e32 v12, v55, v55
	v_pk_add_f32 v[46:47], v[46:47], v[66:67]
	v_add_f32_e32 v44, v44, v45
	v_fmac_f32_e32 v11, v56, v56
	v_fmac_f32_e32 v12, v54, v54
	v_add_f32_e32 v10, v44, v10
	v_add_f32_e32 v11, v11, v12
	v_add_f32_e32 v10, v10, v11
	s_waitcnt vmcnt(2)
	v_pk_fma_f32 v[4:5], v[42:43], v[60:61], v[4:5]
	v_pk_fma_f32 v[2:3], v[46:47], v[58:59], v[2:3]
	v_mul_f32_e32 v12, v5, v5
	v_mul_f32_e32 v11, v3, v3
	v_fmac_f32_e32 v11, v2, v2
	v_fmac_f32_e32 v12, v4, v4
	v_add_f32_e32 v11, v11, v12
	v_add_f32_e32 v10, v10, v11
	s_nop 1
	v_mov_b32_dpp v11, v10 quad_perm:[1,0,3,2] row_mask:0xf bank_mask:0xf
	s_waitcnt vmcnt(1)
	v_pk_mul_f32 v[6:7], v[6:7], v[2:3]
	v_pk_mul_f32 v[2:3], v[8:9], v[4:5]
	s_waitcnt vmcnt(0)
	v_pk_add_f32 v[4:5], v[64:65], 1.0 op_sel_hi:[1,0]
	v_pk_add_f32 v[8:9], v[62:63], 1.0 op_sel_hi:[1,0]
	s_waitcnt lgkmcnt(0)
	v_add_f32_e32 v10, v10, v11
	s_nop 1
	v_mov_b32_dpp v11, v10 quad_perm:[2,3,0,1] row_mask:0xf bank_mask:0xf
	v_pk_mul_f32 v[4:5], v[2:3], v[4:5]
	v_pk_mul_f32 v[6:7], v[6:7], v[8:9]
	s_waitcnt lgkmcnt(0)
	v_add_f32_e32 v10, v10, v11
	s_nop 1
	v_mov_b32_dpp v11, v10 row_half_mirror row_mask:0xf bank_mask:0xf
	v_cvt_pk_bf16_f32 v6, v6, v7
	v_cvt_pk_bf16_f32 v7, v4, v5
	global_store_dwordx2 v[40:41], v[6:7], off offset:1536
	s_waitcnt lgkmcnt(0)
	v_add_f32_e32 v10, v10, v11
	s_nop 1
	v_mov_b32_dpp v11, v10 row_mirror row_mask:0xf bank_mask:0xf
	s_waitcnt lgkmcnt(0)
	v_add_f32_e32 v10, v10, v11
	v_mov_b32_e32 v11, v10
	s_nop 1
	v_permlane16_swap_b32_e32 v10, v11
	s_waitcnt lgkmcnt(0)
	v_add_f32_e32 v2, v10, v11
	v_mov_b32_e32 v3, v2
	s_nop 1
	v_permlane32_swap_b32_e32 v2, v3
	s_and_saveexec_b64 s[22:23], s[38:39]
	s_cbranch_execz .LBB0_1249
	s_lshl_b64 s[0:1], s[0:1], 6
	s_waitcnt lgkmcnt(0)
	v_add_f32_e32 v2, v2, v3
	v_lshl_add_u64 v[4:5], v[32:33], 0, s[0:1]
	v_cndmask_b32_e64 v2, 0, v2, s[40:41]
	global_store_dword v[4:5], v2, off
	s_branch .LBB0_1249

.LBB0_1556:
	s_cmp_gt_i32 s58, 63
	v_readlane_b32 s52, v253, 9
	s_cselect_b64 s[50:51], -1, 0
	v_readlane_b32 s53, v253, 10
	v_mov_b32_e32 v132, v0
	s_and_b64 s[50:51], s[52:53], s[50:51]
	s_andn2_b64 vcc, exec, s[50:51]
	v_and_b32_e32 v214, 15, v132
	v_bfe_u32 v213, v132, 4, 2
	s_mov_b64 s[50:51], -1
	s_cbranch_vccz .LBB0_1578
	s_lshr_b32 s50, s58, 3
	s_cmp_lt_i32 s58, 64
	s_mulk_i32 s50, 0x1800
	s_cselect_b32 s54, s50, 0xc000
	s_ashr_i32 s55, s54, 31
	s_lshl_b32 s50, s58, 8
	s_add_i32 s52, s50, s10
	s_lshl_b64 s[50:51], s[54:55], 2
	v_readlane_b32 s56, v250, 14
	v_readlane_b32 s57, v250, 15
	s_add_u32 s50, s56, s50
	s_addc_u32 s51, s57, s51
	s_add_u32 s50, s50, 0x5000
	s_addc_u32 s51, s51, 0
	s_lshl_b32 s53, s49, 8
	v_lshl_or_b32 v132, v213, 3, s53
	v_or_b32_e32 v230, s11, v132
	s_or_b32 s53, s54, 0x400
	v_lshlrev_b32_e32 v156, 2, v230
	v_add_lshl_u32 v152, v230, s53, 2
	global_load_dwordx4 v[132:135], v156, s[50:51] offset:16
	global_load_dwordx4 v[136:139], v156, s[50:51]
	global_load_dwordx4 v[140:143], v156, s[38:39] offset:16
	global_load_dwordx4 v[144:147], v156, s[38:39]
	global_load_dwordx4 v[148:151], v152, s[26:27] offset:16
	s_nop 0
	global_load_dwordx4 v[152:155], v152, s[26:27]
	v_or_b32_e32 v215, s52, v214
	s_add_i32 s52, s54, 0x1000
	v_add_lshl_u32 v160, v230, s52, 2
	v_lshlrev_b32_e32 v224, 1, v230
	v_lshlrev_b32_e32 v231, 11, v215
	v_add_u32_e32 v223, v224, v231
	v_or_b32_e32 v216, 16, v215
	v_lshlrev_b32_e32 v232, 11, v216
	v_add_u32_e32 v222, 0xb0, v215
	v_or_b32_e32 v217, 32, v215
	v_lshlrev_b32_e32 v233, 11, v222
	v_lshlrev_b32_e32 v225, 11, v217
	v_or_b32_e32 v218, 48, v215
	v_lshlrev_b32_e32 v226, 11, v218
	v_add_u32_e32 v219, 0x80, v215
	v_lshlrev_b32_e32 v227, 11, v219
	v_add_u32_e32 v220, 0x90, v215
	v_lshlrev_b32_e32 v228, 11, v220
	v_add_u32_e32 v221, 0xa0, v215
	v_lshlrev_b32_e32 v229, 11, v221
	s_waitcnt vmcnt(0)
	v_pk_add_f32 v[150:151], v[150:151], 1.0 op_sel_hi:[1,0]
	v_pk_add_f32 v[154:155], v[154:155], 1.0 op_sel_hi:[1,0]
	v_pk_add_f32 v[152:153], v[152:153], 1.0 op_sel_hi:[1,0]
	v_pk_mul_f32 v[182:183], v[146:147], v[154:155]
	v_pk_mul_f32 v[184:185], v[144:145], v[152:153]
	global_load_dwordx4 v[144:147], v156, s[0:1] offset:16
	global_load_dwordx4 v[152:155], v156, s[0:1]
	s_nop 0
	global_load_dwordx4 v[156:159], v160, s[56:57] offset:16
	s_nop 0
	global_load_dwordx4 v[160:163], v160, s[56:57]
	v_pk_add_f32 v[148:149], v[148:149], 1.0 op_sel_hi:[1,0]
	global_load_dwordx4 v[168:171], v223, s[96:97] nt
	v_pk_mul_f32 v[186:187], v[142:143], v[150:151]
	v_pk_mul_f32 v[188:189], v[140:141], v[148:149]
	s_waitcnt vmcnt(2)
	v_pk_add_f32 v[140:141], v[158:159], 1.0 op_sel_hi:[1,0]
	v_pk_add_f32 v[142:143], v[156:157], 1.0 op_sel_hi:[1,0]
	v_pk_mul_f32 v[194:195], v[146:147], v[140:141]
	v_pk_mul_f32 v[140:141], v[144:145], v[142:143]
	v_add_u32_e32 v144, v224, v233
	v_rcp_f32_e32 v196, v140
	v_add_u32_e32 v140, v224, v232
	global_load_dwordx4 v[164:167], v140, s[96:97] nt
	s_waitcnt vmcnt(2)
	v_pk_add_f32 v[162:163], v[162:163], 1.0 op_sel_hi:[1,0]
	v_pk_add_f32 v[160:161], v[160:161], 1.0 op_sel_hi:[1,0]
	global_load_dwordx4 v[144:147], v144, s[96:97] nt
	v_add_u32_e32 v140, v224, v225
	v_pk_mul_f32 v[154:155], v[154:155], v[162:163]
	v_pk_mul_f32 v[152:153], v[152:153], v[160:161]
	global_load_dwordx4 v[160:163], v140, s[96:97] nt
	v_add_u32_e32 v140, v224, v226
	global_load_dwordx4 v[156:159], v140, s[96:97] nt
	v_add_u32_e32 v140, v224, v227
	v_rcp_f32_e32 v192, v152
	v_rcp_f32_e32 v193, v153
	v_rcp_f32_e32 v190, v154
	v_rcp_f32_e32 v191, v155
	global_load_dwordx4 v[152:155], v140, s[96:97] nt
	v_add_u32_e32 v140, v224, v228
	global_load_dwordx4 v[148:151], v140, s[96:97] nt
	v_add_u32_e32 v140, v224, v229
	v_rcp_f32_e32 v197, v141
	global_load_dwordx4 v[140:143], v140, s[96:97] nt
	v_rcp_f32_e32 v194, v194
	v_rcp_f32_e32 v195, v195
	s_waitcnt vmcnt(7)
	v_lshlrev_b32_e32 v204, 16, v168
	v_and_b32_e32 v205, 0xffff0000, v168
	v_lshlrev_b32_e32 v168, 16, v169
	v_and_b32_e32 v169, 0xffff0000, v169
	v_pk_mul_f32 v[204:205], v[192:193], v[204:205]
	v_pk_mul_f32 v[168:169], v[190:191], v[168:169]
	v_lshlrev_b32_e32 v206, 16, v170
	v_and_b32_e32 v207, 0xffff0000, v170
	v_lshlrev_b32_e32 v170, 16, v171
	v_and_b32_e32 v171, 0xffff0000, v171
	v_pk_fma_f32 v[168:169], v[130:131], v[138:139], v[168:169]
	v_pk_fma_f32 v[204:205], v[128:129], v[136:137], v[204:205]
	v_pk_mul_f32 v[206:207], v[196:197], v[206:207]
	v_pk_mul_f32 v[170:171], v[194:195], v[170:171]
	v_mul_f32_e32 v208, v205, v205
	v_mul_f32_e32 v209, v169, v169
	v_pk_fma_f32 v[170:171], v[126:127], v[134:135], v[170:171]
	v_pk_fma_f32 v[206:207], v[124:125], v[132:133], v[206:207]
	v_fmac_f32_e32 v208, v204, v204
	v_fmac_f32_e32 v209, v168, v168
	v_add_f32_e32 v208, v208, v209
	v_mul_f32_e32 v209, v207, v207
	v_mul_f32_e32 v210, v171, v171
	v_fmac_f32_e32 v209, v206, v206
	v_fmac_f32_e32 v210, v170, v170
	v_add_f32_e32 v209, v209, v210
	v_add_f32_e32 v240, v208, v209
	v_pk_mul_f32 v[208:209], v[182:183], v[168:169]
	v_pk_mul_f32 v[168:169], v[184:185], v[204:205]
	v_pk_mul_f32 v[204:205], v[186:187], v[170:171]
	v_pk_mul_f32 v[170:171], v[188:189], v[206:207]
	v_cvt_pk_bf16_f32 v168, v168, v169
	v_cvt_pk_bf16_f32 v169, v208, v209
	v_cvt_pk_bf16_f32 v170, v170, v171
	v_cvt_pk_bf16_f32 v171, v204, v205
	global_store_dwordx4 v223, v[168:171], s[96:97]
	v_add_u32_e32 v206, 0x8000, v223
	s_waitcnt vmcnt(7)
	v_lshlrev_b32_e32 v168, 16, v164
	v_and_b32_e32 v169, 0xffff0000, v164
	v_lshlrev_b32_e32 v164, 16, v165
	v_and_b32_e32 v165, 0xffff0000, v165
	v_pk_mul_f32 v[168:169], v[192:193], v[168:169]
	v_pk_mul_f32 v[164:165], v[190:191], v[164:165]
	v_lshlrev_b32_e32 v170, 16, v166
	v_and_b32_e32 v171, 0xffff0000, v166
	v_lshlrev_b32_e32 v166, 16, v167
	v_and_b32_e32 v167, 0xffff0000, v167
	v_pk_fma_f32 v[164:165], v[122:123], v[138:139], v[164:165]
	v_pk_fma_f32 v[168:169], v[120:121], v[136:137], v[168:169]
	v_pk_mul_f32 v[170:171], v[196:197], v[170:171]
	v_pk_mul_f32 v[166:167], v[194:195], v[166:167]
	v_mul_f32_e32 v204, v169, v169
	v_mul_f32_e32 v205, v165, v165
	v_pk_fma_f32 v[166:167], v[118:119], v[134:135], v[166:167]
	v_pk_fma_f32 v[170:171], v[116:117], v[132:133], v[170:171]
	v_fmac_f32_e32 v204, v168, v168
	v_fmac_f32_e32 v205, v164, v164
	v_add_f32_e32 v204, v204, v205
	v_mul_f32_e32 v205, v171, v171
	v_mul_f32_e32 v207, v167, v167
	v_fmac_f32_e32 v205, v170, v170
	v_fmac_f32_e32 v207, v166, v166
	v_add_f32_e32 v205, v205, v207
	v_add_f32_e32 v239, v204, v205
	v_pk_mul_f32 v[204:205], v[182:183], v[164:165]
	v_pk_mul_f32 v[164:165], v[184:185], v[168:169]
	v_pk_mul_f32 v[168:169], v[186:187], v[166:167]
	v_pk_mul_f32 v[166:167], v[188:189], v[170:171]
	v_cvt_pk_bf16_f32 v164, v164, v165
	v_cvt_pk_bf16_f32 v165, v204, v205
	v_cvt_pk_bf16_f32 v166, v166, v167
	v_cvt_pk_bf16_f32 v167, v168, v169
	global_store_dwordx4 v206, v[164:167], s[96:97]
	v_add_u32_e32 v170, 0x10000, v223
	s_waitcnt vmcnt(6)
	v_lshlrev_b32_e32 v164, 16, v160
	v_and_b32_e32 v165, 0xffff0000, v160
	v_lshlrev_b32_e32 v160, 16, v161
	v_and_b32_e32 v161, 0xffff0000, v161
	v_pk_mul_f32 v[164:165], v[192:193], v[164:165]
	v_pk_mul_f32 v[160:161], v[190:191], v[160:161]
	v_lshlrev_b32_e32 v166, 16, v162
	v_and_b32_e32 v167, 0xffff0000, v162
	v_lshlrev_b32_e32 v162, 16, v163
	v_and_b32_e32 v163, 0xffff0000, v163
	v_pk_fma_f32 v[160:161], v[106:107], v[138:139], v[160:161]
	v_pk_fma_f32 v[164:165], v[104:105], v[136:137], v[164:165]
	v_pk_mul_f32 v[166:167], v[196:197], v[166:167]
	v_pk_mul_f32 v[162:163], v[194:195], v[162:163]
	v_mul_f32_e32 v168, v165, v165
	v_mul_f32_e32 v169, v161, v161
	v_pk_fma_f32 v[162:163], v[102:103], v[134:135], v[162:163]
	v_pk_fma_f32 v[166:167], v[100:101], v[132:133], v[166:167]
	v_fmac_f32_e32 v168, v164, v164
	v_fmac_f32_e32 v169, v160, v160
	v_add_f32_e32 v168, v168, v169
	v_mul_f32_e32 v169, v167, v167
	v_mul_f32_e32 v171, v163, v163
	v_fmac_f32_e32 v169, v166, v166
	v_fmac_f32_e32 v171, v162, v162
	v_add_f32_e32 v169, v169, v171
	v_add_f32_e32 v238, v168, v169
	v_pk_mul_f32 v[168:169], v[182:183], v[160:161]
	v_pk_mul_f32 v[160:161], v[184:185], v[164:165]
	v_pk_mul_f32 v[164:165], v[186:187], v[162:163]
	v_pk_mul_f32 v[162:163], v[188:189], v[166:167]
	v_cvt_pk_bf16_f32 v160, v160, v161
	v_cvt_pk_bf16_f32 v161, v168, v169
	v_cvt_pk_bf16_f32 v162, v162, v163
	v_cvt_pk_bf16_f32 v163, v164, v165
	global_store_dwordx4 v170, v[160:163], s[96:97]
	v_add_u32_e32 v166, 0x18000, v223
	s_waitcnt vmcnt(6)
	v_lshlrev_b32_e32 v160, 16, v156
	v_and_b32_e32 v161, 0xffff0000, v156
	v_lshlrev_b32_e32 v156, 16, v157
	v_and_b32_e32 v157, 0xffff0000, v157
	v_pk_mul_f32 v[160:161], v[192:193], v[160:161]
	v_pk_mul_f32 v[156:157], v[190:191], v[156:157]
	v_lshlrev_b32_e32 v162, 16, v158
	v_and_b32_e32 v163, 0xffff0000, v158
	v_lshlrev_b32_e32 v158, 16, v159
	v_and_b32_e32 v159, 0xffff0000, v159
	v_pk_fma_f32 v[156:157], v[88:89], v[138:139], v[156:157]
	v_pk_fma_f32 v[160:161], v[86:87], v[136:137], v[160:161]
	v_pk_mul_f32 v[162:163], v[196:197], v[162:163]
	v_pk_mul_f32 v[158:159], v[194:195], v[158:159]
	v_mul_f32_e32 v164, v161, v161
	v_mul_f32_e32 v165, v157, v157
	v_pk_fma_f32 v[158:159], v[84:85], v[134:135], v[158:159]
	v_pk_fma_f32 v[162:163], v[82:83], v[132:133], v[162:163]
	v_fmac_f32_e32 v164, v160, v160
	v_fmac_f32_e32 v165, v156, v156
	v_add_f32_e32 v164, v164, v165
	v_mul_f32_e32 v165, v163, v163
	v_mul_f32_e32 v167, v159, v159
	v_fmac_f32_e32 v165, v162, v162
	v_fmac_f32_e32 v167, v158, v158
	v_add_f32_e32 v165, v165, v167
	v_add_f32_e32 v237, v164, v165
	v_pk_mul_f32 v[164:165], v[182:183], v[156:157]
	v_pk_mul_f32 v[156:157], v[184:185], v[160:161]
	v_pk_mul_f32 v[160:161], v[186:187], v[158:159]
	v_pk_mul_f32 v[158:159], v[188:189], v[162:163]
	v_cvt_pk_bf16_f32 v156, v156, v157
	v_cvt_pk_bf16_f32 v157, v164, v165
	v_cvt_pk_bf16_f32 v158, v158, v159
	v_cvt_pk_bf16_f32 v159, v160, v161
	global_store_dwordx4 v166, v[156:159], s[96:97]
	v_add_u32_e32 v162, 0x40000, v223
	s_waitcnt vmcnt(6)
	v_lshlrev_b32_e32 v156, 16, v152
	v_and_b32_e32 v157, 0xffff0000, v152
	v_lshlrev_b32_e32 v152, 16, v153
	v_and_b32_e32 v153, 0xffff0000, v153
	v_pk_mul_f32 v[156:157], v[192:193], v[156:157]
	v_pk_mul_f32 v[152:153], v[190:191], v[152:153]
	v_lshlrev_b32_e32 v158, 16, v154
	v_and_b32_e32 v159, 0xffff0000, v154
	v_lshlrev_b32_e32 v154, 16, v155
	v_and_b32_e32 v155, 0xffff0000, v155
	v_pk_fma_f32 v[152:153], v[64:65], v[138:139], v[152:153]
	v_pk_fma_f32 v[156:157], v[62:63], v[136:137], v[156:157]
	v_pk_mul_f32 v[158:159], v[196:197], v[158:159]
	v_pk_mul_f32 v[154:155], v[194:195], v[154:155]
	v_mul_f32_e32 v160, v157, v157
	v_mul_f32_e32 v161, v153, v153
	v_pk_fma_f32 v[154:155], v[60:61], v[134:135], v[154:155]
	v_pk_fma_f32 v[158:159], v[58:59], v[132:133], v[158:159]
	v_fmac_f32_e32 v160, v156, v156
	v_fmac_f32_e32 v161, v152, v152
	v_add_f32_e32 v160, v160, v161
	v_mul_f32_e32 v161, v159, v159
	v_mul_f32_e32 v163, v155, v155
	v_fmac_f32_e32 v161, v158, v158
	v_fmac_f32_e32 v163, v154, v154
	v_add_f32_e32 v161, v161, v163
	v_add_f32_e32 v236, v160, v161
	v_pk_mul_f32 v[160:161], v[182:183], v[152:153]
	v_pk_mul_f32 v[152:153], v[184:185], v[156:157]
	v_pk_mul_f32 v[156:157], v[186:187], v[154:155]
	v_pk_mul_f32 v[154:155], v[188:189], v[158:159]
	v_cvt_pk_bf16_f32 v152, v152, v153
	v_cvt_pk_bf16_f32 v153, v160, v161
	v_cvt_pk_bf16_f32 v154, v154, v155
	v_cvt_pk_bf16_f32 v155, v156, v157
	global_store_dwordx4 v162, v[152:155], s[96:97]
	v_add_u32_e32 v158, 0x48000, v223
	v_or_b32_e32 v160, 0x80, v230
	s_waitcnt vmcnt(6)
	v_lshlrev_b32_e32 v152, 16, v148
	v_and_b32_e32 v153, 0xffff0000, v148
	v_lshlrev_b32_e32 v148, 16, v149
	v_and_b32_e32 v149, 0xffff0000, v149
	v_pk_mul_f32 v[152:153], v[192:193], v[152:153]
	v_pk_mul_f32 v[148:149], v[190:191], v[148:149]
	v_lshlrev_b32_e32 v154, 16, v150
	v_and_b32_e32 v155, 0xffff0000, v150
	v_lshlrev_b32_e32 v150, 16, v151
	v_and_b32_e32 v151, 0xffff0000, v151
	v_pk_fma_f32 v[148:149], v[56:57], v[138:139], v[148:149]
	v_pk_fma_f32 v[152:153], v[54:55], v[136:137], v[152:153]
	v_pk_mul_f32 v[154:155], v[196:197], v[154:155]
	v_pk_mul_f32 v[150:151], v[194:195], v[150:151]
	v_mul_f32_e32 v156, v153, v153
	v_mul_f32_e32 v157, v149, v149
	v_pk_fma_f32 v[150:151], v[52:53], v[134:135], v[150:151]
	v_pk_fma_f32 v[154:155], v[50:51], v[132:133], v[154:155]
	v_fmac_f32_e32 v156, v152, v152
	v_fmac_f32_e32 v157, v148, v148
	v_add_f32_e32 v156, v156, v157
	v_mul_f32_e32 v157, v155, v155
	v_mul_f32_e32 v159, v151, v151
	v_fmac_f32_e32 v157, v154, v154
	v_fmac_f32_e32 v159, v150, v150
	v_add_f32_e32 v157, v157, v159
	v_add_f32_e32 v235, v156, v157
	v_pk_mul_f32 v[156:157], v[182:183], v[148:149]
	v_pk_mul_f32 v[148:149], v[184:185], v[152:153]
	v_pk_mul_f32 v[152:153], v[186:187], v[150:151]
	v_pk_mul_f32 v[150:151], v[188:189], v[154:155]
	v_cvt_pk_bf16_f32 v148, v148, v149
	v_cvt_pk_bf16_f32 v149, v156, v157
	v_cvt_pk_bf16_f32 v150, v150, v151
	v_cvt_pk_bf16_f32 v151, v152, v153
	global_store_dwordx4 v158, v[148:151], s[96:97]
	v_add_u32_e32 v154, 0x50000, v223
	v_lshlrev_b32_e32 v161, 2, v160
	s_waitcnt vmcnt(6)
	v_lshlrev_b32_e32 v148, 16, v140
	v_and_b32_e32 v149, 0xffff0000, v140
	v_lshlrev_b32_e32 v140, 16, v141
	v_and_b32_e32 v141, 0xffff0000, v141
	v_pk_mul_f32 v[148:149], v[192:193], v[148:149]
	v_pk_mul_f32 v[140:141], v[190:191], v[140:141]
	v_lshlrev_b32_e32 v150, 16, v142
	v_and_b32_e32 v151, 0xffff0000, v142
	v_lshlrev_b32_e32 v142, 16, v143
	v_and_b32_e32 v143, 0xffff0000, v143
	v_pk_fma_f32 v[140:141], v[40:41], v[138:139], v[140:141]
	v_pk_fma_f32 v[148:149], v[38:39], v[136:137], v[148:149]
	v_pk_mul_f32 v[150:151], v[196:197], v[150:151]
	v_pk_mul_f32 v[142:143], v[194:195], v[142:143]
	v_mul_f32_e32 v152, v149, v149
	v_mul_f32_e32 v153, v141, v141
	v_pk_fma_f32 v[142:143], v[36:37], v[134:135], v[142:143]
	v_pk_fma_f32 v[150:151], v[34:35], v[132:133], v[150:151]
	v_fmac_f32_e32 v152, v148, v148
	v_fmac_f32_e32 v153, v140, v140
	v_add_f32_e32 v152, v152, v153
	v_mul_f32_e32 v153, v151, v151
	v_mul_f32_e32 v155, v143, v143
	v_fmac_f32_e32 v153, v150, v150
	v_fmac_f32_e32 v155, v142, v142
	v_add_f32_e32 v153, v153, v155
	v_add_f32_e32 v234, v152, v153
	v_pk_mul_f32 v[152:153], v[182:183], v[140:141]
	v_pk_mul_f32 v[140:141], v[184:185], v[148:149]
	v_pk_mul_f32 v[148:149], v[186:187], v[142:143]
	v_pk_mul_f32 v[142:143], v[188:189], v[150:151]
	v_cvt_pk_bf16_f32 v140, v140, v141
	v_cvt_pk_bf16_f32 v141, v152, v153
	v_cvt_pk_bf16_f32 v142, v142, v143
	v_cvt_pk_bf16_f32 v143, v148, v149
	global_store_dwordx4 v154, v[140:143], s[96:97]
	v_add_u32_e32 v148, 0x58000, v223
	v_add_lshl_u32 v152, v160, s53, 2
	v_lshlrev_b32_e32 v140, 16, v144
	v_and_b32_e32 v141, 0xffff0000, v144
	v_lshlrev_b32_e32 v142, 16, v145
	v_and_b32_e32 v143, 0xffff0000, v145
	v_pk_mul_f32 v[140:141], v[192:193], v[140:141]
	v_pk_mul_f32 v[142:143], v[190:191], v[142:143]
	v_lshlrev_b32_e32 v144, 16, v146
	v_and_b32_e32 v145, 0xffff0000, v146
	v_lshlrev_b32_e32 v146, 16, v147
	v_and_b32_e32 v147, 0xffff0000, v147
	v_pk_fma_f32 v[138:139], v[24:25], v[138:139], v[142:143]
	v_pk_fma_f32 v[136:137], v[22:23], v[136:137], v[140:141]
	v_pk_mul_f32 v[144:145], v[196:197], v[144:145]
	v_pk_mul_f32 v[146:147], v[194:195], v[146:147]
	v_mul_f32_e32 v140, v137, v137
	v_mul_f32_e32 v141, v139, v139
	v_pk_fma_f32 v[134:135], v[20:21], v[134:135], v[146:147]
	v_pk_fma_f32 v[132:133], v[18:19], v[132:133], v[144:145]
	v_fmac_f32_e32 v140, v136, v136
	v_fmac_f32_e32 v141, v138, v138
	v_add_f32_e32 v140, v140, v141
	v_mul_f32_e32 v141, v133, v133
	v_mul_f32_e32 v142, v135, v135
	v_fmac_f32_e32 v141, v132, v132
	v_fmac_f32_e32 v142, v134, v134
	v_add_f32_e32 v141, v141, v142
	v_add_f32_e32 v190, v140, v141
	v_pk_mul_f32 v[138:139], v[182:183], v[138:139]
	v_pk_mul_f32 v[136:137], v[184:185], v[136:137]
	v_pk_mul_f32 v[140:141], v[186:187], v[134:135]
	v_pk_mul_f32 v[134:135], v[188:189], v[132:133]
	v_cvt_pk_bf16_f32 v132, v136, v137
	v_cvt_pk_bf16_f32 v133, v138, v139
	v_cvt_pk_bf16_f32 v134, v134, v135
	v_cvt_pk_bf16_f32 v135, v140, v141
	global_store_dwordx4 v148, v[132:135], s[96:97]
	global_load_dwordx4 v[132:135], v161, s[50:51] offset:16
	global_load_dwordx4 v[136:139], v161, s[50:51]
	global_load_dwordx4 v[140:143], v161, s[38:39] offset:16
	global_load_dwordx4 v[144:147], v161, s[38:39]
	global_load_dwordx4 v[148:151], v152, s[26:27] offset:16
	s_nop 0
	global_load_dwordx4 v[152:155], v152, s[26:27]
	v_add_lshl_u32 v160, v160, s52, 2
	v_or_b32_e32 v191, 0x100, v223
	s_lshl_b32 s50, s49, 4
	s_or_b32 s52, s50, s14
	s_waitcnt vmcnt(1)
	v_pk_add_f32 v[150:151], v[150:151], 1.0 op_sel_hi:[1,0]
	s_waitcnt vmcnt(0)
	v_pk_add_f32 v[154:155], v[154:155], 1.0 op_sel_hi:[1,0]
	v_pk_add_f32 v[152:153], v[152:153], 1.0 op_sel_hi:[1,0]
	v_pk_mul_f32 v[156:157], v[146:147], v[154:155]
	v_pk_mul_f32 v[158:159], v[144:145], v[152:153]
	global_load_dwordx4 v[144:147], v161, s[0:1] offset:16
	global_load_dwordx4 v[152:155], v161, s[0:1]
	global_load_dwordx4 v[168:171], v160, s[56:57] offset:16
	s_nop 0
	global_load_dwordx4 v[160:163], v160, s[56:57]
	v_pk_add_f32 v[148:149], v[148:149], 1.0 op_sel_hi:[1,0]
	s_waitcnt vmcnt(0)
	v_pk_add_f32 v[162:163], v[162:163], 1.0 op_sel_hi:[1,0]
	v_pk_add_f32 v[160:161], v[160:161], 1.0 op_sel_hi:[1,0]
	v_pk_mul_f32 v[154:155], v[154:155], v[162:163]
	v_pk_mul_f32 v[152:153], v[152:153], v[160:161]
	v_pk_mul_f32 v[160:161], v[142:143], v[150:151]
	v_pk_mul_f32 v[162:163], v[140:141], v[148:149]
	v_pk_add_f32 v[140:141], v[170:171], 1.0 op_sel_hi:[1,0]
	v_pk_add_f32 v[142:143], v[168:169], 1.0 op_sel_hi:[1,0]
	v_pk_mul_f32 v[168:169], v[146:147], v[140:141]
	v_pk_mul_f32 v[140:141], v[144:145], v[142:143]
	v_rcp_f32_e32 v166, v152
	v_rcp_f32_e32 v170, v140
	v_or_b32_e32 v140, 0x100, v224
	v_rcp_f32_e32 v171, v141
	v_add_u32_e32 v141, v140, v231
	global_load_dwordx4 v[182:185], v141, s[96:97] nt
	v_add_u32_e32 v141, v140, v232
	global_load_dwordx4 v[186:189], v141, s[96:97] nt
	v_add_u32_e32 v141, v140, v225
	global_load_dwordx4 v[192:195], v141, s[96:97] nt
	v_add_u32_e32 v141, v140, v226
	global_load_dwordx4 v[204:207], v141, s[96:97] nt
	v_add_u32_e32 v141, v140, v227
	v_rcp_f32_e32 v167, v153
	v_rcp_f32_e32 v164, v154
	v_rcp_f32_e32 v165, v155
	global_load_dwordx4 v[152:155], v141, s[96:97] nt
	v_add_u32_e32 v141, v140, v228
	global_load_dwordx4 v[148:151], v141, s[96:97] nt
	v_add_u32_e32 v141, v140, v229
	global_load_dwordx4 v[144:147], v141, s[96:97] nt
	v_add_u32_e32 v140, v140, v233
	global_load_dwordx4 v[140:143], v140, s[96:97] nt
	v_rcp_f32_e32 v168, v168
	v_rcp_f32_e32 v169, v169
	s_waitcnt vmcnt(7)
	v_lshlrev_b32_e32 v196, 16, v182
	v_and_b32_e32 v197, 0xffff0000, v182
	v_lshlrev_b32_e32 v182, 16, v183
	v_and_b32_e32 v183, 0xffff0000, v183
	v_pk_mul_f32 v[196:197], v[166:167], v[196:197]
	v_pk_mul_f32 v[182:183], v[164:165], v[182:183]
	v_lshlrev_b32_e32 v208, 16, v184
	v_and_b32_e32 v209, 0xffff0000, v184
	v_lshlrev_b32_e32 v184, 16, v185
	v_and_b32_e32 v185, 0xffff0000, v185
	v_pk_fma_f32 v[182:183], v[114:115], v[138:139], v[182:183]
	v_pk_fma_f32 v[196:197], v[112:113], v[136:137], v[196:197]
	v_pk_mul_f32 v[208:209], v[170:171], v[208:209]
	v_pk_mul_f32 v[184:185], v[168:169], v[184:185]
	v_mul_f32_e32 v210, v197, v197
	v_mul_f32_e32 v211, v183, v183
	v_pk_fma_f32 v[184:185], v[110:111], v[134:135], v[184:185]
	v_pk_fma_f32 v[208:209], v[108:109], v[132:133], v[208:209]
	v_fmac_f32_e32 v210, v196, v196
	v_fmac_f32_e32 v211, v182, v182
	v_add_f32_e32 v210, v210, v211
	v_mul_f32_e32 v211, v209, v209
	v_mul_f32_e32 v224, v185, v185
	v_fmac_f32_e32 v211, v208, v208
	v_fmac_f32_e32 v224, v184, v184
	v_add_f32_e32 v211, v211, v224
	v_add_f32_e32 v210, v210, v211
	v_add_f32_e32 v224, v240, v210
	v_pk_mul_f32 v[210:211], v[156:157], v[182:183]
	v_pk_mul_f32 v[182:183], v[158:159], v[196:197]
	v_pk_mul_f32 v[196:197], v[160:161], v[184:185]
	v_pk_mul_f32 v[184:185], v[162:163], v[208:209]
	v_cvt_pk_bf16_f32 v182, v182, v183
	v_cvt_pk_bf16_f32 v183, v210, v211
	v_cvt_pk_bf16_f32 v184, v184, v185
	v_cvt_pk_bf16_f32 v185, v196, v197
	global_store_dwordx4 v191, v[182:185], s[96:97]
	v_add_u32_e32 v191, 0x8100, v223
	s_waitcnt vmcnt(7)
	v_lshlrev_b32_e32 v182, 16, v186
	v_and_b32_e32 v183, 0xffff0000, v186
	v_lshlrev_b32_e32 v184, 16, v187
	v_and_b32_e32 v185, 0xffff0000, v187
	v_pk_mul_f32 v[182:183], v[166:167], v[182:183]
	v_pk_mul_f32 v[184:185], v[164:165], v[184:185]
	v_lshlrev_b32_e32 v186, 16, v188
	v_and_b32_e32 v187, 0xffff0000, v188
	v_lshlrev_b32_e32 v188, 16, v189
	v_and_b32_e32 v189, 0xffff0000, v189
	v_pk_fma_f32 v[184:185], v[96:97], v[138:139], v[184:185]
	v_pk_fma_f32 v[196:197], v[94:95], v[136:137], v[182:183]
	v_pk_mul_f32 v[186:187], v[170:171], v[186:187]
	v_pk_mul_f32 v[188:189], v[168:169], v[188:189]
	v_mul_f32_e32 v182, v197, v197
	v_mul_f32_e32 v183, v185, v185
	v_pk_fma_f32 v[188:189], v[92:93], v[134:135], v[188:189]
	v_pk_fma_f32 v[186:187], v[90:91], v[132:133], v[186:187]
	v_fmac_f32_e32 v182, v196, v196
	v_fmac_f32_e32 v183, v184, v184
	v_add_f32_e32 v182, v182, v183
	v_mul_f32_e32 v183, v187, v187
	v_mul_f32_e32 v208, v189, v189
	v_fmac_f32_e32 v183, v186, v186
	v_fmac_f32_e32 v208, v188, v188
	v_add_f32_e32 v183, v183, v208
	v_add_f32_e32 v182, v182, v183
	v_pk_mul_f32 v[208:209], v[156:157], v[184:185]
	v_pk_mul_f32 v[184:185], v[158:159], v[196:197]
	v_pk_mul_f32 v[188:189], v[160:161], v[188:189]
	v_pk_mul_f32 v[186:187], v[162:163], v[186:187]
	v_add_f32_e32 v182, v239, v182
	v_cvt_pk_bf16_f32 v184, v184, v185
	v_cvt_pk_bf16_f32 v185, v208, v209
	v_cvt_pk_bf16_f32 v186, v186, v187
	v_cvt_pk_bf16_f32 v187, v188, v189
	global_store_dwordx4 v191, v[184:187], s[96:97]
	s_waitcnt vmcnt(7)
	v_lshlrev_b32_e32 v188, 16, v194
	v_and_b32_e32 v189, 0xffff0000, v194
	v_lshlrev_b32_e32 v184, 16, v192
	v_and_b32_e32 v185, 0xffff0000, v192
	v_lshlrev_b32_e32 v186, 16, v193
	v_and_b32_e32 v187, 0xffff0000, v193
	v_pk_mul_f32 v[184:185], v[166:167], v[184:185]
	v_pk_mul_f32 v[186:187], v[164:165], v[186:187]
	v_lshlrev_b32_e32 v192, 16, v195
	v_and_b32_e32 v193, 0xffff0000, v195
	v_pk_fma_f32 v[186:187], v[80:81], v[138:139], v[186:187]
	v_pk_fma_f32 v[184:185], v[78:79], v[136:137], v[184:185]
	v_pk_mul_f32 v[188:189], v[170:171], v[188:189]
	v_pk_mul_f32 v[192:193], v[168:169], v[192:193]
	v_mul_f32_e32 v183, v185, v185
	v_mul_f32_e32 v194, v187, v187
	v_pk_fma_f32 v[192:193], v[76:77], v[134:135], v[192:193]
	v_pk_fma_f32 v[188:189], v[74:75], v[132:133], v[188:189]
	v_fmac_f32_e32 v183, v184, v184
	v_fmac_f32_e32 v194, v186, v186
	v_add_f32_e32 v183, v183, v194
	v_mul_f32_e32 v194, v189, v189
	v_mul_f32_e32 v195, v193, v193
	v_fmac_f32_e32 v194, v188, v188
	v_fmac_f32_e32 v195, v192, v192
	v_add_f32_e32 v194, v194, v195
	v_add_f32_e32 v183, v183, v194
	v_pk_mul_f32 v[186:187], v[156:157], v[186:187]
	v_pk_mul_f32 v[184:185], v[158:159], v[184:185]
	v_pk_mul_f32 v[192:193], v[160:161], v[192:193]
	v_pk_mul_f32 v[188:189], v[162:163], v[188:189]
	v_add_u32_e32 v191, 0x10100, v223
	v_add_f32_e32 v183, v238, v183
	v_cvt_pk_bf16_f32 v184, v184, v185
	v_cvt_pk_bf16_f32 v185, v186, v187
	v_cvt_pk_bf16_f32 v186, v188, v189
	v_cvt_pk_bf16_f32 v187, v192, v193
	global_store_dwordx4 v191, v[184:187], s[96:97]
	s_waitcnt vmcnt(7)
	v_lshlrev_b32_e32 v188, 16, v206
	v_and_b32_e32 v189, 0xffff0000, v206
	v_lshlrev_b32_e32 v184, 16, v204
	v_and_b32_e32 v185, 0xffff0000, v204
	v_lshlrev_b32_e32 v186, 16, v205
	v_and_b32_e32 v187, 0xffff0000, v205
	v_pk_mul_f32 v[184:185], v[166:167], v[184:185]
	v_pk_mul_f32 v[186:187], v[164:165], v[186:187]
	v_lshlrev_b32_e32 v192, 16, v207
	v_and_b32_e32 v193, 0xffff0000, v207
	v_pk_fma_f32 v[186:187], v[72:73], v[138:139], v[186:187]
	v_pk_fma_f32 v[194:195], v[70:71], v[136:137], v[184:185]
	v_pk_mul_f32 v[188:189], v[170:171], v[188:189]
	v_pk_mul_f32 v[192:193], v[168:169], v[192:193]
	v_mul_f32_e32 v184, v195, v195
	v_mul_f32_e32 v185, v187, v187
	v_pk_fma_f32 v[192:193], v[68:69], v[134:135], v[192:193]
	v_pk_fma_f32 v[188:189], v[66:67], v[132:133], v[188:189]
	v_fmac_f32_e32 v184, v194, v194
	v_fmac_f32_e32 v185, v186, v186
	v_add_f32_e32 v184, v184, v185
	v_mul_f32_e32 v185, v189, v189
	v_mul_f32_e32 v196, v193, v193
	v_fmac_f32_e32 v185, v188, v188
	v_fmac_f32_e32 v196, v192, v192
	v_add_f32_e32 v185, v185, v196
	v_add_f32_e32 v184, v184, v185
	v_pk_mul_f32 v[196:197], v[156:157], v[186:187]
	v_pk_mul_f32 v[186:187], v[158:159], v[194:195]
	v_pk_mul_f32 v[192:193], v[160:161], v[192:193]
	v_pk_mul_f32 v[188:189], v[162:163], v[188:189]
	v_add_u32_e32 v191, 0x18100, v223
	v_add_f32_e32 v184, v237, v184
	v_cvt_pk_bf16_f32 v186, v186, v187
	v_cvt_pk_bf16_f32 v187, v196, v197
	v_cvt_pk_bf16_f32 v188, v188, v189
	v_cvt_pk_bf16_f32 v189, v192, v193
	global_store_dwordx4 v191, v[186:189], s[96:97]
	v_add_u32_e32 v185, 0x40100, v223
	s_waitcnt vmcnt(7)
	v_lshlrev_b32_e32 v186, 16, v152
	v_and_b32_e32 v187, 0xffff0000, v152
	v_lshlrev_b32_e32 v152, 16, v153
	v_and_b32_e32 v153, 0xffff0000, v153
	v_pk_mul_f32 v[186:187], v[166:167], v[186:187]
	v_pk_mul_f32 v[152:153], v[164:165], v[152:153]
	v_lshlrev_b32_e32 v188, 16, v154
	v_and_b32_e32 v189, 0xffff0000, v154
	v_lshlrev_b32_e32 v154, 16, v155
	v_and_b32_e32 v155, 0xffff0000, v155
	v_pk_fma_f32 v[192:193], v[48:49], v[138:139], v[152:153]
	v_pk_fma_f32 v[186:187], v[46:47], v[136:137], v[186:187]
	v_pk_mul_f32 v[188:189], v[170:171], v[188:189]
	v_pk_mul_f32 v[154:155], v[168:169], v[154:155]
	v_mul_f32_e32 v152, v187, v187
	v_mul_f32_e32 v153, v193, v193
	v_pk_fma_f32 v[154:155], v[44:45], v[134:135], v[154:155]
	v_pk_fma_f32 v[188:189], v[42:43], v[132:133], v[188:189]
	v_fmac_f32_e32 v152, v186, v186
	v_fmac_f32_e32 v153, v192, v192
	v_add_f32_e32 v152, v152, v153
	v_mul_f32_e32 v153, v189, v189
	v_mul_f32_e32 v191, v155, v155
	v_fmac_f32_e32 v153, v188, v188
	v_fmac_f32_e32 v191, v154, v154
	v_add_f32_e32 v153, v153, v191
	v_pk_mul_f32 v[154:155], v[160:161], v[154:155]
	v_pk_mul_f32 v[188:189], v[162:163], v[188:189]
	v_add_f32_e32 v152, v152, v153
	v_pk_mul_f32 v[192:193], v[156:157], v[192:193]
	v_pk_mul_f32 v[186:187], v[158:159], v[186:187]
	v_cvt_pk_bf16_f32 v188, v188, v189
	v_cvt_pk_bf16_f32 v189, v154, v155
	s_waitcnt vmcnt(6)
	v_lshlrev_b32_e32 v154, 16, v148
	v_and_b32_e32 v155, 0xffff0000, v148
	v_lshlrev_b32_e32 v148, 16, v149
	v_and_b32_e32 v149, 0xffff0000, v149
	v_add_f32_e32 v152, v236, v152
	v_cvt_pk_bf16_f32 v186, v186, v187
	v_cvt_pk_bf16_f32 v187, v192, v193
	v_pk_mul_f32 v[154:155], v[166:167], v[154:155]
	v_pk_mul_f32 v[148:149], v[164:165], v[148:149]
	global_store_dwordx4 v185, v[186:189], s[96:97]
	v_pk_fma_f32 v[154:155], v[30:31], v[136:137], v[154:155]
	v_add_u32_e32 v153, 0x48100, v223
	v_lshlrev_b32_e32 v186, 16, v150
	v_and_b32_e32 v187, 0xffff0000, v150
	v_lshlrev_b32_e32 v150, 16, v151
	v_and_b32_e32 v151, 0xffff0000, v151
	v_pk_fma_f32 v[188:189], v[32:33], v[138:139], v[148:149]
	v_pk_mul_f32 v[186:187], v[170:171], v[186:187]
	v_pk_mul_f32 v[150:151], v[168:169], v[150:151]
	v_mul_f32_e32 v148, v155, v155
	v_mul_f32_e32 v149, v189, v189
	v_pk_fma_f32 v[150:151], v[28:29], v[134:135], v[150:151]
	v_pk_fma_f32 v[186:187], v[26:27], v[132:133], v[186:187]
	v_fmac_f32_e32 v148, v154, v154
	v_fmac_f32_e32 v149, v188, v188
	v_add_f32_e32 v148, v148, v149
	v_mul_f32_e32 v149, v187, v187
	v_mul_f32_e32 v185, v151, v151
	v_fmac_f32_e32 v149, v186, v186
	v_fmac_f32_e32 v185, v150, v150
	v_pk_mul_f32 v[154:155], v[158:159], v[154:155]
	v_add_f32_e32 v149, v149, v185
	v_pk_mul_f32 v[188:189], v[156:157], v[188:189]
	v_pk_mul_f32 v[150:151], v[160:161], v[150:151]
	v_pk_mul_f32 v[192:193], v[162:163], v[186:187]
	v_cvt_pk_bf16_f32 v186, v154, v155
	s_waitcnt vmcnt(6)
	v_lshlrev_b32_e32 v154, 16, v146
	v_and_b32_e32 v155, 0xffff0000, v146
	v_lshlrev_b32_e32 v146, 16, v147
	v_and_b32_e32 v147, 0xffff0000, v147
	v_add_f32_e32 v148, v148, v149
	v_cvt_pk_bf16_f32 v187, v188, v189
	v_cvt_pk_bf16_f32 v189, v150, v151
	v_lshlrev_b32_e32 v150, 16, v144
	v_and_b32_e32 v151, 0xffff0000, v144
	v_lshlrev_b32_e32 v144, 16, v145
	v_and_b32_e32 v145, 0xffff0000, v145
	v_pk_mul_f32 v[146:147], v[168:169], v[146:147]
	v_add_f32_e32 v148, v235, v148
	v_cvt_pk_bf16_f32 v188, v192, v193
	v_pk_mul_f32 v[150:151], v[166:167], v[150:151]
	v_pk_mul_f32 v[144:145], v[164:165], v[144:145]
	v_pk_fma_f32 v[146:147], v[12:13], v[134:135], v[146:147]
	global_store_dwordx4 v153, v[186:189], s[96:97]
	v_pk_fma_f32 v[150:151], v[14:15], v[136:137], v[150:151]
	v_mul_f32_e32 v153, v147, v147
	v_pk_fma_f32 v[186:187], v[16:17], v[138:139], v[144:145]
	v_mul_f32_e32 v144, v151, v151
	v_fmac_f32_e32 v153, v146, v146
	v_pk_mul_f32 v[188:189], v[156:157], v[186:187]
	v_pk_mul_f32 v[146:147], v[160:161], v[146:147]
	v_fmac_f32_e32 v144, v150, v150
	v_mul_f32_e32 v145, v187, v187
	v_pk_mul_f32 v[150:151], v[158:159], v[150:151]
	v_cvt_pk_bf16_f32 v187, v188, v189
	v_cvt_pk_bf16_f32 v189, v146, v147
	s_waitcnt vmcnt(6)
	v_lshlrev_b32_e32 v146, 16, v140
	v_and_b32_e32 v147, 0xffff0000, v140
	v_lshlrev_b32_e32 v140, 16, v141
	v_and_b32_e32 v141, 0xffff0000, v141
	v_fmac_f32_e32 v145, v186, v186
	v_cvt_pk_bf16_f32 v186, v150, v151
	v_lshlrev_b32_e32 v150, 16, v142
	v_and_b32_e32 v151, 0xffff0000, v142
	v_pk_mul_f32 v[146:147], v[166:167], v[146:147]
	v_pk_mul_f32 v[140:141], v[164:165], v[140:141]
	v_pk_mul_f32 v[154:155], v[170:171], v[154:155]
	v_lshlrev_b32_e32 v142, 16, v143
	v_and_b32_e32 v143, 0xffff0000, v143
	v_pk_mul_f32 v[150:151], v[170:171], v[150:151]
	v_pk_fma_f32 v[138:139], v[8:9], v[138:139], v[140:141]
	v_pk_fma_f32 v[136:137], v[6:7], v[136:137], v[146:147]
	v_pk_fma_f32 v[154:155], v[10:11], v[132:133], v[154:155]
	v_pk_mul_f32 v[142:143], v[168:169], v[142:143]
	v_pk_fma_f32 v[140:141], v[2:3], v[132:133], v[150:151]
	v_mul_f32_e32 v132, v137, v137
	v_mul_f32_e32 v133, v139, v139
	v_pk_fma_f32 v[134:135], v[4:5], v[134:135], v[142:143]
	v_fmac_f32_e32 v132, v136, v136
	v_fmac_f32_e32 v133, v138, v138
	v_add_f32_e32 v144, v144, v145
	v_mul_f32_e32 v145, v155, v155
	v_add_f32_e32 v132, v132, v133
	v_mul_f32_e32 v133, v141, v141
	v_mul_f32_e32 v142, v135, v135
	v_fmac_f32_e32 v145, v154, v154
	v_fmac_f32_e32 v133, v140, v140
	v_fmac_f32_e32 v142, v134, v134
	v_add_f32_e32 v145, v145, v153
	v_add_f32_e32 v133, v133, v142
	v_add_f32_e32 v144, v144, v145
	v_pk_mul_f32 v[154:155], v[162:163], v[154:155]
	v_add_f32_e32 v132, v132, v133
	v_pk_mul_f32 v[138:139], v[156:157], v[138:139]
	v_pk_mul_f32 v[136:137], v[158:159], v[136:137]
	v_pk_mul_f32 v[142:143], v[160:161], v[134:135]
	v_pk_mul_f32 v[140:141], v[162:163], v[140:141]
	v_add_u32_e32 v149, 0x50100, v223
	v_add_f32_e32 v144, v234, v144
	v_cvt_pk_bf16_f32 v188, v154, v155
	v_add_u32_e32 v145, 0x58100, v223
	v_add_f32_e32 v132, v190, v132
	v_cvt_pk_bf16_f32 v134, v136, v137
	v_cvt_pk_bf16_f32 v135, v138, v139
	v_cvt_pk_bf16_f32 v136, v140, v141
	v_cvt_pk_bf16_f32 v137, v142, v143
	global_store_dwordx4 v149, v[186:189], s[96:97]
	global_store_dwordx4 v145, v[134:137], s[96:97]
	v_xor_b32_e32 v133, 16, v1
	s_nop 0
	v_and_b32_e32 v134, 64, v1
	v_add_u32_e32 v134, 64, v134
	v_cmp_lt_i32_e32 vcc, v133, v134
	v_xor_b32_e32 v135, 32, v1
	s_nop 0
	v_cndmask_b32_e32 v133, v1, v133, vcc
	v_lshlrev_b32_e32 v133, 2, v133
	v_cmp_lt_i32_e32 vcc, v135, v134
	s_nop 1
	v_cndmask_b32_e32 v134, v1, v135, vcc
	v_mov_b32_e32 v135, v224
	s_nop 1
	v_permlane16_swap_b32_e32 v224, v135
	v_lshlrev_b32_e32 v134, 2, v134
	v_cmp_eq_u32_e32 vcc, 0, v213
	s_waitcnt lgkmcnt(0)
	v_add_f32_e32 v135, v224, v135
	v_mov_b32_e32 v136, v135
	s_nop 1
	v_permlane32_swap_b32_e32 v135, v136
	s_and_saveexec_b64 s[50:51], vcc
	s_cbranch_execz .LBB0_1559
	v_readlane_b32 s54, v251, 32
	s_waitcnt lgkmcnt(0)
	v_add_f32_e32 v135, v135, v136
	v_lshl_add_u32 v136, v215, 6, s52
	v_readlane_b32 s55, v251, 33
	s_nop 4
	global_store_dword v136, v135, s[54:55]
.LBB0_1559:
	s_or_b64 exec, exec, s[50:51]
	v_mov_b32_e32 v135, v182
	s_nop 1
	v_permlane16_swap_b32_e32 v182, v135
	s_waitcnt lgkmcnt(0)
	v_add_f32_e32 v135, v182, v135
	v_mov_b32_e32 v136, v135
	s_nop 1
	v_permlane32_swap_b32_e32 v135, v136
	s_and_saveexec_b64 s[50:51], vcc
	s_cbranch_execz .LBB0_1561
	v_readlane_b32 s54, v251, 32
	s_waitcnt lgkmcnt(0)
	v_add_f32_e32 v135, v135, v136
	v_lshl_add_u32 v136, v216, 6, s52
	v_readlane_b32 s55, v251, 33
	s_nop 4
	global_store_dword v136, v135, s[54:55]
.LBB0_1561:
	s_or_b64 exec, exec, s[50:51]
	v_mov_b32_e32 v135, v183
	s_nop 1
	v_permlane16_swap_b32_e32 v183, v135
	s_waitcnt lgkmcnt(0)
	v_add_f32_e32 v135, v183, v135
	v_mov_b32_e32 v136, v135
	s_nop 1
	v_permlane32_swap_b32_e32 v135, v136
	s_and_saveexec_b64 s[50:51], vcc
	s_cbranch_execz .LBB0_1563
	v_readlane_b32 s54, v251, 32
	s_waitcnt lgkmcnt(0)
	v_add_f32_e32 v135, v135, v136
	v_lshl_add_u32 v136, v217, 6, s52
	v_readlane_b32 s55, v251, 33
	s_nop 4
	global_store_dword v136, v135, s[54:55]
.LBB0_1563:
	s_or_b64 exec, exec, s[50:51]
	v_mov_b32_e32 v135, v184
	s_nop 1
	v_permlane16_swap_b32_e32 v184, v135
	s_waitcnt lgkmcnt(0)
	v_add_f32_e32 v135, v184, v135
	v_mov_b32_e32 v136, v135
	s_nop 1
	v_permlane32_swap_b32_e32 v135, v136
	s_and_saveexec_b64 s[50:51], vcc
	s_cbranch_execz .LBB0_1565
	v_readlane_b32 s54, v251, 32
	s_waitcnt lgkmcnt(0)
	v_add_f32_e32 v135, v135, v136
	v_lshl_add_u32 v136, v218, 6, s52
	v_readlane_b32 s55, v251, 33
	s_nop 4
	global_store_dword v136, v135, s[54:55]
.LBB0_1565:
	s_or_b64 exec, exec, s[50:51]
	v_mov_b32_e32 v135, v152
	s_nop 1
	v_permlane16_swap_b32_e32 v152, v135
	s_waitcnt lgkmcnt(0)
	v_add_f32_e32 v135, v152, v135
	v_mov_b32_e32 v136, v135
	s_nop 1
	v_permlane32_swap_b32_e32 v135, v136
	s_and_saveexec_b64 s[50:51], vcc
	s_cbranch_execz .LBB0_1567
	v_readlane_b32 s54, v251, 32
	s_waitcnt lgkmcnt(0)
	v_add_f32_e32 v135, v135, v136
	v_lshl_add_u32 v136, v219, 6, s52
	v_readlane_b32 s55, v251, 33
	s_nop 4
	global_store_dword v136, v135, s[54:55]
.LBB0_1567:
	s_or_b64 exec, exec, s[50:51]
	v_mov_b32_e32 v135, v148
	s_nop 1
	v_permlane16_swap_b32_e32 v148, v135
	s_waitcnt lgkmcnt(0)
	v_add_f32_e32 v135, v148, v135
	v_mov_b32_e32 v136, v135
	s_nop 1
	v_permlane32_swap_b32_e32 v135, v136
	s_and_saveexec_b64 s[50:51], vcc
	s_cbranch_execz .LBB0_1569
	v_readlane_b32 s54, v251, 32
	s_waitcnt lgkmcnt(0)
	v_add_f32_e32 v135, v135, v136
	v_lshl_add_u32 v136, v220, 6, s52
	v_readlane_b32 s55, v251, 33
	s_nop 4
	global_store_dword v136, v135, s[54:55]
.LBB0_1569:
	s_or_b64 exec, exec, s[50:51]
	v_mov_b32_e32 v135, v144
	s_nop 1
	v_permlane16_swap_b32_e32 v144, v135
	s_waitcnt lgkmcnt(0)
	v_add_f32_e32 v135, v144, v135
	v_mov_b32_e32 v136, v135
	s_nop 1
	v_permlane32_swap_b32_e32 v135, v136
	s_and_saveexec_b64 s[50:51], vcc
	s_cbranch_execz .LBB0_1571
	v_readlane_b32 s54, v251, 32
	s_waitcnt lgkmcnt(0)
	v_add_f32_e32 v135, v135, v136
	v_lshl_add_u32 v136, v221, 6, s52
	v_readlane_b32 s55, v251, 33
	s_nop 4
	global_store_dword v136, v135, s[54:55]
.LBB0_1571:
	s_or_b64 exec, exec, s[50:51]
	v_mov_b32_e32 v133, v132
	s_nop 1
	v_permlane16_swap_b32_e32 v132, v133
	s_waitcnt lgkmcnt(0)
	v_add_f32_e32 v132, v132, v133
	v_mov_b32_e32 v133, v132
	s_nop 1
	v_permlane32_swap_b32_e32 v132, v133
	s_and_saveexec_b64 s[50:51], vcc
	s_cbranch_execz .LBB0_1573
	s_waitcnt lgkmcnt(0)
	v_add_f32_e32 v132, v132, v133
	v_lshl_add_u32 v133, v222, 6, s52
	v_readlane_b32 s52, v251, 32
	v_readlane_b32 s53, v251, 33
	s_nop 4
	global_store_dword v133, v132, s[52:53]

.LBB0_1638:
	s_waitcnt lgkmcnt(0)
	v_lshl_add_u64 v[2:3], s[86:87], 0, v[42:43]
	v_add_co_u32_e32 v46, vcc, 0x4d00000, v2
	v_lshl_add_u64 v[4:5], s[86:87], 0, v[40:41]
	s_nop 0
	v_addc_co_u32_e32 v47, vcc, 0, v3, vcc
	global_load_dwordx2 v[2:3], v[46:47], off
	v_add_co_u32_e32 v48, vcc, 0xd400000, v4
	s_nop 1
	v_addc_co_u32_e32 v49, vcc, 0, v5, vcc
	v_add_co_u32_e32 v50, vcc, 0xd800000, v4
	global_load_dwordx2 v[104:105], v[48:49], off nt
	s_nop 0
	v_addc_co_u32_e32 v51, vcc, 0, v5, vcc
	v_add_co_u32_e32 v52, vcc, 0xdc00000, v4
	global_load_dwordx2 v[106:107], v[50:51], off nt
	s_nop 0
	v_addc_co_u32_e32 v53, vcc, 0, v5, vcc
	v_add_co_u32_e32 v54, vcc, 0xe000000, v4
	global_load_dwordx2 v[108:109], v[52:53], off nt
	s_nop 0
	v_addc_co_u32_e32 v55, vcc, 0, v5, vcc
	v_add_co_u32_e32 v126, vcc, 0xe400000, v4
	global_load_dwordx2 v[110:111], v[54:55], off nt
	s_nop 0
	v_addc_co_u32_e32 v127, vcc, 0, v5, vcc
	v_add_co_u32_e32 v128, vcc, 0xe800000, v4
	global_load_dwordx2 v[112:113], v[126:127], off nt
	s_nop 0
	v_addc_co_u32_e32 v129, vcc, 0, v5, vcc
	v_add_co_u32_e32 v130, vcc, 0xec00000, v4
	global_load_dwordx2 v[114:115], v[128:129], off nt
	s_nop 0
	v_addc_co_u32_e32 v131, vcc, 0, v5, vcc
	v_add_co_u32_e32 v4, vcc, 0xf000000, v4
	global_load_dwordx2 v[116:117], v[130:131], off nt
	s_nop 0
	v_addc_co_u32_e32 v5, vcc, 0, v5, vcc
	global_load_dwordx2 v[118:119], v[4:5], off nt
	global_load_dwordx2 v[102:103], v[46:47], off offset:512
	global_load_dwordx2 v[100:101], v[48:49], off offset:512 nt
	global_load_dwordx2 v[96:97], v[50:51], off offset:512 nt
	global_load_dwordx2 v[94:95], v[52:53], off offset:512 nt
	global_load_dwordx2 v[92:93], v[54:55], off offset:512 nt
	global_load_dwordx2 v[90:91], v[126:127], off offset:512 nt
	global_load_dwordx2 v[88:89], v[128:129], off offset:512 nt
	global_load_dwordx2 v[86:87], v[130:131], off offset:512 nt
	global_load_dwordx2 v[84:85], v[4:5], off offset:512 nt
	global_load_dwordx2 v[82:83], v[46:47], off offset:1024
	global_load_dwordx2 v[80:81], v[48:49], off offset:1024 nt
	global_load_dwordx2 v[78:79], v[50:51], off offset:1024 nt
	global_load_dwordx2 v[76:77], v[52:53], off offset:1024 nt
	global_load_dwordx2 v[74:75], v[54:55], off offset:1024 nt
	global_load_dwordx2 v[72:73], v[126:127], off offset:1024 nt
	global_load_dwordx2 v[70:71], v[128:129], off offset:1024 nt
	global_load_dwordx2 v[68:69], v[130:131], off offset:1024 nt
	global_load_dwordx2 v[66:67], v[4:5], off offset:1024 nt
	global_load_dwordx2 v[64:65], v[46:47], off offset:1536
	global_load_dwordx2 v[62:63], v[48:49], off offset:1536 nt
	global_load_dwordx2 v[60:61], v[50:51], off offset:1536 nt
	global_load_dwordx2 v[58:59], v[52:53], off offset:1536 nt
	global_load_dwordx2 v[56:57], v[54:55], off offset:1536 nt
	s_nop 0
	global_load_dwordx2 v[54:55], v[126:127], off offset:1536 nt
	global_load_dwordx2 v[52:53], v[128:129], off offset:1536 nt
	global_load_dwordx2 v[50:51], v[130:131], off offset:1536 nt
	global_load_dwordx2 v[48:49], v[4:5], off offset:1536 nt
	s_waitcnt vmcnt(35)
	v_lshlrev_b32_e32 v125, 16, v2
	v_and_b32_e32 v130, 0xffff0000, v2
	v_lshlrev_b32_e32 v131, 16, v3
	v_and_b32_e32 v132, 0xffff0000, v3
	global_load_dwordx4 v[2:5], v[6:7], off
	global_load_dwordx4 v[126:129], v[8:9], off
	s_waitcnt vmcnt(0)
	v_pk_add_f32 v[126:127], v[126:127], 1.0 op_sel_hi:[1,0]
	s_nop 0
	v_pk_mul_f32 v[2:3], v[2:3], v[126:127]
	v_pk_add_f32 v[128:129], v[128:129], 1.0 op_sel_hi:[1,0]
	v_div_scale_f32 v126, s[0:1], v2, v2, v125
	v_rcp_f32_e32 v127, v126
	v_pk_mul_f32 v[4:5], v[4:5], v[128:129]
	v_fma_f32 v128, -v126, v127, 1.0
	v_fmac_f32_e32 v127, v128, v127
	v_div_scale_f32 v128, vcc, v125, v2, v125
	v_mul_f32_e32 v129, v128, v127
	v_fma_f32 v133, -v126, v129, v128
	v_fmac_f32_e32 v129, v133, v127
	v_fma_f32 v126, -v126, v129, v128
	v_div_fmas_f32 v126, v126, v127, v129
	v_div_fixup_f32 v126, v126, v2, v125
	v_div_scale_f32 v2, s[0:1], v3, v3, v130
	v_rcp_f32_e32 v125, v2
	s_nop 0
	v_fma_f32 v127, -v2, v125, 1.0
	v_fmac_f32_e32 v125, v127, v125
	v_div_scale_f32 v127, vcc, v130, v3, v130
	v_mul_f32_e32 v128, v127, v125
	v_fma_f32 v129, -v2, v128, v127
	v_fmac_f32_e32 v128, v129, v125
	v_fma_f32 v2, -v2, v128, v127
	v_div_fmas_f32 v2, v2, v125, v128
	v_div_fixup_f32 v127, v2, v3, v130
	v_div_scale_f32 v2, s[0:1], v4, v4, v131
	v_rcp_f32_e32 v3, v2
	s_nop 0
	v_fma_f32 v125, -v2, v3, 1.0
	v_fmac_f32_e32 v3, v125, v3
	v_div_scale_f32 v125, vcc, v131, v4, v131
	v_mul_f32_e32 v128, v125, v3
	v_fma_f32 v129, -v2, v128, v125
	v_fmac_f32_e32 v128, v129, v3
	v_fma_f32 v2, -v2, v128, v125
	v_div_fmas_f32 v2, v2, v3, v128
	v_div_fixup_f32 v128, v2, v4, v131
	v_div_scale_f32 v2, s[0:1], v5, v5, v132
	v_rcp_f32_e32 v3, v2
	s_nop 0
	v_fma_f32 v4, -v2, v3, 1.0
	v_fmac_f32_e32 v3, v4, v3
	v_div_scale_f32 v4, vcc, v132, v5, v132
	v_mul_f32_e32 v125, v4, v3
	v_fma_f32 v129, -v2, v125, v4
	v_fmac_f32_e32 v125, v129, v3
	v_fma_f32 v2, -v2, v125, v4
	v_div_fmas_f32 v2, v2, v3, v125
	v_div_fixup_f32 v129, v2, v5, v132
	v_lshlrev_b32_e32 v2, 16, v104
	v_and_b32_e32 v3, 0xffff0000, v104
	v_pk_add_f32 v[2:3], v[2:3], 0 op_sel_hi:[1,0]
	v_lshlrev_b32_e32 v4, 16, v106
	v_and_b32_e32 v5, 0xffff0000, v106
	v_pk_add_f32 v[2:3], v[2:3], v[4:5]
	v_lshlrev_b32_e32 v4, 16, v108
	v_and_b32_e32 v5, 0xffff0000, v108
	v_pk_add_f32 v[2:3], v[2:3], v[4:5]
	v_lshlrev_b32_e32 v4, 16, v110
	v_and_b32_e32 v5, 0xffff0000, v110
	v_pk_add_f32 v[2:3], v[2:3], v[4:5]
	v_lshlrev_b32_e32 v4, 16, v112
	v_and_b32_e32 v5, 0xffff0000, v112
	v_pk_add_f32 v[2:3], v[2:3], v[4:5]
	v_lshlrev_b32_e32 v4, 16, v114
	v_and_b32_e32 v5, 0xffff0000, v114
	v_pk_add_f32 v[2:3], v[2:3], v[4:5]
	v_lshlrev_b32_e32 v4, 16, v116
	v_and_b32_e32 v5, 0xffff0000, v116
	v_pk_add_f32 v[2:3], v[2:3], v[4:5]
	v_lshlrev_b32_e32 v4, 16, v118
	v_and_b32_e32 v5, 0xffff0000, v118
	v_pk_add_f32 v[130:131], v[2:3], v[4:5]
	v_lshlrev_b32_e32 v2, 16, v105
	v_and_b32_e32 v3, 0xffff0000, v105
	v_pk_add_f32 v[2:3], v[2:3], 0 op_sel_hi:[1,0]
	v_lshlrev_b32_e32 v4, 16, v107
	v_and_b32_e32 v5, 0xffff0000, v107
	v_pk_add_f32 v[2:3], v[2:3], v[4:5]
	v_lshlrev_b32_e32 v4, 16, v109
	v_and_b32_e32 v5, 0xffff0000, v109
	v_pk_add_f32 v[2:3], v[2:3], v[4:5]
	v_lshlrev_b32_e32 v4, 16, v111
	v_and_b32_e32 v5, 0xffff0000, v111
	v_pk_add_f32 v[2:3], v[2:3], v[4:5]
	v_lshlrev_b32_e32 v4, 16, v113
	v_and_b32_e32 v5, 0xffff0000, v113
	v_pk_add_f32 v[2:3], v[2:3], v[4:5]
	v_lshlrev_b32_e32 v4, 16, v115
	v_and_b32_e32 v5, 0xffff0000, v115
	v_pk_add_f32 v[2:3], v[2:3], v[4:5]
	v_lshlrev_b32_e32 v4, 16, v117
	v_and_b32_e32 v5, 0xffff0000, v117
	v_pk_add_f32 v[2:3], v[2:3], v[4:5]
	v_lshlrev_b32_e32 v4, 16, v119
	v_and_b32_e32 v5, 0xffff0000, v119
	v_pk_add_f32 v[104:105], v[2:3], v[4:5]
	global_load_dwordx4 v[2:5], v[10:11], off
	v_lshlrev_b32_e32 v109, 16, v103
	v_and_b32_e32 v110, 0xffff0000, v103
	s_waitcnt vmcnt(0)
	v_pk_fma_f32 v[104:105], v[104:105], v[4:5], v[128:129]
	v_pk_fma_f32 v[106:107], v[130:131], v[2:3], v[126:127]
	v_mul_f32_e32 v3, v105, v105
	v_mul_f32_e32 v2, v107, v107
	v_fmac_f32_e32 v2, v106, v106
	v_fmac_f32_e32 v3, v104, v104
	v_add_f32_e32 v108, v2, v3
	global_load_dwordx4 v[2:5], v[12:13], off
	s_waitcnt vmcnt(0)
	v_pk_mul_f32 v[104:105], v[4:5], v[104:105]
	v_pk_mul_f32 v[106:107], v[2:3], v[106:107]
	global_load_dwordx4 v[2:5], v[14:15], off
	s_waitcnt vmcnt(0)
	v_pk_add_f32 v[4:5], v[4:5], 1.0 op_sel_hi:[1,0]
	v_pk_add_f32 v[2:3], v[2:3], 1.0 op_sel_hi:[1,0]
	v_pk_mul_f32 v[4:5], v[4:5], v[104:105]
	v_pk_mul_f32 v[2:3], v[2:3], v[106:107]
	v_lshlrev_b32_e32 v106, 16, v102
	v_cvt_pk_bf16_f32 v2, v2, v3
	v_cvt_pk_bf16_f32 v3, v4, v5
	global_store_dwordx2 v[46:47], v[2:3], off
	v_and_b32_e32 v107, 0xffff0000, v102
	global_load_dwordx4 v[2:5], v[6:7], off offset:1024
	global_load_dwordx4 v[102:105], v[16:17], off
	s_waitcnt vmcnt(0)
	v_pk_add_f32 v[102:103], v[102:103], 1.0 op_sel_hi:[1,0]
	s_nop 0
	v_pk_mul_f32 v[2:3], v[2:3], v[102:103]
	v_pk_add_f32 v[104:105], v[104:105], 1.0 op_sel_hi:[1,0]
	v_div_scale_f32 v102, s[0:1], v2, v2, v106
	v_rcp_f32_e32 v103, v102
	v_pk_mul_f32 v[4:5], v[4:5], v[104:105]
	v_fma_f32 v104, -v102, v103, 1.0
	v_fmac_f32_e32 v103, v104, v103
	v_div_scale_f32 v104, vcc, v106, v2, v106
	v_mul_f32_e32 v105, v104, v103
	v_fma_f32 v111, -v102, v105, v104
	v_fmac_f32_e32 v105, v111, v103
	v_fma_f32 v102, -v102, v105, v104
	v_div_fmas_f32 v102, v102, v103, v105
	v_div_fixup_f32 v102, v102, v2, v106
	v_div_scale_f32 v2, s[0:1], v3, v3, v107
	v_rcp_f32_e32 v103, v2
	s_nop 0
	v_fma_f32 v104, -v2, v103, 1.0
	v_fmac_f32_e32 v103, v104, v103
	v_div_scale_f32 v104, vcc, v107, v3, v107
	v_mul_f32_e32 v105, v104, v103
	v_fma_f32 v106, -v2, v105, v104
	v_fmac_f32_e32 v105, v106, v103
	v_fma_f32 v2, -v2, v105, v104
	v_div_fmas_f32 v2, v2, v103, v105
	v_div_fixup_f32 v103, v2, v3, v107
	v_div_scale_f32 v2, s[0:1], v4, v4, v109
	v_rcp_f32_e32 v3, v2
	s_nop 0
	v_fma_f32 v104, -v2, v3, 1.0
	v_fmac_f32_e32 v3, v104, v3
	v_div_scale_f32 v104, vcc, v109, v4, v109
	v_mul_f32_e32 v105, v104, v3
	v_fma_f32 v106, -v2, v105, v104
	v_fmac_f32_e32 v105, v106, v3
	v_fma_f32 v2, -v2, v105, v104
	v_div_fmas_f32 v2, v2, v3, v105
	v_div_fixup_f32 v104, v2, v4, v109
	v_div_scale_f32 v2, s[0:1], v5, v5, v110
	v_rcp_f32_e32 v3, v2
	s_nop 0
	v_fma_f32 v4, -v2, v3, 1.0
	v_fmac_f32_e32 v3, v4, v3
	v_div_scale_f32 v4, vcc, v110, v5, v110
	v_mul_f32_e32 v105, v4, v3
	v_fma_f32 v106, -v2, v105, v4
	v_fmac_f32_e32 v105, v106, v3
	v_fma_f32 v2, -v2, v105, v4
	v_div_fmas_f32 v2, v2, v3, v105
	v_div_fixup_f32 v105, v2, v5, v110
	v_lshlrev_b32_e32 v2, 16, v100
	v_and_b32_e32 v3, 0xffff0000, v100
	v_pk_add_f32 v[2:3], v[2:3], 0 op_sel_hi:[1,0]
	v_lshlrev_b32_e32 v4, 16, v96
	v_and_b32_e32 v5, 0xffff0000, v96
	v_pk_add_f32 v[2:3], v[2:3], v[4:5]
	v_lshlrev_b32_e32 v4, 16, v94
	v_and_b32_e32 v5, 0xffff0000, v94
	v_pk_add_f32 v[2:3], v[2:3], v[4:5]
	v_lshlrev_b32_e32 v4, 16, v92
	v_and_b32_e32 v5, 0xffff0000, v92
	v_pk_add_f32 v[2:3], v[2:3], v[4:5]
	v_lshlrev_b32_e32 v4, 16, v90
	v_and_b32_e32 v5, 0xffff0000, v90
	v_pk_add_f32 v[2:3], v[2:3], v[4:5]
	v_lshlrev_b32_e32 v4, 16, v88
	v_and_b32_e32 v5, 0xffff0000, v88
	v_pk_add_f32 v[2:3], v[2:3], v[4:5]
	v_lshlrev_b32_e32 v4, 16, v86
	v_and_b32_e32 v5, 0xffff0000, v86
	v_pk_add_f32 v[2:3], v[2:3], v[4:5]
	v_lshlrev_b32_e32 v4, 16, v84
	v_and_b32_e32 v5, 0xffff0000, v84
	v_pk_add_f32 v[106:107], v[2:3], v[4:5]
	v_lshlrev_b32_e32 v2, 16, v101
	v_and_b32_e32 v3, 0xffff0000, v101
	v_pk_add_f32 v[2:3], v[2:3], 0 op_sel_hi:[1,0]
	v_lshlrev_b32_e32 v4, 16, v97
	v_and_b32_e32 v5, 0xffff0000, v97
	v_pk_add_f32 v[2:3], v[2:3], v[4:5]
	v_lshlrev_b32_e32 v4, 16, v95
	v_and_b32_e32 v5, 0xffff0000, v95
	v_pk_add_f32 v[2:3], v[2:3], v[4:5]
	v_lshlrev_b32_e32 v4, 16, v93
	v_and_b32_e32 v5, 0xffff0000, v93
	v_pk_add_f32 v[2:3], v[2:3], v[4:5]
	v_lshlrev_b32_e32 v4, 16, v91
	v_and_b32_e32 v5, 0xffff0000, v91
	v_pk_add_f32 v[2:3], v[2:3], v[4:5]
	v_lshlrev_b32_e32 v4, 16, v89
	v_and_b32_e32 v5, 0xffff0000, v89
	v_pk_add_f32 v[2:3], v[2:3], v[4:5]
	v_lshlrev_b32_e32 v4, 16, v87
	v_and_b32_e32 v5, 0xffff0000, v87
	v_pk_add_f32 v[2:3], v[2:3], v[4:5]
	v_lshlrev_b32_e32 v4, 16, v85
	v_and_b32_e32 v5, 0xffff0000, v85
	v_pk_add_f32 v[84:85], v[2:3], v[4:5]
	global_load_dwordx4 v[2:5], v[18:19], off
	v_lshlrev_b32_e32 v89, 16, v83
	v_and_b32_e32 v90, 0xffff0000, v83
	s_waitcnt vmcnt(0)
	v_pk_fma_f32 v[84:85], v[84:85], v[4:5], v[104:105]
	v_pk_fma_f32 v[86:87], v[106:107], v[2:3], v[102:103]
	v_mul_f32_e32 v3, v85, v85
	v_mul_f32_e32 v2, v87, v87
	v_fmac_f32_e32 v2, v86, v86
	v_fmac_f32_e32 v3, v84, v84
	v_add_f32_e32 v2, v2, v3
	v_add_f32_e32 v88, v108, v2
	global_load_dwordx4 v[2:5], v[20:21], off
	s_waitcnt vmcnt(0)
	v_pk_mul_f32 v[84:85], v[4:5], v[84:85]
	v_pk_mul_f32 v[86:87], v[2:3], v[86:87]
	global_load_dwordx4 v[2:5], v[22:23], off
	s_waitcnt vmcnt(0)
	v_pk_add_f32 v[4:5], v[4:5], 1.0 op_sel_hi:[1,0]
	v_pk_add_f32 v[2:3], v[2:3], 1.0 op_sel_hi:[1,0]
	v_pk_mul_f32 v[4:5], v[4:5], v[84:85]
	v_pk_mul_f32 v[2:3], v[2:3], v[86:87]
	v_lshlrev_b32_e32 v86, 16, v82
	v_cvt_pk_bf16_f32 v2, v2, v3
	v_cvt_pk_bf16_f32 v3, v4, v5
	global_store_dwordx2 v[46:47], v[2:3], off offset:512
	v_and_b32_e32 v87, 0xffff0000, v82
	global_load_dwordx4 v[2:5], v[6:7], off offset:2048
	global_load_dwordx4 v[82:85], v[24:25], off
	s_waitcnt vmcnt(0)
	v_pk_add_f32 v[82:83], v[82:83], 1.0 op_sel_hi:[1,0]
	s_nop 0
	v_pk_mul_f32 v[2:3], v[2:3], v[82:83]
	v_pk_add_f32 v[84:85], v[84:85], 1.0 op_sel_hi:[1,0]
	v_div_scale_f32 v82, s[0:1], v2, v2, v86
	v_rcp_f32_e32 v83, v82
	v_pk_mul_f32 v[4:5], v[4:5], v[84:85]
	v_fma_f32 v84, -v82, v83, 1.0
	v_fmac_f32_e32 v83, v84, v83
	v_div_scale_f32 v84, vcc, v86, v2, v86
	v_mul_f32_e32 v85, v84, v83
	v_fma_f32 v91, -v82, v85, v84
	v_fmac_f32_e32 v85, v91, v83
	v_fma_f32 v82, -v82, v85, v84
	v_div_fmas_f32 v82, v82, v83, v85
	v_div_fixup_f32 v82, v82, v2, v86
	v_div_scale_f32 v2, s[0:1], v3, v3, v87
	v_rcp_f32_e32 v83, v2
	s_nop 0
	v_fma_f32 v84, -v2, v83, 1.0
	v_fmac_f32_e32 v83, v84, v83
	v_div_scale_f32 v84, vcc, v87, v3, v87
	v_mul_f32_e32 v85, v84, v83
	v_fma_f32 v86, -v2, v85, v84
	v_fmac_f32_e32 v85, v86, v83
	v_fma_f32 v2, -v2, v85, v84
	v_div_fmas_f32 v2, v2, v83, v85
	v_div_fixup_f32 v83, v2, v3, v87
	v_div_scale_f32 v2, s[0:1], v4, v4, v89
	v_rcp_f32_e32 v3, v2
	s_nop 0
	v_fma_f32 v84, -v2, v3, 1.0
	v_fmac_f32_e32 v3, v84, v3
	v_div_scale_f32 v84, vcc, v89, v4, v89
	v_mul_f32_e32 v85, v84, v3
	v_fma_f32 v86, -v2, v85, v84
	v_fmac_f32_e32 v85, v86, v3
	v_fma_f32 v2, -v2, v85, v84
	v_div_fmas_f32 v2, v2, v3, v85
	v_div_fixup_f32 v84, v2, v4, v89
	v_div_scale_f32 v2, s[0:1], v5, v5, v90
	v_rcp_f32_e32 v3, v2
	s_nop 0
	v_fma_f32 v4, -v2, v3, 1.0
	v_fmac_f32_e32 v3, v4, v3
	v_div_scale_f32 v4, vcc, v90, v5, v90
	v_mul_f32_e32 v85, v4, v3
	v_fma_f32 v86, -v2, v85, v4
	v_fmac_f32_e32 v85, v86, v3
	v_fma_f32 v2, -v2, v85, v4
	v_div_fmas_f32 v2, v2, v3, v85
	v_div_fixup_f32 v85, v2, v5, v90
	v_lshlrev_b32_e32 v2, 16, v80
	v_and_b32_e32 v3, 0xffff0000, v80
	v_pk_add_f32 v[2:3], v[2:3], 0 op_sel_hi:[1,0]
	v_lshlrev_b32_e32 v4, 16, v78
	v_and_b32_e32 v5, 0xffff0000, v78
	v_pk_add_f32 v[2:3], v[2:3], v[4:5]
	v_lshlrev_b32_e32 v4, 16, v76
	v_and_b32_e32 v5, 0xffff0000, v76
	v_pk_add_f32 v[2:3], v[2:3], v[4:5]
	v_lshlrev_b32_e32 v4, 16, v74
	v_and_b32_e32 v5, 0xffff0000, v74
	v_pk_add_f32 v[2:3], v[2:3], v[4:5]
	v_lshlrev_b32_e32 v4, 16, v72
	v_and_b32_e32 v5, 0xffff0000, v72
	v_pk_add_f32 v[2:3], v[2:3], v[4:5]
	v_lshlrev_b32_e32 v4, 16, v70
	v_and_b32_e32 v5, 0xffff0000, v70
	v_pk_add_f32 v[2:3], v[2:3], v[4:5]
	v_lshlrev_b32_e32 v4, 16, v68
	v_and_b32_e32 v5, 0xffff0000, v68
	v_pk_add_f32 v[2:3], v[2:3], v[4:5]
	v_lshlrev_b32_e32 v4, 16, v66
	v_and_b32_e32 v5, 0xffff0000, v66
	v_pk_add_f32 v[86:87], v[2:3], v[4:5]
	v_lshlrev_b32_e32 v2, 16, v81
	v_and_b32_e32 v3, 0xffff0000, v81
	v_pk_add_f32 v[2:3], v[2:3], 0 op_sel_hi:[1,0]
	v_lshlrev_b32_e32 v4, 16, v79
	v_and_b32_e32 v5, 0xffff0000, v79
	v_pk_add_f32 v[2:3], v[2:3], v[4:5]
	v_lshlrev_b32_e32 v4, 16, v77
	v_and_b32_e32 v5, 0xffff0000, v77
	v_pk_add_f32 v[2:3], v[2:3], v[4:5]
	v_lshlrev_b32_e32 v4, 16, v75
	v_and_b32_e32 v5, 0xffff0000, v75
	v_pk_add_f32 v[2:3], v[2:3], v[4:5]
	v_lshlrev_b32_e32 v4, 16, v73
	v_and_b32_e32 v5, 0xffff0000, v73
	v_pk_add_f32 v[2:3], v[2:3], v[4:5]
	v_lshlrev_b32_e32 v4, 16, v71
	v_and_b32_e32 v5, 0xffff0000, v71
	v_pk_add_f32 v[2:3], v[2:3], v[4:5]
	v_lshlrev_b32_e32 v4, 16, v69
	v_and_b32_e32 v5, 0xffff0000, v69
	v_pk_add_f32 v[2:3], v[2:3], v[4:5]
	v_lshlrev_b32_e32 v4, 16, v67
	v_and_b32_e32 v5, 0xffff0000, v67
	v_pk_add_f32 v[66:67], v[2:3], v[4:5]
	global_load_dwordx4 v[2:5], v[26:27], off
	v_lshlrev_b32_e32 v71, 16, v65
	v_and_b32_e32 v72, 0xffff0000, v65
	s_waitcnt vmcnt(0)
	v_pk_fma_f32 v[66:67], v[66:67], v[4:5], v[84:85]
	v_pk_fma_f32 v[68:69], v[86:87], v[2:3], v[82:83]
	v_mul_f32_e32 v3, v67, v67
	v_mul_f32_e32 v2, v69, v69
	v_fmac_f32_e32 v2, v68, v68
	v_fmac_f32_e32 v3, v66, v66
	v_add_f32_e32 v2, v2, v3
	v_add_f32_e32 v70, v88, v2
	global_load_dwordx4 v[2:5], v[28:29], off
	s_waitcnt vmcnt(0)
	v_pk_mul_f32 v[66:67], v[4:5], v[66:67]
	v_pk_mul_f32 v[68:69], v[2:3], v[68:69]
	global_load_dwordx4 v[2:5], v[30:31], off
	s_waitcnt vmcnt(0)
	v_pk_add_f32 v[4:5], v[4:5], 1.0 op_sel_hi:[1,0]
	v_pk_add_f32 v[2:3], v[2:3], 1.0 op_sel_hi:[1,0]
	v_pk_mul_f32 v[4:5], v[4:5], v[66:67]
	v_pk_mul_f32 v[2:3], v[2:3], v[68:69]
	v_lshlrev_b32_e32 v68, 16, v64
	v_cvt_pk_bf16_f32 v2, v2, v3
	v_cvt_pk_bf16_f32 v3, v4, v5
	global_store_dwordx2 v[46:47], v[2:3], off offset:1024
	v_and_b32_e32 v69, 0xffff0000, v64
	global_load_dwordx4 v[2:5], v[6:7], off offset:3072
	global_load_dwordx4 v[64:67], v[32:33], off
	s_waitcnt vmcnt(0)
	v_pk_add_f32 v[64:65], v[64:65], 1.0 op_sel_hi:[1,0]
	s_nop 0
	v_pk_mul_f32 v[2:3], v[2:3], v[64:65]
	v_pk_add_f32 v[66:67], v[66:67], 1.0 op_sel_hi:[1,0]
	v_div_scale_f32 v64, s[0:1], v2, v2, v68
	v_rcp_f32_e32 v65, v64
	v_pk_mul_f32 v[4:5], v[4:5], v[66:67]
	v_fma_f32 v66, -v64, v65, 1.0
	v_fmac_f32_e32 v65, v66, v65
	v_div_scale_f32 v66, vcc, v68, v2, v68
	v_mul_f32_e32 v67, v66, v65
	v_fma_f32 v73, -v64, v67, v66
	v_fmac_f32_e32 v67, v73, v65
	v_fma_f32 v64, -v64, v67, v66
	v_div_fmas_f32 v64, v64, v65, v67
	v_div_fixup_f32 v64, v64, v2, v68
	v_div_scale_f32 v2, s[0:1], v3, v3, v69
	v_rcp_f32_e32 v65, v2
	s_nop 0
	v_fma_f32 v66, -v2, v65, 1.0
	v_fmac_f32_e32 v65, v66, v65
	v_div_scale_f32 v66, vcc, v69, v3, v69
	v_mul_f32_e32 v67, v66, v65
	v_fma_f32 v68, -v2, v67, v66
	v_fmac_f32_e32 v67, v68, v65
	v_fma_f32 v2, -v2, v67, v66
	v_div_fmas_f32 v2, v2, v65, v67
	v_div_fixup_f32 v65, v2, v3, v69
	v_div_scale_f32 v2, s[0:1], v4, v4, v71
	v_rcp_f32_e32 v3, v2
	s_nop 0
	v_fma_f32 v66, -v2, v3, 1.0
	v_fmac_f32_e32 v3, v66, v3
	v_div_scale_f32 v66, vcc, v71, v4, v71
	v_mul_f32_e32 v67, v66, v3
	v_fma_f32 v68, -v2, v67, v66
	v_fmac_f32_e32 v67, v68, v3
	v_fma_f32 v2, -v2, v67, v66
	v_div_fmas_f32 v2, v2, v3, v67
	v_div_fixup_f32 v66, v2, v4, v71
	v_div_scale_f32 v2, s[0:1], v5, v5, v72
	v_rcp_f32_e32 v3, v2
	s_nop 0
	v_fma_f32 v4, -v2, v3, 1.0
	v_fmac_f32_e32 v3, v4, v3
	v_div_scale_f32 v4, vcc, v72, v5, v72
	v_mul_f32_e32 v67, v4, v3
	v_fma_f32 v68, -v2, v67, v4
	v_fmac_f32_e32 v67, v68, v3
	v_fma_f32 v2, -v2, v67, v4
	v_div_fmas_f32 v2, v2, v3, v67
	v_div_fixup_f32 v67, v2, v5, v72
	v_lshlrev_b32_e32 v2, 16, v62
	v_and_b32_e32 v3, 0xffff0000, v62
	v_pk_add_f32 v[2:3], v[2:3], 0 op_sel_hi:[1,0]
	v_lshlrev_b32_e32 v4, 16, v60
	v_and_b32_e32 v5, 0xffff0000, v60
	v_pk_add_f32 v[2:3], v[2:3], v[4:5]
	v_lshlrev_b32_e32 v4, 16, v58
	v_and_b32_e32 v5, 0xffff0000, v58
	v_pk_add_f32 v[2:3], v[2:3], v[4:5]
	v_lshlrev_b32_e32 v4, 16, v56
	v_and_b32_e32 v5, 0xffff0000, v56
	v_pk_add_f32 v[2:3], v[2:3], v[4:5]
	v_lshlrev_b32_e32 v4, 16, v54
	v_and_b32_e32 v5, 0xffff0000, v54
	v_pk_add_f32 v[2:3], v[2:3], v[4:5]
	v_lshlrev_b32_e32 v4, 16, v52
	v_and_b32_e32 v5, 0xffff0000, v52
	v_pk_add_f32 v[2:3], v[2:3], v[4:5]
	v_lshlrev_b32_e32 v4, 16, v50
	v_and_b32_e32 v5, 0xffff0000, v50
	v_pk_add_f32 v[2:3], v[2:3], v[4:5]
	v_lshlrev_b32_e32 v4, 16, v48
	v_and_b32_e32 v5, 0xffff0000, v48
	v_pk_add_f32 v[68:69], v[2:3], v[4:5]
	v_lshlrev_b32_e32 v2, 16, v63
	v_and_b32_e32 v3, 0xffff0000, v63
	v_pk_add_f32 v[2:3], v[2:3], 0 op_sel_hi:[1,0]
	v_lshlrev_b32_e32 v4, 16, v61
	v_and_b32_e32 v5, 0xffff0000, v61
	v_pk_add_f32 v[2:3], v[2:3], v[4:5]
	v_lshlrev_b32_e32 v4, 16, v59
	v_and_b32_e32 v5, 0xffff0000, v59
	v_pk_add_f32 v[2:3], v[2:3], v[4:5]
	v_lshlrev_b32_e32 v4, 16, v57
	v_and_b32_e32 v5, 0xffff0000, v57
	v_pk_add_f32 v[2:3], v[2:3], v[4:5]
	v_lshlrev_b32_e32 v4, 16, v55
	v_and_b32_e32 v5, 0xffff0000, v55
	v_pk_add_f32 v[2:3], v[2:3], v[4:5]
	v_lshlrev_b32_e32 v4, 16, v53
	v_and_b32_e32 v5, 0xffff0000, v53
	v_pk_add_f32 v[2:3], v[2:3], v[4:5]
	v_lshlrev_b32_e32 v4, 16, v51
	v_and_b32_e32 v5, 0xffff0000, v51
	v_pk_add_f32 v[2:3], v[2:3], v[4:5]
	v_lshlrev_b32_e32 v4, 16, v49
	v_and_b32_e32 v5, 0xffff0000, v49
	v_pk_add_f32 v[48:49], v[2:3], v[4:5]
	global_load_dwordx4 v[2:5], v[34:35], off
	global_load_dwordx4 v[50:53], v[36:37], off
	s_waitcnt vmcnt(1)
	v_pk_fma_f32 v[4:5], v[48:49], v[4:5], v[66:67]
	v_pk_fma_f32 v[54:55], v[68:69], v[2:3], v[64:65]
	v_mul_f32_e32 v3, v5, v5
	v_mul_f32_e32 v2, v55, v55
	v_fmac_f32_e32 v2, v54, v54
	v_fmac_f32_e32 v3, v4, v4
	v_add_f32_e32 v2, v2, v3
	v_add_f32_e32 v48, v70, v2
	s_waitcnt vmcnt(0)
	v_pk_mul_f32 v[2:3], v[52:53], v[4:5]
	v_pk_mul_f32 v[4:5], v[50:51], v[54:55]
	global_load_dwordx4 v[50:53], v[38:39], off
	s_waitcnt vmcnt(0)
	v_pk_add_f32 v[52:53], v[52:53], 1.0 op_sel_hi:[1,0]
	v_pk_add_f32 v[50:51], v[50:51], 1.0 op_sel_hi:[1,0]
	v_pk_mul_f32 v[2:3], v[52:53], v[2:3]
	v_pk_mul_f32 v[4:5], v[50:51], v[4:5]
	s_nop 0
	v_cvt_pk_bf16_f32 v4, v4, v5
	v_cvt_pk_bf16_f32 v5, v2, v3
	v_mov_b32_dpp v2, v48 quad_perm:[1,0,3,2] row_mask:0xf bank_mask:0xf
	global_store_dwordx2 v[46:47], v[4:5], off offset:1536
	s_waitcnt lgkmcnt(0)
	v_add_f32_e32 v2, v48, v2
	s_nop 1
	v_mov_b32_dpp v3, v2 quad_perm:[2,3,0,1] row_mask:0xf bank_mask:0xf
	s_waitcnt lgkmcnt(0)
	v_add_f32_e32 v2, v2, v3
	s_nop 1
	v_mov_b32_dpp v3, v2 row_half_mirror row_mask:0xf bank_mask:0xf
	s_waitcnt lgkmcnt(0)
	v_add_f32_e32 v2, v2, v3
	s_nop 1
	v_mov_b32_dpp v3, v2 row_mirror row_mask:0xf bank_mask:0xf
	s_waitcnt lgkmcnt(0)
	v_add_f32_e32 v2, v2, v3
	v_mov_b32_e32 v3, v2
	s_nop 1
	v_permlane16_swap_b32_e32 v2, v3
	s_waitcnt lgkmcnt(0)
	v_add_f32_e32 v2, v2, v3
	v_mov_b32_e32 v3, v2
	s_nop 1
	v_permlane32_swap_b32_e32 v2, v3
	s_and_saveexec_b64 s[0:1], s[36:37]
	s_cbranch_execz .LBB0_1637
	s_waitcnt lgkmcnt(0)
	v_add_f32_e32 v2, v2, v3
	v_lshl_add_u64 v[4:5], s[86:87], 0, v[44:45]
	v_cndmask_b32_e64 v2, 0, v2, s[38:39]
	global_store_dword v[4:5], v2, off
	s_branch .LBB0_1637

.LBB0_1704:
	s_waitcnt vmcnt(3)
	v_lshlrev_b32_e32 v51, 16, v41
	v_lshlrev_b32_e32 v50, 16, v40
	v_and_b32_e32 v41, 0xffff0000, v41
	v_and_b32_e32 v40, 0xffff0000, v40
	s_waitcnt vmcnt(2)
	v_lshlrev_b32_e32 v55, 16, v39
	v_lshlrev_b32_e32 v54, 16, v38
	v_and_b32_e32 v39, 0xffff0000, v39
	v_and_b32_e32 v38, 0xffff0000, v38
	v_pk_mul_f32 v[52:53], v[40:41], v[40:41]
	v_pk_mul_f32 v[56:57], v[38:39], v[38:39]
	s_waitcnt vmcnt(1)
	v_lshlrev_b32_e32 v58, 16, v36
	v_and_b32_e32 v59, 0xffff0000, v36
	v_lshlrev_b32_e32 v64, 16, v37
	s_waitcnt vmcnt(0)
	v_lshlrev_b32_e32 v60, 16, v34
	v_pk_fma_f32 v[52:53], v[50:51], v[50:51], v[52:53]
	v_pk_fma_f32 v[56:57], v[54:55], v[54:55], v[56:57]
	v_mul_f32_e32 v61, v58, v58
	v_mul_f32_e32 v63, v59, v59
	v_and_b32_e32 v65, 0xffff0000, v37
	v_mul_f32_e32 v36, v64, v64
	v_mov_b32_e32 v62, v60
	v_pk_add_f32 v[52:53], v[52:53], v[52:53] op_sel_hi:[0,1]
	v_pk_add_f32 v[56:57], v[56:57], v[56:57] op_sel_hi:[0,1]
	v_pk_fma_f32 v[36:37], v[64:65], v[64:65], v[36:37] op_sel_hi:[1,1,0]
	v_and_b32_e32 v68, 0xffff0000, v34
	v_lshlrev_b32_e32 v66, 16, v35
	v_and_b32_e32 v67, 0xffff0000, v35
	v_pk_add_f32 v[62:63], v[60:61], v[62:63]
	v_mul_f32_e32 v36, v68, v68
	v_mul_f32_e32 v56, v66, v66
	v_mul_f32_e32 v52, v67, v67
	v_mul_f32_e32 v34, v60, v60
	v_mov_b32_e32 v35, v63
	v_pk_add_f32 v[34:35], v[34:35], v[36:37]
	v_pk_add_f32 v[36:37], v[56:57], v[52:53]
	s_add_i32 s6, s9, s8
	v_pk_add_f32 v[52:53], v[34:35], v[36:37]
	global_load_dwordx4 v[34:37], v[4:5], off
	v_add_f32_e32 v52, v52, v53
	s_nop 1
	v_mov_b32_dpp v53, v52 quad_perm:[1,0,3,2] row_mask:0xf bank_mask:0xf
	s_cmpk_gt_i32 s6, 0x3fff
	s_waitcnt lgkmcnt(0)
	v_add_f32_e32 v52, v52, v53
	s_nop 1
	v_mov_b32_dpp v53, v52 quad_perm:[2,3,0,1] row_mask:0xf bank_mask:0xf
	s_waitcnt lgkmcnt(0)
	v_add_f32_e32 v52, v52, v53
	s_nop 1
	v_mov_b32_dpp v53, v52 row_half_mirror row_mask:0xf bank_mask:0xf
	s_waitcnt lgkmcnt(0)
	v_add_f32_e32 v52, v52, v53
	s_nop 1
	v_mov_b32_dpp v53, v52 row_mirror row_mask:0xf bank_mask:0xf
	s_waitcnt lgkmcnt(0)
	v_add_f32_e32 v52, v52, v53
	v_mov_b32_e32 v53, v52
	s_nop 1
	v_permlane16_swap_b32_e32 v52, v53
	s_waitcnt lgkmcnt(0)
	v_add_f32_e32 v52, v52, v53
	v_mov_b32_e32 v53, v52
	s_nop 1
	v_permlane32_swap_b32_e32 v52, v53
	s_waitcnt lgkmcnt(0)
	v_add_f32_e32 v52, v52, v53
	v_fmamk_f32 v52, v52, 0x3a800000, v48
	v_mul_f32_e32 v53, 0x4f800000, v52
	v_cmp_gt_f32_e32 vcc, s12, v52
	s_nop 1
	v_cndmask_b32_e32 v52, v52, v53, vcc
	v_sqrt_f32_e32 v53, v52
	s_nop 0
	v_add_u32_e32 v56, -1, v53
	v_fma_f32 v57, -v56, v53, v52
	v_cmp_ge_f32_e64 s[0:1], 0, v57
	v_add_u32_e32 v57, 1, v53
	s_nop 0
	v_cndmask_b32_e64 v56, v53, v56, s[0:1]
	v_fma_f32 v53, -v57, v53, v52
	v_cmp_lt_f32_e64 s[0:1], 0, v53
	s_nop 1
	v_cndmask_b32_e64 v53, v56, v57, s[0:1]
	v_mul_f32_e32 v56, 0x37800000, v53
	v_cndmask_b32_e32 v53, v53, v56, vcc
	v_cmp_class_f32_e32 vcc, v52, v49
	s_nop 1
	v_cndmask_b32_e32 v52, v53, v52, vcc
	v_div_scale_f32 v53, s[0:1], v52, v52, 1.0
	v_rcp_f32_e32 v56, v53
	s_nop 0
	v_fma_f32 v57, -v53, v56, 1.0
	v_fmac_f32_e32 v56, v57, v56
	v_div_scale_f32 v57, vcc, 1.0, v52, 1.0
	v_mul_f32_e32 v61, v57, v56
	v_fma_f32 v62, -v53, v61, v57
	v_fmac_f32_e32 v61, v62, v56
	v_fma_f32 v53, -v53, v61, v57
	v_div_fmas_f32 v53, v53, v56, v61
	v_div_fixup_f32 v52, v53, v52, 1.0
	v_mov_b32_e32 v56, v50
	v_mov_b32_e32 v57, v40
	v_mov_b32_e32 v40, v51
	v_pk_mul_f32 v[56:57], v[52:53], v[56:57] op_sel_hi:[0,1]
	v_pk_mul_f32 v[40:41], v[52:53], v[40:41] op_sel_hi:[0,1]
	s_waitcnt vmcnt(0)
	v_pk_mul_f32 v[36:37], v[36:37], v[40:41]
	v_pk_mul_f32 v[34:35], v[34:35], v[56:57]
	global_store_dwordx4 v[0:1], v[34:37], off offset:-3072 nt
	global_load_dwordx4 v[34:37], v[4:5], off offset:1024
	v_mov_b32_e32 v40, v55
	v_mov_b32_e32 v41, v39
	v_mov_b32_e32 v55, v38
	v_pk_mul_f32 v[38:39], v[52:53], v[40:41] op_sel_hi:[0,1]
	v_pk_mul_f32 v[40:41], v[52:53], v[54:55] op_sel_hi:[0,1]
	v_mov_b32_e32 v61, v68
	s_waitcnt vmcnt(0)
	v_pk_mul_f32 v[34:35], v[34:35], v[40:41]
	v_pk_mul_f32 v[36:37], v[36:37], v[38:39]
	global_store_dwordx4 v[0:1], v[34:37], off offset:-2048 nt
	global_load_dwordx4 v[34:37], v[4:5], off offset:2048
	v_pk_mul_f32 v[38:39], v[64:65], v[52:53] op_sel_hi:[1,0]
	v_pk_mul_f32 v[40:41], v[58:59], v[52:53] op_sel_hi:[1,0]
	s_waitcnt vmcnt(0)
	v_pk_mul_f32 v[36:37], v[36:37], v[38:39]
	v_pk_mul_f32 v[34:35], v[34:35], v[40:41]
	global_store_dwordx4 v[0:1], v[34:37], off offset:-1024 nt
	global_load_dwordx4 v[34:37], v[4:5], off offset:3072
	v_pk_mul_f32 v[38:39], v[66:67], v[52:53] op_sel_hi:[1,0]
	v_pk_mul_f32 v[40:41], v[60:61], v[52:53] op_sel_hi:[1,0]
	s_waitcnt vmcnt(0)
	v_pk_mul_f32 v[36:37], v[36:37], v[38:39]
	v_pk_mul_f32 v[34:35], v[34:35], v[40:41]
	global_store_dwordx4 v[0:1], v[34:37], off nt
	s_cbranch_scc1 .LBB0_1699
	s_nop 0
	v_lshlrev_b32_e32 v35, 16, v33
	v_lshlrev_b32_e32 v34, 16, v32
	v_and_b32_e32 v33, 0xffff0000, v33
	v_and_b32_e32 v32, 0xffff0000, v32
	v_lshlrev_b32_e32 v39, 16, v31
	v_lshlrev_b32_e32 v38, 16, v30
	v_and_b32_e32 v31, 0xffff0000, v31
	v_and_b32_e32 v30, 0xffff0000, v30
	v_pk_mul_f32 v[36:37], v[32:33], v[32:33]
	v_pk_mul_f32 v[40:41], v[30:31], v[30:31]
	v_lshlrev_b32_e32 v50, 16, v28
	v_and_b32_e32 v51, 0xffff0000, v28
	v_lshlrev_b32_e32 v56, 16, v29
	v_lshlrev_b32_e32 v52, 16, v26
	v_pk_fma_f32 v[36:37], v[34:35], v[34:35], v[36:37]
	v_pk_fma_f32 v[40:41], v[38:39], v[38:39], v[40:41]
	v_mul_f32_e32 v53, v50, v50
	v_mul_f32_e32 v55, v51, v51
	v_and_b32_e32 v57, 0xffff0000, v29
	v_mul_f32_e32 v28, v56, v56
	v_mov_b32_e32 v54, v52
	v_pk_add_f32 v[36:37], v[36:37], v[36:37] op_sel_hi:[0,1]
	v_pk_add_f32 v[40:41], v[40:41], v[40:41] op_sel_hi:[0,1]
	v_pk_fma_f32 v[28:29], v[56:57], v[56:57], v[28:29] op_sel_hi:[1,1,0]
	v_and_b32_e32 v60, 0xffff0000, v26
	v_lshlrev_b32_e32 v58, 16, v27
	v_and_b32_e32 v59, 0xffff0000, v27
	v_pk_add_f32 v[54:55], v[52:53], v[54:55]
	v_mul_f32_e32 v28, v60, v60
	v_mul_f32_e32 v40, v58, v58
	v_mul_f32_e32 v36, v59, v59
	v_mul_f32_e32 v26, v52, v52
	v_mov_b32_e32 v27, v55
	v_pk_add_f32 v[26:27], v[26:27], v[28:29]
	v_pk_add_f32 v[28:29], v[40:41], v[36:37]
	s_ashr_i32 s7, s6, 31
	v_pk_add_f32 v[36:37], v[26:27], v[28:29]
	global_load_dwordx4 v[26:29], v[4:5], off
	v_add_f32_e32 v36, v36, v37
	s_nop 1
	v_mov_b32_dpp v37, v36 quad_perm:[1,0,3,2] row_mask:0xf bank_mask:0xf
	s_waitcnt lgkmcnt(0)
	v_add_f32_e32 v36, v36, v37
	s_nop 1
	v_mov_b32_dpp v37, v36 quad_perm:[2,3,0,1] row_mask:0xf bank_mask:0xf
	s_waitcnt lgkmcnt(0)
	v_add_f32_e32 v36, v36, v37
	s_nop 1
	v_mov_b32_dpp v37, v36 row_half_mirror row_mask:0xf bank_mask:0xf
	s_waitcnt lgkmcnt(0)
	v_add_f32_e32 v36, v36, v37
	s_nop 1
	v_mov_b32_dpp v37, v36 row_mirror row_mask:0xf bank_mask:0xf
	s_waitcnt lgkmcnt(0)
	v_add_f32_e32 v36, v36, v37
	v_mov_b32_e32 v37, v36
	s_nop 1
	v_permlane16_swap_b32_e32 v36, v37
	s_waitcnt lgkmcnt(0)
	v_add_f32_e32 v36, v36, v37
	v_mov_b32_e32 v37, v36
	s_nop 1
	v_permlane32_swap_b32_e32 v36, v37
	s_waitcnt lgkmcnt(0)
	v_add_f32_e32 v36, v36, v37
	v_fmamk_f32 v36, v36, 0x3a800000, v48
	v_mul_f32_e32 v37, 0x4f800000, v36
	v_cmp_gt_f32_e32 vcc, s12, v36
	s_nop 1
	v_cndmask_b32_e32 v36, v36, v37, vcc
	v_sqrt_f32_e32 v37, v36
	s_nop 0
	v_add_u32_e32 v40, -1, v37
	v_fma_f32 v41, -v40, v37, v36
	v_cmp_ge_f32_e64 s[0:1], 0, v41
	v_add_u32_e32 v41, 1, v37
	s_nop 0
	v_cndmask_b32_e64 v40, v37, v40, s[0:1]
	v_fma_f32 v37, -v41, v37, v36
	v_cmp_lt_f32_e64 s[0:1], 0, v37
	s_nop 1
	v_cndmask_b32_e64 v37, v40, v41, s[0:1]
	v_mul_f32_e32 v40, 0x37800000, v37
	v_cndmask_b32_e32 v37, v37, v40, vcc
	v_cmp_class_f32_e32 vcc, v36, v49
	s_nop 1
	v_cndmask_b32_e32 v36, v37, v36, vcc
	v_div_scale_f32 v37, s[0:1], v36, v36, 1.0
	v_rcp_f32_e32 v40, v37
	s_lshl_b64 s[0:1], s[6:7], 12
	v_fma_f32 v41, -v37, v40, 1.0
	v_fmac_f32_e32 v40, v41, v40
	v_div_scale_f32 v41, vcc, 1.0, v36, 1.0
	v_mul_f32_e32 v53, v41, v40
	v_fma_f32 v54, -v37, v53, v41
	v_fmac_f32_e32 v53, v54, v40
	v_fma_f32 v37, -v37, v53, v41
	v_div_fmas_f32 v37, v37, v40, v53
	v_div_fixup_f32 v36, v37, v36, 1.0
	v_mov_b32_e32 v40, v34
	v_mov_b32_e32 v41, v32
	v_mov_b32_e32 v32, v35
	v_pk_mul_f32 v[40:41], v[36:37], v[40:41] op_sel_hi:[0,1]
	v_pk_mul_f32 v[32:33], v[36:37], v[32:33] op_sel_hi:[0,1]
	s_waitcnt vmcnt(0)
	v_pk_mul_f32 v[28:29], v[28:29], v[32:33]
	v_pk_mul_f32 v[26:27], v[26:27], v[40:41]
	v_lshl_add_u64 v[32:33], v[6:7], 0, s[0:1]
	global_store_dwordx4 v[32:33], v[26:29], off nt
	global_load_dwordx4 v[26:29], v[4:5], off offset:1024
	v_mov_b32_e32 v34, v39
	v_mov_b32_e32 v35, v31
	v_mov_b32_e32 v39, v30
	v_pk_mul_f32 v[30:31], v[36:37], v[34:35] op_sel_hi:[0,1]
	v_pk_mul_f32 v[34:35], v[36:37], v[38:39] op_sel_hi:[0,1]
	v_mov_b32_e32 v53, v60
	s_waitcnt vmcnt(0)
	v_pk_mul_f32 v[26:27], v[26:27], v[34:35]
	v_pk_mul_f32 v[28:29], v[28:29], v[30:31]
	global_store_dwordx4 v[32:33], v[26:29], off offset:1024 nt
	global_load_dwordx4 v[26:29], v[4:5], off offset:2048
	v_pk_mul_f32 v[30:31], v[56:57], v[36:37] op_sel_hi:[1,0]
	v_pk_mul_f32 v[34:35], v[50:51], v[36:37] op_sel_hi:[1,0]
	s_waitcnt vmcnt(0)
	v_pk_mul_f32 v[28:29], v[28:29], v[30:31]
	v_pk_mul_f32 v[26:27], v[26:27], v[34:35]
	global_store_dwordx4 v[32:33], v[26:29], off offset:2048 nt
	global_load_dwordx4 v[26:29], v[4:5], off offset:3072
	v_pk_mul_f32 v[30:31], v[58:59], v[36:37] op_sel_hi:[1,0]
	v_pk_mul_f32 v[34:35], v[52:53], v[36:37] op_sel_hi:[1,0]
	s_waitcnt vmcnt(0)
	v_pk_mul_f32 v[28:29], v[28:29], v[30:31]
	v_pk_mul_f32 v[26:27], v[26:27], v[34:35]
	global_store_dwordx4 v[32:33], v[26:29], off offset:3072 nt
	s_branch .LBB0_1699
